# g8 + P8 second-half conv loads hoisted + tail (it=30) staging writes interleaved into MFMAs + duplicate adjacent barriers removed
# speedup vs baseline: 1.0018x; 1.0018x over previous
; DI f32x4 mfma16(bf16x8 a, bf16x8 b, f32x4 c) { return __builtin_amdgcn_mfma_f32_16x16x32_bf16(a, b, c, 0, 0, 0); }
; template <int NI, class XL, class EP>
; DI void gemm_tile(const u16* __restrict__ W, int ldw, int f0, int t0, int K, XL xl, EP ep, unsigned char* smem) {
;     ...
;   for (int it = 0; it < nk; ++it) {
;     const u16* Ws = S0 + (it & 1) * BUF; const u16* Xs = Ws + 128 * LST;
;     __builtin_amdgcn_s_setprio(1);
;     bf16x8 a[4];
; #pragma unroll
;     for (int mi = 0; mi < 4; ++mi) a[mi] = *(const bf16x8*)(Ws + (wf * 64 + mi * 16 + lr) * LST + lq * 8);
; #pragma unroll
;     for (int ni = 0; ni < NI; ++ni) {
;       const bf16x8 b = *(const bf16x8*)(Xs + (wt * (NI * 16) + ni * 16 + lr) * LST + lq * 8);
; #pragma unroll
;       for (int mi = 0; mi < 4; ++mi) acc[mi][ni] = mfma16(a[mi], b, acc[mi][ni]);
;     }
;     __builtin_amdgcn_sched_group_barrier(0x100, 6, 0);
; #pragma unroll
;     for (int ni = 0; ni < NI; ++ni) { __builtin_amdgcn_sched_group_barrier(0x008, 4, 0); if (ni + 2 < NI) __builtin_amdgcn_sched_group_barrier(0x100, 1, 0); }
;     __builtin_amdgcn_s_setprio(0);
;     if (it + 1 < nk) lstore((it + 1) & 1);
;     if (it + 2 < nk) gload(it + 2);
;     __syncthreads();
.LBB0_269:
	s_setprio 1
	ds_read_b128 v[170:173], v228 offset:0
	ds_read_b128 v[174:177], v228 offset:1536
	ds_read_b128 v[182:185], v228 offset:3072
	ds_read_b128 v[186:189], v228 offset:4608
	ds_read_b128 v[178:181], v152 offset:12288
	ds_read_b128 v[190:193], v152 offset:13824
	s_waitcnt lgkmcnt(1)
	v_mfma_f32_16x16x32_bf16 v[148:151], v[170:173], v[178:181], v[148:151]
	v_mfma_f32_16x16x32_bf16 v[136:139], v[174:177], v[178:181], v[136:139]
	v_mfma_f32_16x16x32_bf16 v[112:115], v[182:185], v[178:181], v[112:115]
	v_mfma_f32_16x16x32_bf16 v[80:83], v[186:189], v[178:181], v[80:83]
	ds_read_b128 v[178:181], v152 offset:15360
	s_waitcnt vmcnt(6)
	ds_write_b128 v194, v[20:23] offset:36864
	s_waitcnt lgkmcnt(2)
	v_mfma_f32_16x16x32_bf16 v[144:147], v[170:173], v[190:193], v[144:147]
	v_mfma_f32_16x16x32_bf16 v[128:131], v[174:177], v[190:193], v[128:131]
	v_mfma_f32_16x16x32_bf16 v[100:103], v[182:185], v[190:193], v[100:103]
	v_mfma_f32_16x16x32_bf16 v[68:71], v[186:189], v[190:193], v[68:71]
	ds_read_b128 v[190:193], v152 offset:16896
	ds_write_b128 v194, v[16:19] offset:36960
	global_load_dwordx4 v[20:23], v154, s[98:99]
	global_load_dwordx4 v[16:19], v154, s[98:99] offset:64
	s_waitcnt lgkmcnt(3)
	v_mfma_f32_16x16x32_bf16 v[140:143], v[170:173], v[178:181], v[140:143]
	v_mfma_f32_16x16x32_bf16 v[120:123], v[174:177], v[178:181], v[120:123]
	v_mfma_f32_16x16x32_bf16 v[88:91], v[182:185], v[178:181], v[88:91]
	v_mfma_f32_16x16x32_bf16 v[56:59], v[186:189], v[178:181], v[56:59]
	ds_read_b128 v[178:181], v152 offset:18432
	ds_write_b128 v195, v[36:39] offset:49152
	global_load_dwordx4 v[36:39], v156, s[100:101] offset:2048
	s_waitcnt lgkmcnt(3)
	v_mfma_f32_16x16x32_bf16 v[132:135], v[170:173], v[190:193], v[132:135]
	v_mfma_f32_16x16x32_bf16 v[108:111], v[174:177], v[190:193], v[108:111]
	v_mfma_f32_16x16x32_bf16 v[76:79], v[182:185], v[190:193], v[76:79]
	v_mfma_f32_16x16x32_bf16 v[40:43], v[186:189], v[190:193], v[40:43]
	ds_read_b128 v[190:193], v152 offset:19968
	ds_write_b128 v195, v[32:35] offset:49248
	global_load_dwordx4 v[32:35], v156, s[100:101] offset:2112
	s_waitcnt lgkmcnt(3)
	v_mfma_f32_16x16x32_bf16 v[124:127], v[170:173], v[178:181], v[124:127]
	v_mfma_f32_16x16x32_bf16 v[96:99], v[174:177], v[178:181], v[96:99]
	v_mfma_f32_16x16x32_bf16 v[64:67], v[182:185], v[178:181], v[64:67]
	v_mfma_f32_16x16x32_bf16 v[12:15], v[186:189], v[178:181], v[12:15]
	ds_read_b128 v[178:181], v152 offset:21504
	ds_write_b128 v195, v[28:31] offset:49344
	global_load_dwordx4 v[28:31], v156, s[100:101] offset:2176
	s_waitcnt lgkmcnt(3)
	v_mfma_f32_16x16x32_bf16 v[116:119], v[170:173], v[190:193], v[116:119]
	v_mfma_f32_16x16x32_bf16 v[84:87], v[174:177], v[190:193], v[84:87]
	v_mfma_f32_16x16x32_bf16 v[52:55], v[182:185], v[190:193], v[52:55]
	v_mfma_f32_16x16x32_bf16 v[8:11], v[186:189], v[190:193], v[8:11]
	ds_read_b128 v[190:193], v152 offset:23040
	ds_write_b128 v195, v[24:27] offset:49440
	global_load_dwordx4 v[24:27], v156, s[100:101] offset:2240
	s_waitcnt lgkmcnt(3)
	v_mfma_f32_16x16x32_bf16 v[104:107], v[170:173], v[178:181], v[104:107]
	v_mfma_f32_16x16x32_bf16 v[72:75], v[174:177], v[178:181], v[72:75]
	v_mfma_f32_16x16x32_bf16 v[48:51], v[182:185], v[178:181], v[48:51]
	v_mfma_f32_16x16x32_bf16 v[4:7], v[186:189], v[178:181], v[4:7]
	s_add_u32 s98, s98, s4
	s_addc_u32 s99, s99, s5
	s_add_u32 s100, s100, s14
	s_addc_u32 s101, s101, s15
	s_waitcnt lgkmcnt(1)
	v_mfma_f32_16x16x32_bf16 v[92:95], v[170:173], v[190:193], v[92:95]
	v_mfma_f32_16x16x32_bf16 v[60:63], v[174:177], v[190:193], v[60:63]
	v_mfma_f32_16x16x32_bf16 v[44:47], v[182:185], v[190:193], v[44:47]
	v_mfma_f32_16x16x32_bf16 v[0:3], v[186:189], v[190:193], v[0:3]
	s_setprio 0
	s_waitcnt lgkmcnt(0)
	s_barrier
	s_setprio 1
	ds_read_b128 v[170:173], v228 offset:36864
	ds_read_b128 v[174:177], v228 offset:38400
	ds_read_b128 v[182:185], v228 offset:39936
	ds_read_b128 v[186:189], v228 offset:41472
	ds_read_b128 v[178:181], v152 offset:49152
	ds_read_b128 v[190:193], v152 offset:50688
	s_waitcnt lgkmcnt(1)
	v_mfma_f32_16x16x32_bf16 v[148:151], v[170:173], v[178:181], v[148:151]
	v_mfma_f32_16x16x32_bf16 v[136:139], v[174:177], v[178:181], v[136:139]
	v_mfma_f32_16x16x32_bf16 v[112:115], v[182:185], v[178:181], v[112:115]
	v_mfma_f32_16x16x32_bf16 v[80:83], v[186:189], v[178:181], v[80:83]
	ds_read_b128 v[178:181], v152 offset:52224
	s_waitcnt vmcnt(6)
	ds_write_b128 v194, v[200:203] offset:0
	s_waitcnt lgkmcnt(2)
	v_mfma_f32_16x16x32_bf16 v[144:147], v[170:173], v[190:193], v[144:147]
	v_mfma_f32_16x16x32_bf16 v[128:131], v[174:177], v[190:193], v[128:131]
	v_mfma_f32_16x16x32_bf16 v[100:103], v[182:185], v[190:193], v[100:103]
	v_mfma_f32_16x16x32_bf16 v[68:71], v[186:189], v[190:193], v[68:71]
	ds_read_b128 v[190:193], v152 offset:53760
	ds_write_b128 v194, v[204:207] offset:96
	global_load_dwordx4 v[200:203], v154, s[98:99]
	global_load_dwordx4 v[204:207], v154, s[98:99] offset:64
	s_waitcnt lgkmcnt(3)
	v_mfma_f32_16x16x32_bf16 v[140:143], v[170:173], v[178:181], v[140:143]
	v_mfma_f32_16x16x32_bf16 v[120:123], v[174:177], v[178:181], v[120:123]
	v_mfma_f32_16x16x32_bf16 v[88:91], v[182:185], v[178:181], v[88:91]
	v_mfma_f32_16x16x32_bf16 v[56:59], v[186:189], v[178:181], v[56:59]
	ds_read_b128 v[178:181], v152 offset:55296
	ds_write_b128 v195, v[208:211] offset:12288
	global_load_dwordx4 v[208:211], v156, s[100:101] offset:2048
	s_waitcnt lgkmcnt(3)
; DI f32x4 mfma16(bf16x8 a, bf16x8 b, f32x4 c) { return __builtin_amdgcn_mfma_f32_16x16x32_bf16(a, b, c, 0, 0, 0); }
; template <int NI, class XL, class EP>
; DI void gemm_tile(const u16* __restrict__ W, int ldw, int f0, int t0, int K, XL xl, EP ep, unsigned char* smem) {
;     ...
;   for (int it = 0; it < nk; ++it) {
;     const u16* Ws = S0 + (it & 1) * BUF; const u16* Xs = Ws + 128 * LST;
;     __builtin_amdgcn_s_setprio(1);
;     bf16x8 a[4];
; #pragma unroll
;     for (int mi = 0; mi < 4; ++mi) a[mi] = *(const bf16x8*)(Ws + (wf * 64 + mi * 16 + lr) * LST + lq * 8);
; #pragma unroll
;     for (int ni = 0; ni < NI; ++ni) {
;       const bf16x8 b = *(const bf16x8*)(Xs + (wt * (NI * 16) + ni * 16 + lr) * LST + lq * 8);
; #pragma unroll
;       for (int mi = 0; mi < 4; ++mi) acc[mi][ni] = mfma16(a[mi], b, acc[mi][ni]);
;     }
;     __builtin_amdgcn_sched_group_barrier(0x100, 6, 0);
; #pragma unroll
;     for (int ni = 0; ni < NI; ++ni) { __builtin_amdgcn_sched_group_barrier(0x008, 4, 0); if (ni + 2 < NI) __builtin_amdgcn_sched_group_barrier(0x100, 1, 0); }
;     __builtin_amdgcn_s_setprio(0);
;     if (it + 1 < nk) lstore((it + 1) & 1);
;     if (it + 2 < nk) gload(it + 2);
;     __syncthreads();
	v_mfma_f32_16x16x32_bf16 v[132:135], v[170:173], v[190:193], v[132:135]
	v_mfma_f32_16x16x32_bf16 v[108:111], v[174:177], v[190:193], v[108:111]
	v_mfma_f32_16x16x32_bf16 v[76:79], v[182:185], v[190:193], v[76:79]
	v_mfma_f32_16x16x32_bf16 v[40:43], v[186:189], v[190:193], v[40:43]
	ds_read_b128 v[190:193], v152 offset:56832
	ds_write_b128 v195, v[212:215] offset:12384
	global_load_dwordx4 v[212:215], v156, s[100:101] offset:2112
	s_waitcnt lgkmcnt(3)
	v_mfma_f32_16x16x32_bf16 v[124:127], v[170:173], v[178:181], v[124:127]
	v_mfma_f32_16x16x32_bf16 v[96:99], v[174:177], v[178:181], v[96:99]
	v_mfma_f32_16x16x32_bf16 v[64:67], v[182:185], v[178:181], v[64:67]
	v_mfma_f32_16x16x32_bf16 v[12:15], v[186:189], v[178:181], v[12:15]
	ds_read_b128 v[178:181], v152 offset:58368
	ds_write_b128 v195, v[220:223] offset:12480
	global_load_dwordx4 v[220:223], v156, s[100:101] offset:2176
	s_waitcnt lgkmcnt(3)
	v_mfma_f32_16x16x32_bf16 v[116:119], v[170:173], v[190:193], v[116:119]
	v_mfma_f32_16x16x32_bf16 v[84:87], v[174:177], v[190:193], v[84:87]
	v_mfma_f32_16x16x32_bf16 v[52:55], v[182:185], v[190:193], v[52:55]
	v_mfma_f32_16x16x32_bf16 v[8:11], v[186:189], v[190:193], v[8:11]
	ds_read_b128 v[190:193], v152 offset:59904
	ds_write_b128 v195, v[224:227] offset:12576
	global_load_dwordx4 v[224:227], v156, s[100:101] offset:2240
	s_waitcnt lgkmcnt(3)
	v_mfma_f32_16x16x32_bf16 v[104:107], v[170:173], v[178:181], v[104:107]
	v_mfma_f32_16x16x32_bf16 v[72:75], v[174:177], v[178:181], v[72:75]
	v_mfma_f32_16x16x32_bf16 v[48:51], v[182:185], v[178:181], v[48:51]
	v_mfma_f32_16x16x32_bf16 v[4:7], v[186:189], v[178:181], v[4:7]
	s_add_u32 s98, s98, s4
	s_addc_u32 s99, s99, s5
	s_add_u32 s100, s100, s14
	s_addc_u32 s101, s101, s15
	s_add_i32 s22, s22, 2
	s_waitcnt lgkmcnt(1)
	v_mfma_f32_16x16x32_bf16 v[92:95], v[170:173], v[190:193], v[92:95]
	v_mfma_f32_16x16x32_bf16 v[60:63], v[174:177], v[190:193], v[60:63]
	v_mfma_f32_16x16x32_bf16 v[44:47], v[182:185], v[190:193], v[44:47]
	v_mfma_f32_16x16x32_bf16 v[0:3], v[186:189], v[190:193], v[0:3]
	s_setprio 0
	s_cmp_eq_u32 s22, 29
	s_waitcnt lgkmcnt(0)
	s_barrier
	s_cbranch_scc0 .LBB0_269
	s_setprio 1
	ds_read_b128 v[170:173], v228 offset:0
	ds_read_b128 v[174:177], v228 offset:1536
	ds_read_b128 v[182:185], v228 offset:3072
	ds_read_b128 v[186:189], v228 offset:4608
	ds_read_b128 v[178:181], v152 offset:12288
	ds_read_b128 v[190:193], v152 offset:13824
	s_waitcnt lgkmcnt(1)
	v_mfma_f32_16x16x32_bf16 v[148:151], v[170:173], v[178:181], v[148:151]
	v_mfma_f32_16x16x32_bf16 v[136:139], v[174:177], v[178:181], v[136:139]
	v_mfma_f32_16x16x32_bf16 v[112:115], v[182:185], v[178:181], v[112:115]
	v_mfma_f32_16x16x32_bf16 v[80:83], v[186:189], v[178:181], v[80:83]
	ds_read_b128 v[178:181], v152 offset:15360
	s_waitcnt vmcnt(6)
	ds_write_b128 v194, v[20:23] offset:36864
	s_waitcnt lgkmcnt(2)
	v_mfma_f32_16x16x32_bf16 v[144:147], v[170:173], v[190:193], v[144:147]
	v_mfma_f32_16x16x32_bf16 v[128:131], v[174:177], v[190:193], v[128:131]
	v_mfma_f32_16x16x32_bf16 v[100:103], v[182:185], v[190:193], v[100:103]
	v_mfma_f32_16x16x32_bf16 v[68:71], v[186:189], v[190:193], v[68:71]
	ds_read_b128 v[190:193], v152 offset:16896
	ds_write_b128 v194, v[16:19] offset:36960
	global_load_dwordx4 v[20:23], v154, s[98:99]
	global_load_dwordx4 v[16:19], v154, s[98:99] offset:64
	s_waitcnt lgkmcnt(3)
	v_mfma_f32_16x16x32_bf16 v[140:143], v[170:173], v[178:181], v[140:143]
	v_mfma_f32_16x16x32_bf16 v[120:123], v[174:177], v[178:181], v[120:123]
	v_mfma_f32_16x16x32_bf16 v[88:91], v[182:185], v[178:181], v[88:91]
	v_mfma_f32_16x16x32_bf16 v[56:59], v[186:189], v[178:181], v[56:59]
	ds_read_b128 v[178:181], v152 offset:18432
	ds_write_b128 v195, v[36:39] offset:49152
	global_load_dwordx4 v[36:39], v156, s[100:101] offset:2048
	s_waitcnt lgkmcnt(3)
	v_mfma_f32_16x16x32_bf16 v[132:135], v[170:173], v[190:193], v[132:135]
	v_mfma_f32_16x16x32_bf16 v[108:111], v[174:177], v[190:193], v[108:111]
	v_mfma_f32_16x16x32_bf16 v[76:79], v[182:185], v[190:193], v[76:79]
	v_mfma_f32_16x16x32_bf16 v[40:43], v[186:189], v[190:193], v[40:43]
	ds_read_b128 v[190:193], v152 offset:19968
	ds_write_b128 v195, v[32:35] offset:49248
	global_load_dwordx4 v[32:35], v156, s[100:101] offset:2112
	s_waitcnt lgkmcnt(3)
	v_mfma_f32_16x16x32_bf16 v[124:127], v[170:173], v[178:181], v[124:127]
	v_mfma_f32_16x16x32_bf16 v[96:99], v[174:177], v[178:181], v[96:99]
	v_mfma_f32_16x16x32_bf16 v[64:67], v[182:185], v[178:181], v[64:67]
	v_mfma_f32_16x16x32_bf16 v[12:15], v[186:189], v[178:181], v[12:15]
	ds_read_b128 v[178:181], v152 offset:21504
	ds_write_b128 v195, v[28:31] offset:49344
	global_load_dwordx4 v[28:31], v156, s[100:101] offset:2176
	s_waitcnt lgkmcnt(3)
	v_mfma_f32_16x16x32_bf16 v[116:119], v[170:173], v[190:193], v[116:119]
	v_mfma_f32_16x16x32_bf16 v[84:87], v[174:177], v[190:193], v[84:87]
	v_mfma_f32_16x16x32_bf16 v[52:55], v[182:185], v[190:193], v[52:55]
	v_mfma_f32_16x16x32_bf16 v[8:11], v[186:189], v[190:193], v[8:11]
	ds_read_b128 v[190:193], v152 offset:23040
	ds_write_b128 v195, v[24:27] offset:49440
	global_load_dwordx4 v[24:27], v156, s[100:101] offset:2240
	s_waitcnt lgkmcnt(3)
	v_mfma_f32_16x16x32_bf16 v[104:107], v[170:173], v[178:181], v[104:107]
	v_mfma_f32_16x16x32_bf16 v[72:75], v[174:177], v[178:181], v[72:75]
	v_mfma_f32_16x16x32_bf16 v[48:51], v[182:185], v[178:181], v[48:51]
	v_mfma_f32_16x16x32_bf16 v[4:7], v[186:189], v[178:181], v[4:7]
	s_add_u32 s98, s98, s4
	s_addc_u32 s99, s99, s5
	s_add_u32 s100, s100, s14
	s_addc_u32 s101, s101, s15
	s_waitcnt lgkmcnt(1)
	v_mfma_f32_16x16x32_bf16 v[92:95], v[170:173], v[190:193], v[92:95]
	v_mfma_f32_16x16x32_bf16 v[60:63], v[174:177], v[190:193], v[60:63]
	v_mfma_f32_16x16x32_bf16 v[44:47], v[182:185], v[190:193], v[44:47]
	v_mfma_f32_16x16x32_bf16 v[0:3], v[186:189], v[190:193], v[0:3]
	s_setprio 0
	s_waitcnt lgkmcnt(0)
	s_barrier
; DI f32x4 mfma16(bf16x8 a, bf16x8 b, f32x4 c) { return __builtin_amdgcn_mfma_f32_16x16x32_bf16(a, b, c, 0, 0, 0); }
; template <int NI, class XL, class EP>
; DI void gemm_tile(const u16* __restrict__ W, int ldw, int f0, int t0, int K, XL xl, EP ep, unsigned char* smem) {
;     ...
;   for (int it = 0; it < nk; ++it) {
;     const u16* Ws = S0 + (it & 1) * BUF; const u16* Xs = Ws + 128 * LST;
;     __builtin_amdgcn_s_setprio(1);
;     bf16x8 a[4];
; #pragma unroll
;     for (int mi = 0; mi < 4; ++mi) a[mi] = *(const bf16x8*)(Ws + (wf * 64 + mi * 16 + lr) * LST + lq * 8);
; #pragma unroll
;     for (int ni = 0; ni < NI; ++ni) {
;       const bf16x8 b = *(const bf16x8*)(Xs + (wt * (NI * 16) + ni * 16 + lr) * LST + lq * 8);
; #pragma unroll
;       for (int mi = 0; mi < 4; ++mi) acc[mi][ni] = mfma16(a[mi], b, acc[mi][ni]);
;     }
;     __builtin_amdgcn_sched_group_barrier(0x100, 6, 0);
; #pragma unroll
;     for (int ni = 0; ni < NI; ++ni) { __builtin_amdgcn_sched_group_barrier(0x008, 4, 0); if (ni + 2 < NI) __builtin_amdgcn_sched_group_barrier(0x100, 1, 0); }
;     __builtin_amdgcn_s_setprio(0);
;     if (it + 1 < nk) lstore((it + 1) & 1);
;     if (it + 2 < nk) gload(it + 2);
;     __syncthreads();
	s_setprio 1
	ds_read_b128 v[170:173], v228 offset:36864
	ds_read_b128 v[174:177], v228 offset:38400
	ds_read_b128 v[182:185], v228 offset:39936
	ds_read_b128 v[186:189], v228 offset:41472
	ds_read_b128 v[178:181], v152 offset:49152
	ds_read_b128 v[190:193], v152 offset:50688
	s_waitcnt lgkmcnt(1)
	v_mfma_f32_16x16x32_bf16 v[148:151], v[170:173], v[178:181], v[148:151]
	v_mfma_f32_16x16x32_bf16 v[136:139], v[174:177], v[178:181], v[136:139]
	v_mfma_f32_16x16x32_bf16 v[112:115], v[182:185], v[178:181], v[112:115]
	v_mfma_f32_16x16x32_bf16 v[80:83], v[186:189], v[178:181], v[80:83]
	ds_read_b128 v[178:181], v152 offset:52224
	s_waitcnt vmcnt(6)
	ds_write_b128 v194, v[200:203] offset:0
	s_waitcnt lgkmcnt(2)
	v_mfma_f32_16x16x32_bf16 v[144:147], v[170:173], v[190:193], v[144:147]
	v_mfma_f32_16x16x32_bf16 v[128:131], v[174:177], v[190:193], v[128:131]
	v_mfma_f32_16x16x32_bf16 v[100:103], v[182:185], v[190:193], v[100:103]
	v_mfma_f32_16x16x32_bf16 v[68:71], v[186:189], v[190:193], v[68:71]
	ds_read_b128 v[190:193], v152 offset:53760
	ds_write_b128 v194, v[204:207] offset:96
	s_waitcnt lgkmcnt(3)
	v_mfma_f32_16x16x32_bf16 v[140:143], v[170:173], v[178:181], v[140:143]
	v_mfma_f32_16x16x32_bf16 v[120:123], v[174:177], v[178:181], v[120:123]
	v_mfma_f32_16x16x32_bf16 v[88:91], v[182:185], v[178:181], v[88:91]
	v_mfma_f32_16x16x32_bf16 v[56:59], v[186:189], v[178:181], v[56:59]
	ds_read_b128 v[178:181], v152 offset:55296
	ds_write_b128 v195, v[208:211] offset:12288
	s_waitcnt lgkmcnt(3)
	v_mfma_f32_16x16x32_bf16 v[132:135], v[170:173], v[190:193], v[132:135]
	v_mfma_f32_16x16x32_bf16 v[108:111], v[174:177], v[190:193], v[108:111]
	v_mfma_f32_16x16x32_bf16 v[76:79], v[182:185], v[190:193], v[76:79]
	v_mfma_f32_16x16x32_bf16 v[40:43], v[186:189], v[190:193], v[40:43]
	ds_read_b128 v[190:193], v152 offset:56832
	ds_write_b128 v195, v[212:215] offset:12384
	s_waitcnt lgkmcnt(3)
	v_mfma_f32_16x16x32_bf16 v[124:127], v[170:173], v[178:181], v[124:127]
	v_mfma_f32_16x16x32_bf16 v[96:99], v[174:177], v[178:181], v[96:99]
	v_mfma_f32_16x16x32_bf16 v[64:67], v[182:185], v[178:181], v[64:67]
	v_mfma_f32_16x16x32_bf16 v[12:15], v[186:189], v[178:181], v[12:15]
	ds_read_b128 v[178:181], v152 offset:58368
	ds_write_b128 v195, v[220:223] offset:12480
	s_waitcnt lgkmcnt(3)
	v_mfma_f32_16x16x32_bf16 v[116:119], v[170:173], v[190:193], v[116:119]
	v_mfma_f32_16x16x32_bf16 v[84:87], v[174:177], v[190:193], v[84:87]
	v_mfma_f32_16x16x32_bf16 v[52:55], v[182:185], v[190:193], v[52:55]
	v_mfma_f32_16x16x32_bf16 v[8:11], v[186:189], v[190:193], v[8:11]
	ds_read_b128 v[190:193], v152 offset:59904
	ds_write_b128 v195, v[224:227] offset:12576
	s_waitcnt lgkmcnt(3)
	v_mfma_f32_16x16x32_bf16 v[104:107], v[170:173], v[178:181], v[104:107]
	v_mfma_f32_16x16x32_bf16 v[72:75], v[174:177], v[178:181], v[72:75]
	v_mfma_f32_16x16x32_bf16 v[48:51], v[182:185], v[178:181], v[48:51]
	v_mfma_f32_16x16x32_bf16 v[4:7], v[186:189], v[178:181], v[4:7]
	s_add_i32 s22, s22, 2
	s_waitcnt lgkmcnt(1)
	v_mfma_f32_16x16x32_bf16 v[92:95], v[170:173], v[190:193], v[92:95]
	v_mfma_f32_16x16x32_bf16 v[60:63], v[174:177], v[190:193], v[60:63]
	v_mfma_f32_16x16x32_bf16 v[44:47], v[182:185], v[190:193], v[44:47]
	v_mfma_f32_16x16x32_bf16 v[0:3], v[186:189], v[190:193], v[0:3]
	s_setprio 0
	s_waitcnt lgkmcnt(0)
	s_barrier
	s_setprio 1
	v_lshl_add_u32 v152, v168, 1, v166
	ds_read_b128 v[154:157], v152
	v_lshl_add_u32 v228, v165, 1, v166
	ds_read_b128 v[166:169], v152 offset:1536
	ds_read_b128 v[174:177], v152 offset:3072
	ds_read_b128 v[178:181], v152 offset:4608
	ds_read_b128 v[170:173], v228 offset:12288
	ds_read_b128 v[182:185], v228 offset:13824
	s_waitcnt lgkmcnt(1)
	v_mfma_f32_16x16x32_bf16 v[148:151], v[154:157], v[170:173], v[148:151]
	v_mfma_f32_16x16x32_bf16 v[136:139], v[166:169], v[170:173], v[136:139]
	v_mfma_f32_16x16x32_bf16 v[112:115], v[174:177], v[170:173], v[112:115]
	v_mfma_f32_16x16x32_bf16 v[170:173], v[178:181], v[170:173], v[80:83]
	s_nop 2
	ds_read_b128 v[80:83], v228 offset:15360
	s_waitcnt vmcnt(5)
	ds_write_b128 v163, v[20:23] offset:36864
	s_waitcnt lgkmcnt(2)
	v_mfma_f32_16x16x32_bf16 v[144:147], v[154:157], v[182:185], v[144:147]
	v_mfma_f32_16x16x32_bf16 v[128:131], v[166:169], v[182:185], v[128:131]
	v_mfma_f32_16x16x32_bf16 v[100:103], v[174:177], v[182:185], v[100:103]
	v_mfma_f32_16x16x32_bf16 v[68:71], v[178:181], v[182:185], v[68:71]
	ds_read_b128 v[182:185], v228 offset:16896
	s_waitcnt vmcnt(4)
	ds_write_b128 v163, v[16:19] offset:36960
	s_waitcnt lgkmcnt(3)
	v_mfma_f32_16x16x32_bf16 v[140:143], v[154:157], v[80:83], v[140:143]
	v_mfma_f32_16x16x32_bf16 v[186:189], v[166:169], v[80:83], v[120:123]
	v_mfma_f32_16x16x32_bf16 v[88:91], v[174:177], v[80:83], v[88:91]
	v_mfma_f32_16x16x32_bf16 v[56:59], v[178:181], v[80:83], v[56:59]
	ds_read_b128 v[80:83], v228 offset:18432
	s_waitcnt vmcnt(3)
	ds_write_b128 v164, v[36:39] offset:49152
	s_waitcnt lgkmcnt(3)
	v_mfma_f32_16x16x32_bf16 v[132:135], v[154:157], v[182:185], v[132:135]
	v_mfma_f32_16x16x32_bf16 v[108:111], v[166:169], v[182:185], v[108:111]
	v_mfma_f32_16x16x32_bf16 v[76:79], v[174:177], v[182:185], v[76:79]
	v_mfma_f32_16x16x32_bf16 v[182:185], v[178:181], v[182:185], v[40:43]
	s_nop 2
	ds_read_b128 v[40:43], v228 offset:19968
	s_waitcnt vmcnt(2)
	ds_write_b128 v164, v[32:35] offset:49248
	s_waitcnt lgkmcnt(3)
	v_mfma_f32_16x16x32_bf16 v[190:193], v[154:157], v[80:83], v[124:127]
	v_mfma_f32_16x16x32_bf16 v[96:99], v[166:169], v[80:83], v[96:99]
	v_mfma_f32_16x16x32_bf16 v[194:197], v[174:177], v[80:83], v[64:67]
	v_mfma_f32_16x16x32_bf16 v[198:201], v[178:181], v[80:83], v[12:15]
	s_nop 2
	ds_read_b128 v[12:15], v228 offset:21504
	s_waitcnt vmcnt(1)
	ds_write_b128 v164, v[28:31] offset:49344
	s_waitcnt lgkmcnt(3)
	v_mfma_f32_16x16x32_bf16 v[202:205], v[154:157], v[40:43], v[116:119]
	v_mfma_f32_16x16x32_bf16 v[84:87], v[166:169], v[40:43], v[84:87]
	v_mfma_f32_16x16x32_bf16 v[52:55], v[174:177], v[40:43], v[52:55]
	v_mfma_f32_16x16x32_bf16 v[206:209], v[178:181], v[40:43], v[8:11]
	s_nop 2
	ds_read_b128 v[8:11], v228 offset:23040
	s_waitcnt vmcnt(0)
	ds_write_b128 v164, v[24:27] offset:49440
	s_waitcnt lgkmcnt(3)
	v_mfma_f32_16x16x32_bf16 v[210:213], v[154:157], v[12:15], v[104:107]
	v_mfma_f32_16x16x32_bf16 v[214:217], v[166:169], v[12:15], v[72:75]
	v_mfma_f32_16x16x32_bf16 v[220:223], v[174:177], v[12:15], v[48:51]
	v_mfma_f32_16x16x32_bf16 v[224:227], v[178:181], v[12:15], v[4:7]
	s_waitcnt lgkmcnt(1)
	v_mfma_f32_16x16x32_bf16 v[92:95], v[154:157], v[8:11], v[92:95]
	v_mfma_f32_16x16x32_bf16 v[60:63], v[166:169], v[8:11], v[60:63]
	v_mfma_f32_16x16x32_bf16 v[154:157], v[174:177], v[8:11], v[44:47]
	v_mfma_f32_16x16x32_bf16 v[166:169], v[178:181], v[8:11], v[0:3]
	s_setprio 0
	s_waitcnt lgkmcnt(0)
	s_barrier
; DI f32x4 mfma16(bf16x8 a, bf16x8 b, f32x4 c) { return __builtin_amdgcn_mfma_f32_16x16x32_bf16(a, b, c, 0, 0, 0); }
; template <int NI, class XL, class EP>
; DI void gemm_tile(const u16* __restrict__ W, int ldw, int f0, int t0, int K, XL xl, EP ep, unsigned char* smem) {
;     ...
;   for (int it = 0; it < nk; ++it) {
;     const u16* Ws = S0 + (it & 1) * BUF; const u16* Xs = Ws + 128 * LST;
;     __builtin_amdgcn_s_setprio(1);
;     bf16x8 a[4];
; #pragma unroll
;     for (int mi = 0; mi < 4; ++mi) a[mi] = *(const bf16x8*)(Ws + (wf * 64 + mi * 16 + lr) * LST + lq * 8);
; #pragma unroll
;     for (int ni = 0; ni < NI; ++ni) {
;       const bf16x8 b = *(const bf16x8*)(Xs + (wt * (NI * 16) + ni * 16 + lr) * LST + lq * 8);
; #pragma unroll
;       for (int mi = 0; mi < 4; ++mi) acc[mi][ni] = mfma16(a[mi], b, acc[mi][ni]);
;     }
;     __builtin_amdgcn_sched_group_barrier(0x100, 6, 0);
; #pragma unroll
;     for (int ni = 0; ni < NI; ++ni) { __builtin_amdgcn_sched_group_barrier(0x008, 4, 0); if (ni + 2 < NI) __builtin_amdgcn_sched_group_barrier(0x100, 1, 0); }
;     __builtin_amdgcn_s_setprio(0);
;     if (it + 1 < nk) lstore((it + 1) & 1);
;     if (it + 2 < nk) gload(it + 2);
;     __syncthreads();
;   }
; DI void phase1(const Params& p, const Sched& sched, unsigned char* smem) {
;     ...
;       u16* dst; int ld, cb;
;       if (tn < 8) { dst = (u16*)(p.ws + OFF_QB); ld = 1024; cb = 0; }
;       else if (tn < 12) { dst = (u16*)(p.ws + OFF_KVC); ld = 512; cb = 1024; }
;       else if (tn < 16) { dst = (u16*)(p.ws + OFF_KVS); ld = 512; cb = 1536; }
;       else if (tn < 20) { dst = (u16*)(p.ws + OFF_KVW); ld = 512; cb = 2048; }
;       else if (tn < 22) { dst = (u16*)(p.ws + OFF_MQ); ld = 256; cb = 2560; }
;       else if (tn < 24) { dst = (u16*)(p.ws + OFF_MKV); ld = 256; cb = 2816; }
;       else if (tn < 32) { dst = (u16*)(p.ws + OFF_MA); ld = 1024; cb = 3072; }
;       else { dst = (u16*)(p.ws + OFF_MB); ld = 1024; cb = 4096; }
	s_setprio 1
	ds_read_b128 v[36:39], v152 offset:36864
	ds_read_b128 v[162:165], v152 offset:38400
	ds_read_b128 v[174:177], v152 offset:39936
	ds_read_b128 v[178:181], v152 offset:41472
	ds_read_b128 v[0:3], v228 offset:49152
	ds_read_b128 v[4:7], v228 offset:50688
	s_waitcnt lgkmcnt(1)
	v_mfma_f32_16x16x32_bf16 v[124:127], v[36:39], v[0:3], v[148:151]
	v_mfma_f32_16x16x32_bf16 v[80:83], v[162:165], v[0:3], v[136:139]
	v_mfma_f32_16x16x32_bf16 v[28:31], v[174:177], v[0:3], v[112:115]
	v_mfma_f32_16x16x32_bf16 v[0:3], v[178:181], v[0:3], v[170:173]
	ds_read_b128 v[8:11], v228 offset:52224
	s_waitcnt lgkmcnt(1)
	v_mfma_f32_16x16x32_bf16 v[120:123], v[36:39], v[4:7], v[144:147]
	v_mfma_f32_16x16x32_bf16 v[72:75], v[162:165], v[4:7], v[128:131]
	v_mfma_f32_16x16x32_bf16 v[32:35], v[174:177], v[4:7], v[100:103]
	v_mfma_f32_16x16x32_bf16 v[4:7], v[178:181], v[4:7], v[68:71]
	ds_read_b128 v[12:15], v228 offset:53760
	s_waitcnt lgkmcnt(1)
	v_mfma_f32_16x16x32_bf16 v[116:119], v[36:39], v[8:11], v[140:143]
	v_mfma_f32_16x16x32_bf16 v[64:67], v[162:165], v[8:11], v[186:189]
	v_mfma_f32_16x16x32_bf16 v[40:43], v[174:177], v[8:11], v[88:91]
	v_mfma_f32_16x16x32_bf16 v[8:11], v[178:181], v[8:11], v[56:59]
	ds_read_b128 v[16:19], v228 offset:55296
	s_waitcnt lgkmcnt(1)
	v_mfma_f32_16x16x32_bf16 v[112:115], v[36:39], v[12:15], v[132:135]
	v_mfma_f32_16x16x32_bf16 v[68:71], v[162:165], v[12:15], v[108:111]
	v_mfma_f32_16x16x32_bf16 v[44:47], v[174:177], v[12:15], v[76:79]
	v_mfma_f32_16x16x32_bf16 v[12:15], v[178:181], v[12:15], v[182:185]
	ds_read_b128 v[20:23], v228 offset:56832
	s_waitcnt lgkmcnt(1)
	v_mfma_f32_16x16x32_bf16 v[108:111], v[36:39], v[16:19], v[190:193]
	v_mfma_f32_16x16x32_bf16 v[76:79], v[162:165], v[16:19], v[96:99]
	v_mfma_f32_16x16x32_bf16 v[48:51], v[174:177], v[16:19], v[194:197]
	v_mfma_f32_16x16x32_bf16 v[16:19], v[178:181], v[16:19], v[198:201]
	ds_read_b128 v[24:27], v228 offset:58368
	s_waitcnt lgkmcnt(1)
	v_mfma_f32_16x16x32_bf16 v[104:107], v[36:39], v[20:23], v[202:205]
	v_mfma_f32_16x16x32_bf16 v[84:87], v[162:165], v[20:23], v[84:87]
	v_mfma_f32_16x16x32_bf16 v[52:55], v[174:177], v[20:23], v[52:55]
	v_mfma_f32_16x16x32_bf16 v[20:23], v[178:181], v[20:23], v[206:209]
	ds_read_b128 v[128:131], v228 offset:59904
	s_waitcnt lgkmcnt(1)
	v_mfma_f32_16x16x32_bf16 v[100:103], v[36:39], v[24:27], v[210:213]
	v_mfma_f32_16x16x32_bf16 v[88:91], v[162:165], v[24:27], v[214:217]
	v_mfma_f32_16x16x32_bf16 v[56:59], v[174:177], v[24:27], v[220:223]
	v_mfma_f32_16x16x32_bf16 v[24:27], v[178:181], v[24:27], v[224:227]
	s_waitcnt lgkmcnt(0)
	v_mfma_f32_16x16x32_bf16 v[96:99], v[36:39], v[128:131], v[92:95]
	v_mfma_f32_16x16x32_bf16 v[92:95], v[162:165], v[128:131], v[60:63]
	v_mfma_f32_16x16x32_bf16 v[60:63], v[174:177], v[128:131], v[154:157]
	v_mfma_f32_16x16x32_bf16 v[36:39], v[178:181], v[128:131], v[166:169]
	s_setprio 0
	s_cmp_lt_i32 s61, 8
	s_barrier
	s_cbranch_scc1 .LBB0_275
	s_cmp_lt_u32 s61, 12
	s_cselect_b64 s[22:23], -1, 0
	s_or_b64 s[24:25], s[22:23], s[16:17]
	s_and_b64 s[22:23], s[22:23], exec
	s_cselect_b32 s22, s48, 0x17b00800
	s_cselect_b32 s62, s47, 0xfffffa00
	s_add_u32 s22, s42, s22
	s_addc_u32 s23, s43, 0
	s_and_b64 vcc, exec, s[24:25]
	s_cbranch_vccnz .LBB0_276
	s_cmp_lt_u32 s61, 20
	s_cbranch_scc1 .LBB0_277
	s_cmp_lt_u32 s61, 22
	s_cselect_b64 s[22:23], -1, 0
	s_or_b64 s[24:25], s[22:23], s[18:19]
	s_and_b64 s[22:23], s[22:23], exec
	s_cselect_b32 s22, s50, 0x21b00800
	s_cselect_b32 s62, s49, 0xfffff500
	s_add_u32 s22, s42, s22
	s_addc_u32 s23, s43, 0
	s_and_b64 vcc, exec, s[24:25]
	s_cbranch_vccnz .LBB0_278
	s_mov_b64 s[24:25], 0x400
	s_mov_b64 s[22:23], s[20:21]
	s_mov_b32 s62, s55
	s_branch .LBB0_279

; DI f32x4 mfma16(bf16x8 a, bf16x8 b, f32x4 c) { return __builtin_amdgcn_mfma_f32_16x16x32_bf16(a, b, c, 0, 0, 0); }
; template <int NI, class XL, class EP>
; DI void gemm_tile(const u16* __restrict__ W, int ldw, int f0, int t0, int K, XL xl, EP ep, unsigned char* smem) {
;     ...
;   auto gload = [&](int it) {
;     const int k = it * 32;
;     const char* wb = (const char*)(W + (size_t)(k >> 5) * ldw * 32);
;     const char* xb = (const char*)xl.kbase(k);
; #pragma unroll
;     for (int i = 0; i < 2; ++i) wr[i] = *(const u32x4*)(wb + wbyte + i * 64);
; #pragma unroll
;     for (int i = 0; i < XR; ++i) xr[i] = *(const u32x4*)(xb + xbyte + i * xrs);
;   };
;   auto lstore = [&](int buf) {
;     u16* Ws = S0 + buf * BUF; u16* Xs = Ws + 128 * LST;
; #pragma unroll
;     for (int i = 0; i < 2; ++i) *(u32x4*)(Ws + (srow * 2 + i) * LST + sch) = wr[i];
; #pragma unroll
;     for (int i = 0; i < XR; ++i) *(u32x4*)(Xs + (srow * XR + i) * LST + sch) = xr[i];
;   };
;   gload(0);
;   __syncthreads();
;   lstore(0);
;   __syncthreads();
;   if (nk > 1) gload(1);
;   for (int it = 0; it < nk; ++it) {
;     const u16* Ws = S0 + (it & 1) * BUF; const u16* Xs = Ws + 128 * LST;
;     __builtin_amdgcn_s_setprio(1);
;     bf16x8 a[4];
; #pragma unroll
;     for (int mi = 0; mi < 4; ++mi) a[mi] = *(const bf16x8*)(Ws + (wf * 64 + mi * 16 + lr) * LST + lq * 8);
; #pragma unroll
;     for (int ni = 0; ni < NI; ++ni) {
;       const bf16x8 b = *(const bf16x8*)(Xs + (wt * (NI * 16) + ni * 16 + lr) * LST + lq * 8);
; #pragma unroll
;       for (int mi = 0; mi < 4; ++mi) acc[mi][ni] = mfma16(a[mi], b, acc[mi][ni]);
;     }
;     __builtin_amdgcn_sched_group_barrier(0x100, 6, 0);
; #pragma unroll
;     for (int ni = 0; ni < NI; ++ni) { __builtin_amdgcn_sched_group_barrier(0x008, 4, 0); if (ni + 2 < NI) __builtin_amdgcn_sched_group_barrier(0x100, 1, 0); }
;     __builtin_amdgcn_s_setprio(0);
;     if (it + 1 < nk) lstore((it + 1) & 1);
;     if (it + 2 < nk) gload(it + 2);
;     __syncthreads();
.LBB0_812:
	s_setprio 1
	ds_read_b128 v[168:171], v228 offset:0
	ds_read_b128 v[172:175], v228 offset:1536
	ds_read_b128 v[180:183], v228 offset:3072
	ds_read_b128 v[184:187], v228 offset:4608
	ds_read_b128 v[176:179], v152 offset:12288
	ds_read_b128 v[188:191], v152 offset:13824
	s_waitcnt lgkmcnt(1)
	v_mfma_f32_16x16x32_bf16 v[148:151], v[168:171], v[176:179], v[148:151]
	v_mfma_f32_16x16x32_bf16 v[136:139], v[172:175], v[176:179], v[136:139]
	v_mfma_f32_16x16x32_bf16 v[112:115], v[180:183], v[176:179], v[112:115]
	v_mfma_f32_16x16x32_bf16 v[80:83], v[184:187], v[176:179], v[80:83]
	ds_read_b128 v[176:179], v152 offset:15360
	s_waitcnt vmcnt(6)
	ds_write_b128 v229, v[20:23] offset:36864
	s_waitcnt lgkmcnt(2)
	v_mfma_f32_16x16x32_bf16 v[144:147], v[168:171], v[188:191], v[144:147]
	v_mfma_f32_16x16x32_bf16 v[128:131], v[172:175], v[188:191], v[128:131]
	v_mfma_f32_16x16x32_bf16 v[100:103], v[180:183], v[188:191], v[100:103]
	v_mfma_f32_16x16x32_bf16 v[68:71], v[184:187], v[188:191], v[68:71]
	ds_read_b128 v[188:191], v152 offset:16896
	ds_write_b128 v229, v[16:19] offset:36960
	global_load_dwordx4 v[20:23], v154, s[98:99]
	global_load_dwordx4 v[16:19], v154, s[98:99] offset:64
	s_waitcnt lgkmcnt(3)
	v_mfma_f32_16x16x32_bf16 v[140:143], v[168:171], v[176:179], v[140:143]
	v_mfma_f32_16x16x32_bf16 v[120:123], v[172:175], v[176:179], v[120:123]
	v_mfma_f32_16x16x32_bf16 v[88:91], v[180:183], v[176:179], v[88:91]
	v_mfma_f32_16x16x32_bf16 v[44:47], v[184:187], v[176:179], v[44:47]
	ds_read_b128 v[176:179], v152 offset:18432
	ds_write_b128 v230, v[36:39] offset:49152
	global_load_dwordx4 v[36:39], v156, s[100:101] offset:2048
	s_waitcnt lgkmcnt(3)
	v_mfma_f32_16x16x32_bf16 v[132:135], v[168:171], v[188:191], v[132:135]
	v_mfma_f32_16x16x32_bf16 v[108:111], v[172:175], v[188:191], v[108:111]
	v_mfma_f32_16x16x32_bf16 v[76:79], v[180:183], v[188:191], v[76:79]
	v_mfma_f32_16x16x32_bf16 v[40:43], v[184:187], v[188:191], v[40:43]
	ds_read_b128 v[188:191], v152 offset:19968
	ds_write_b128 v230, v[32:35] offset:49248
	global_load_dwordx4 v[32:35], v156, s[100:101] offset:2112
	s_waitcnt lgkmcnt(3)
	v_mfma_f32_16x16x32_bf16 v[124:127], v[168:171], v[176:179], v[124:127]
	v_mfma_f32_16x16x32_bf16 v[96:99], v[172:175], v[176:179], v[96:99]
	v_mfma_f32_16x16x32_bf16 v[64:67], v[180:183], v[176:179], v[64:67]
	v_mfma_f32_16x16x32_bf16 v[12:15], v[184:187], v[176:179], v[12:15]
	ds_read_b128 v[176:179], v152 offset:21504
	ds_write_b128 v230, v[28:31] offset:49344
	global_load_dwordx4 v[28:31], v156, s[100:101] offset:2176
	s_waitcnt lgkmcnt(3)
	v_mfma_f32_16x16x32_bf16 v[116:119], v[168:171], v[188:191], v[116:119]
	v_mfma_f32_16x16x32_bf16 v[84:87], v[172:175], v[188:191], v[84:87]
	v_mfma_f32_16x16x32_bf16 v[56:59], v[180:183], v[188:191], v[56:59]
	v_mfma_f32_16x16x32_bf16 v[8:11], v[184:187], v[188:191], v[8:11]
	ds_read_b128 v[188:191], v152 offset:23040
	ds_write_b128 v230, v[24:27] offset:49440
	global_load_dwordx4 v[24:27], v156, s[100:101] offset:2240
	s_waitcnt lgkmcnt(3)
	v_mfma_f32_16x16x32_bf16 v[104:107], v[168:171], v[176:179], v[104:107]
	v_mfma_f32_16x16x32_bf16 v[72:75], v[172:175], v[176:179], v[72:75]
	v_mfma_f32_16x16x32_bf16 v[52:55], v[180:183], v[176:179], v[52:55]
	v_mfma_f32_16x16x32_bf16 v[4:7], v[184:187], v[176:179], v[4:7]
	s_add_u32 s98, s98, s18
	s_addc_u32 s99, s99, s19
	s_add_u32 s100, s100, s10
	s_addc_u32 s101, s101, s11
	s_waitcnt lgkmcnt(1)
	v_mfma_f32_16x16x32_bf16 v[92:95], v[168:171], v[188:191], v[92:95]
	v_mfma_f32_16x16x32_bf16 v[60:63], v[172:175], v[188:191], v[60:63]
	v_mfma_f32_16x16x32_bf16 v[48:51], v[180:183], v[188:191], v[48:51]
	v_mfma_f32_16x16x32_bf16 v[0:3], v[184:187], v[188:191], v[0:3]
	s_setprio 0
	s_waitcnt lgkmcnt(0)
	s_barrier
	s_setprio 1
	ds_read_b128 v[168:171], v228 offset:36864
	ds_read_b128 v[172:175], v228 offset:38400
	ds_read_b128 v[180:183], v228 offset:39936
	ds_read_b128 v[184:187], v228 offset:41472
	ds_read_b128 v[176:179], v152 offset:49152
	ds_read_b128 v[188:191], v152 offset:50688
	s_waitcnt lgkmcnt(1)
	v_mfma_f32_16x16x32_bf16 v[148:151], v[168:171], v[176:179], v[148:151]
	v_mfma_f32_16x16x32_bf16 v[136:139], v[172:175], v[176:179], v[136:139]
	v_mfma_f32_16x16x32_bf16 v[112:115], v[180:183], v[176:179], v[112:115]
	v_mfma_f32_16x16x32_bf16 v[80:83], v[184:187], v[176:179], v[80:83]
	ds_read_b128 v[176:179], v152 offset:52224
	s_waitcnt vmcnt(6)
	ds_write_b128 v229, v[200:203] offset:0
	s_waitcnt lgkmcnt(2)
	v_mfma_f32_16x16x32_bf16 v[144:147], v[168:171], v[188:191], v[144:147]
	v_mfma_f32_16x16x32_bf16 v[128:131], v[172:175], v[188:191], v[128:131]
	v_mfma_f32_16x16x32_bf16 v[100:103], v[180:183], v[188:191], v[100:103]
	v_mfma_f32_16x16x32_bf16 v[68:71], v[184:187], v[188:191], v[68:71]
	ds_read_b128 v[188:191], v152 offset:53760
	ds_write_b128 v229, v[204:207] offset:96
	global_load_dwordx4 v[200:203], v154, s[98:99]
	global_load_dwordx4 v[204:207], v154, s[98:99] offset:64
	s_waitcnt lgkmcnt(3)
	v_mfma_f32_16x16x32_bf16 v[140:143], v[168:171], v[176:179], v[140:143]
	v_mfma_f32_16x16x32_bf16 v[120:123], v[172:175], v[176:179], v[120:123]
	v_mfma_f32_16x16x32_bf16 v[88:91], v[180:183], v[176:179], v[88:91]
	v_mfma_f32_16x16x32_bf16 v[44:47], v[184:187], v[176:179], v[44:47]
	ds_read_b128 v[176:179], v152 offset:55296
	ds_write_b128 v230, v[208:211] offset:12288
	global_load_dwordx4 v[208:211], v156, s[100:101] offset:2048
	s_waitcnt lgkmcnt(3)
; DI f32x4 mfma16(bf16x8 a, bf16x8 b, f32x4 c) { return __builtin_amdgcn_mfma_f32_16x16x32_bf16(a, b, c, 0, 0, 0); }
; template <int NI, class XL, class EP>
; DI void gemm_tile(const u16* __restrict__ W, int ldw, int f0, int t0, int K, XL xl, EP ep, unsigned char* smem) {
;     ...
;   auto gload = [&](int it) {
;     const int k = it * 32;
;     const char* wb = (const char*)(W + (size_t)(k >> 5) * ldw * 32);
;     const char* xb = (const char*)xl.kbase(k);
; #pragma unroll
;     for (int i = 0; i < 2; ++i) wr[i] = *(const u32x4*)(wb + wbyte + i * 64);
; #pragma unroll
;     for (int i = 0; i < XR; ++i) xr[i] = *(const u32x4*)(xb + xbyte + i * xrs);
;   };
;   auto lstore = [&](int buf) {
;     u16* Ws = S0 + buf * BUF; u16* Xs = Ws + 128 * LST;
; #pragma unroll
;     for (int i = 0; i < 2; ++i) *(u32x4*)(Ws + (srow * 2 + i) * LST + sch) = wr[i];
; #pragma unroll
;     for (int i = 0; i < XR; ++i) *(u32x4*)(Xs + (srow * XR + i) * LST + sch) = xr[i];
;   };
;   gload(0);
;   __syncthreads();
;   lstore(0);
;   __syncthreads();
;   if (nk > 1) gload(1);
;   for (int it = 0; it < nk; ++it) {
;     const u16* Ws = S0 + (it & 1) * BUF; const u16* Xs = Ws + 128 * LST;
;     __builtin_amdgcn_s_setprio(1);
;     bf16x8 a[4];
; #pragma unroll
;     for (int mi = 0; mi < 4; ++mi) a[mi] = *(const bf16x8*)(Ws + (wf * 64 + mi * 16 + lr) * LST + lq * 8);
; #pragma unroll
;     for (int ni = 0; ni < NI; ++ni) {
;       const bf16x8 b = *(const bf16x8*)(Xs + (wt * (NI * 16) + ni * 16 + lr) * LST + lq * 8);
; #pragma unroll
;       for (int mi = 0; mi < 4; ++mi) acc[mi][ni] = mfma16(a[mi], b, acc[mi][ni]);
;     }
;     __builtin_amdgcn_sched_group_barrier(0x100, 6, 0);
; #pragma unroll
;     for (int ni = 0; ni < NI; ++ni) { __builtin_amdgcn_sched_group_barrier(0x008, 4, 0); if (ni + 2 < NI) __builtin_amdgcn_sched_group_barrier(0x100, 1, 0); }
;     __builtin_amdgcn_s_setprio(0);
;     if (it + 1 < nk) lstore((it + 1) & 1);
;     if (it + 2 < nk) gload(it + 2);
;     __syncthreads();
	v_mfma_f32_16x16x32_bf16 v[132:135], v[168:171], v[188:191], v[132:135]
	v_mfma_f32_16x16x32_bf16 v[108:111], v[172:175], v[188:191], v[108:111]
	v_mfma_f32_16x16x32_bf16 v[76:79], v[180:183], v[188:191], v[76:79]
	v_mfma_f32_16x16x32_bf16 v[40:43], v[184:187], v[188:191], v[40:43]
	ds_read_b128 v[188:191], v152 offset:56832
	ds_write_b128 v230, v[212:215] offset:12384
	global_load_dwordx4 v[212:215], v156, s[100:101] offset:2112
	s_waitcnt lgkmcnt(3)
	v_mfma_f32_16x16x32_bf16 v[124:127], v[168:171], v[176:179], v[124:127]
	v_mfma_f32_16x16x32_bf16 v[96:99], v[172:175], v[176:179], v[96:99]
	v_mfma_f32_16x16x32_bf16 v[64:67], v[180:183], v[176:179], v[64:67]
	v_mfma_f32_16x16x32_bf16 v[12:15], v[184:187], v[176:179], v[12:15]
	ds_read_b128 v[176:179], v152 offset:58368
	ds_write_b128 v230, v[220:223] offset:12480
	global_load_dwordx4 v[220:223], v156, s[100:101] offset:2176
	s_waitcnt lgkmcnt(3)
	v_mfma_f32_16x16x32_bf16 v[116:119], v[168:171], v[188:191], v[116:119]
	v_mfma_f32_16x16x32_bf16 v[84:87], v[172:175], v[188:191], v[84:87]
	v_mfma_f32_16x16x32_bf16 v[56:59], v[180:183], v[188:191], v[56:59]
	v_mfma_f32_16x16x32_bf16 v[8:11], v[184:187], v[188:191], v[8:11]
	ds_read_b128 v[188:191], v152 offset:59904
	ds_write_b128 v230, v[224:227] offset:12576
	global_load_dwordx4 v[224:227], v156, s[100:101] offset:2240
	s_waitcnt lgkmcnt(3)
	v_mfma_f32_16x16x32_bf16 v[104:107], v[168:171], v[176:179], v[104:107]
	v_mfma_f32_16x16x32_bf16 v[72:75], v[172:175], v[176:179], v[72:75]
	v_mfma_f32_16x16x32_bf16 v[52:55], v[180:183], v[176:179], v[52:55]
	v_mfma_f32_16x16x32_bf16 v[4:7], v[184:187], v[176:179], v[4:7]
	s_add_u32 s98, s98, s18
	s_addc_u32 s99, s99, s19
	s_add_u32 s100, s100, s10
	s_addc_u32 s101, s101, s11
	s_add_i32 s36, s36, 2
	s_waitcnt lgkmcnt(1)
	v_mfma_f32_16x16x32_bf16 v[92:95], v[168:171], v[188:191], v[92:95]
	v_mfma_f32_16x16x32_bf16 v[60:63], v[172:175], v[188:191], v[60:63]
	v_mfma_f32_16x16x32_bf16 v[48:51], v[180:183], v[188:191], v[48:51]
	v_mfma_f32_16x16x32_bf16 v[0:3], v[184:187], v[188:191], v[0:3]
	s_setprio 0
	s_cmp_lg_u32 s36, 29
	s_waitcnt lgkmcnt(0)
	s_barrier
	s_cbranch_scc1 .LBB0_812
	s_setprio 1
	ds_read_b128 v[168:171], v228 offset:0
	ds_read_b128 v[172:175], v228 offset:1536
	ds_read_b128 v[180:183], v228 offset:3072
	ds_read_b128 v[184:187], v228 offset:4608
	ds_read_b128 v[176:179], v152 offset:12288
	ds_read_b128 v[188:191], v152 offset:13824
	s_waitcnt lgkmcnt(1)
	v_mfma_f32_16x16x32_bf16 v[148:151], v[168:171], v[176:179], v[148:151]
	v_mfma_f32_16x16x32_bf16 v[136:139], v[172:175], v[176:179], v[136:139]
	v_mfma_f32_16x16x32_bf16 v[112:115], v[180:183], v[176:179], v[112:115]
	v_mfma_f32_16x16x32_bf16 v[80:83], v[184:187], v[176:179], v[80:83]
	ds_read_b128 v[176:179], v152 offset:15360
	s_waitcnt vmcnt(6)
	ds_write_b128 v229, v[20:23] offset:36864
	s_waitcnt lgkmcnt(2)
	v_mfma_f32_16x16x32_bf16 v[144:147], v[168:171], v[188:191], v[144:147]
	v_mfma_f32_16x16x32_bf16 v[128:131], v[172:175], v[188:191], v[128:131]
	v_mfma_f32_16x16x32_bf16 v[100:103], v[180:183], v[188:191], v[100:103]
	v_mfma_f32_16x16x32_bf16 v[68:71], v[184:187], v[188:191], v[68:71]
	ds_read_b128 v[188:191], v152 offset:16896
	ds_write_b128 v229, v[16:19] offset:36960
	global_load_dwordx4 v[20:23], v154, s[98:99]
	global_load_dwordx4 v[16:19], v154, s[98:99] offset:64
	s_waitcnt lgkmcnt(3)
	v_mfma_f32_16x16x32_bf16 v[140:143], v[168:171], v[176:179], v[140:143]
	v_mfma_f32_16x16x32_bf16 v[120:123], v[172:175], v[176:179], v[120:123]
	v_mfma_f32_16x16x32_bf16 v[88:91], v[180:183], v[176:179], v[88:91]
	v_mfma_f32_16x16x32_bf16 v[44:47], v[184:187], v[176:179], v[44:47]
	ds_read_b128 v[176:179], v152 offset:18432
	ds_write_b128 v230, v[36:39] offset:49152
	global_load_dwordx4 v[36:39], v156, s[100:101] offset:2048
	s_waitcnt lgkmcnt(3)
	v_mfma_f32_16x16x32_bf16 v[132:135], v[168:171], v[188:191], v[132:135]
	v_mfma_f32_16x16x32_bf16 v[108:111], v[172:175], v[188:191], v[108:111]
	v_mfma_f32_16x16x32_bf16 v[76:79], v[180:183], v[188:191], v[76:79]
	v_mfma_f32_16x16x32_bf16 v[40:43], v[184:187], v[188:191], v[40:43]
	ds_read_b128 v[188:191], v152 offset:19968
	ds_write_b128 v230, v[32:35] offset:49248
	global_load_dwordx4 v[32:35], v156, s[100:101] offset:2112
	s_waitcnt lgkmcnt(3)
	v_mfma_f32_16x16x32_bf16 v[124:127], v[168:171], v[176:179], v[124:127]
	v_mfma_f32_16x16x32_bf16 v[96:99], v[172:175], v[176:179], v[96:99]
	v_mfma_f32_16x16x32_bf16 v[64:67], v[180:183], v[176:179], v[64:67]
	v_mfma_f32_16x16x32_bf16 v[12:15], v[184:187], v[176:179], v[12:15]
	ds_read_b128 v[176:179], v152 offset:21504
	ds_write_b128 v230, v[28:31] offset:49344
	global_load_dwordx4 v[28:31], v156, s[100:101] offset:2176
	s_waitcnt lgkmcnt(3)
	v_mfma_f32_16x16x32_bf16 v[116:119], v[168:171], v[188:191], v[116:119]
	v_mfma_f32_16x16x32_bf16 v[84:87], v[172:175], v[188:191], v[84:87]
	v_mfma_f32_16x16x32_bf16 v[56:59], v[180:183], v[188:191], v[56:59]
	v_mfma_f32_16x16x32_bf16 v[8:11], v[184:187], v[188:191], v[8:11]
	ds_read_b128 v[188:191], v152 offset:23040
	ds_write_b128 v230, v[24:27] offset:49440
	global_load_dwordx4 v[24:27], v156, s[100:101] offset:2240
	s_waitcnt lgkmcnt(3)
	v_mfma_f32_16x16x32_bf16 v[104:107], v[168:171], v[176:179], v[104:107]
	v_mfma_f32_16x16x32_bf16 v[72:75], v[172:175], v[176:179], v[72:75]
	v_mfma_f32_16x16x32_bf16 v[52:55], v[180:183], v[176:179], v[52:55]
	v_mfma_f32_16x16x32_bf16 v[4:7], v[184:187], v[176:179], v[4:7]
	s_add_u32 s98, s98, s18
	s_addc_u32 s99, s99, s19
	s_add_u32 s100, s100, s10
	s_addc_u32 s101, s101, s11
	s_waitcnt lgkmcnt(1)
	v_mfma_f32_16x16x32_bf16 v[92:95], v[168:171], v[188:191], v[92:95]
	v_mfma_f32_16x16x32_bf16 v[60:63], v[172:175], v[188:191], v[60:63]
	v_mfma_f32_16x16x32_bf16 v[48:51], v[180:183], v[188:191], v[48:51]
	v_mfma_f32_16x16x32_bf16 v[0:3], v[184:187], v[188:191], v[0:3]
	s_setprio 0
	s_waitcnt lgkmcnt(0)
	s_barrier
; DI f32x4 mfma16(bf16x8 a, bf16x8 b, f32x4 c) { return __builtin_amdgcn_mfma_f32_16x16x32_bf16(a, b, c, 0, 0, 0); }
; template <int NI, class XL, class EP>
; DI void gemm_tile(const u16* __restrict__ W, int ldw, int f0, int t0, int K, XL xl, EP ep, unsigned char* smem) {
;     ...
;   for (int it = 0; it < nk; ++it) {
;     const u16* Ws = S0 + (it & 1) * BUF; const u16* Xs = Ws + 128 * LST;
;     __builtin_amdgcn_s_setprio(1);
;     bf16x8 a[4];
; #pragma unroll
;     for (int mi = 0; mi < 4; ++mi) a[mi] = *(const bf16x8*)(Ws + (wf * 64 + mi * 16 + lr) * LST + lq * 8);
; #pragma unroll
;     for (int ni = 0; ni < NI; ++ni) {
;       const bf16x8 b = *(const bf16x8*)(Xs + (wt * (NI * 16) + ni * 16 + lr) * LST + lq * 8);
; #pragma unroll
;       for (int mi = 0; mi < 4; ++mi) acc[mi][ni] = mfma16(a[mi], b, acc[mi][ni]);
;     }
;     __builtin_amdgcn_sched_group_barrier(0x100, 6, 0);
; #pragma unroll
;     for (int ni = 0; ni < NI; ++ni) { __builtin_amdgcn_sched_group_barrier(0x008, 4, 0); if (ni + 2 < NI) __builtin_amdgcn_sched_group_barrier(0x100, 1, 0); }
;     __builtin_amdgcn_s_setprio(0);
;     if (it + 1 < nk) lstore((it + 1) & 1);
;     if (it + 2 < nk) gload(it + 2);
;     __syncthreads();
	s_setprio 1
	ds_read_b128 v[168:171], v228 offset:36864
	ds_read_b128 v[172:175], v228 offset:38400
	ds_read_b128 v[180:183], v228 offset:39936
	ds_read_b128 v[184:187], v228 offset:41472
	ds_read_b128 v[176:179], v152 offset:49152
	ds_read_b128 v[188:191], v152 offset:50688
	s_waitcnt lgkmcnt(1)
	v_mfma_f32_16x16x32_bf16 v[148:151], v[168:171], v[176:179], v[148:151]
	v_mfma_f32_16x16x32_bf16 v[136:139], v[172:175], v[176:179], v[136:139]
	v_mfma_f32_16x16x32_bf16 v[112:115], v[180:183], v[176:179], v[112:115]
	v_mfma_f32_16x16x32_bf16 v[80:83], v[184:187], v[176:179], v[80:83]
	ds_read_b128 v[176:179], v152 offset:52224
	s_waitcnt vmcnt(6)
	ds_write_b128 v229, v[200:203] offset:0
	s_waitcnt lgkmcnt(2)
	v_mfma_f32_16x16x32_bf16 v[144:147], v[168:171], v[188:191], v[144:147]
	v_mfma_f32_16x16x32_bf16 v[128:131], v[172:175], v[188:191], v[128:131]
	v_mfma_f32_16x16x32_bf16 v[100:103], v[180:183], v[188:191], v[100:103]
	v_mfma_f32_16x16x32_bf16 v[68:71], v[184:187], v[188:191], v[68:71]
	ds_read_b128 v[188:191], v152 offset:53760
	ds_write_b128 v229, v[204:207] offset:96
	s_waitcnt lgkmcnt(3)
	v_mfma_f32_16x16x32_bf16 v[140:143], v[168:171], v[176:179], v[140:143]
	v_mfma_f32_16x16x32_bf16 v[120:123], v[172:175], v[176:179], v[120:123]
	v_mfma_f32_16x16x32_bf16 v[88:91], v[180:183], v[176:179], v[88:91]
	v_mfma_f32_16x16x32_bf16 v[44:47], v[184:187], v[176:179], v[44:47]
	ds_read_b128 v[176:179], v152 offset:55296
	ds_write_b128 v230, v[208:211] offset:12288
	s_waitcnt lgkmcnt(3)
	v_mfma_f32_16x16x32_bf16 v[132:135], v[168:171], v[188:191], v[132:135]
	v_mfma_f32_16x16x32_bf16 v[108:111], v[172:175], v[188:191], v[108:111]
	v_mfma_f32_16x16x32_bf16 v[76:79], v[180:183], v[188:191], v[76:79]
	v_mfma_f32_16x16x32_bf16 v[40:43], v[184:187], v[188:191], v[40:43]
	ds_read_b128 v[188:191], v152 offset:56832
	ds_write_b128 v230, v[212:215] offset:12384
	s_waitcnt lgkmcnt(3)
	v_mfma_f32_16x16x32_bf16 v[124:127], v[168:171], v[176:179], v[124:127]
	v_mfma_f32_16x16x32_bf16 v[96:99], v[172:175], v[176:179], v[96:99]
	v_mfma_f32_16x16x32_bf16 v[64:67], v[180:183], v[176:179], v[64:67]
	v_mfma_f32_16x16x32_bf16 v[12:15], v[184:187], v[176:179], v[12:15]
	ds_read_b128 v[176:179], v152 offset:58368
	ds_write_b128 v230, v[220:223] offset:12480
	s_waitcnt lgkmcnt(3)
	v_mfma_f32_16x16x32_bf16 v[116:119], v[168:171], v[188:191], v[116:119]
	v_mfma_f32_16x16x32_bf16 v[84:87], v[172:175], v[188:191], v[84:87]
	v_mfma_f32_16x16x32_bf16 v[56:59], v[180:183], v[188:191], v[56:59]
	v_mfma_f32_16x16x32_bf16 v[8:11], v[184:187], v[188:191], v[8:11]
	ds_read_b128 v[188:191], v152 offset:59904
	ds_write_b128 v230, v[224:227] offset:12576
	s_waitcnt lgkmcnt(3)
	v_mfma_f32_16x16x32_bf16 v[104:107], v[168:171], v[176:179], v[104:107]
	v_mfma_f32_16x16x32_bf16 v[72:75], v[172:175], v[176:179], v[72:75]
	v_mfma_f32_16x16x32_bf16 v[52:55], v[180:183], v[176:179], v[52:55]
	v_mfma_f32_16x16x32_bf16 v[4:7], v[184:187], v[176:179], v[4:7]
	s_add_i32 s36, s36, 2
	s_waitcnt lgkmcnt(1)
	v_mfma_f32_16x16x32_bf16 v[92:95], v[168:171], v[188:191], v[92:95]
	v_mfma_f32_16x16x32_bf16 v[60:63], v[172:175], v[188:191], v[60:63]
	v_mfma_f32_16x16x32_bf16 v[48:51], v[180:183], v[188:191], v[48:51]
	v_mfma_f32_16x16x32_bf16 v[0:3], v[184:187], v[188:191], v[0:3]
	s_setprio 0
	s_waitcnt lgkmcnt(0)
	s_barrier
	s_setprio 1
	v_lshl_add_u32 v152, v167, 1, v164
	ds_read_b128 v[154:157], v152
	v_lshl_add_u32 v161, v165, 1, v164
	ds_read_b128 v[164:167], v152 offset:1536
	ds_read_b128 v[172:175], v152 offset:3072
	ds_read_b128 v[176:179], v152 offset:4608
	ds_read_b128 v[168:171], v161 offset:12288
	ds_read_b128 v[180:183], v161 offset:13824
	s_waitcnt lgkmcnt(1)
	v_mfma_f32_16x16x32_bf16 v[148:151], v[154:157], v[168:171], v[148:151]
	v_mfma_f32_16x16x32_bf16 v[136:139], v[164:167], v[168:171], v[136:139]
	v_mfma_f32_16x16x32_bf16 v[112:115], v[172:175], v[168:171], v[112:115]
	v_mfma_f32_16x16x32_bf16 v[80:83], v[176:179], v[168:171], v[80:83]
	ds_read_b128 v[168:171], v161 offset:15360
	s_waitcnt vmcnt(5)
	ds_write_b128 v162, v[20:23] offset:36864
	s_waitcnt lgkmcnt(2)
	v_mfma_f32_16x16x32_bf16 v[144:147], v[154:157], v[180:183], v[144:147]
	v_mfma_f32_16x16x32_bf16 v[128:131], v[164:167], v[180:183], v[128:131]
	v_mfma_f32_16x16x32_bf16 v[100:103], v[172:175], v[180:183], v[100:103]
	v_mfma_f32_16x16x32_bf16 v[68:71], v[176:179], v[180:183], v[68:71]
	ds_read_b128 v[180:183], v161 offset:16896
	s_waitcnt vmcnt(4)
	ds_write_b128 v162, v[16:19] offset:36960
	s_waitcnt lgkmcnt(3)
	v_mfma_f32_16x16x32_bf16 v[140:143], v[154:157], v[168:171], v[140:143]
	v_mfma_f32_16x16x32_bf16 v[120:123], v[164:167], v[168:171], v[120:123]
	v_mfma_f32_16x16x32_bf16 v[184:187], v[172:175], v[168:171], v[88:91]
	v_mfma_f32_16x16x32_bf16 v[44:47], v[176:179], v[168:171], v[44:47]
	s_nop 1
	ds_read_b128 v[88:91], v161 offset:18432
	s_waitcnt vmcnt(3)
	ds_write_b128 v163, v[36:39] offset:49152
	s_waitcnt lgkmcnt(3)
	v_mfma_f32_16x16x32_bf16 v[132:135], v[154:157], v[180:183], v[132:135]
	v_mfma_f32_16x16x32_bf16 v[168:171], v[164:167], v[180:183], v[108:111]
	v_mfma_f32_16x16x32_bf16 v[188:191], v[172:175], v[180:183], v[76:79]
	v_mfma_f32_16x16x32_bf16 v[180:183], v[176:179], v[180:183], v[40:43]
	s_nop 2
	ds_read_b128 v[40:43], v161 offset:19968
	s_waitcnt vmcnt(2)
	ds_write_b128 v163, v[32:35] offset:49248
	s_waitcnt lgkmcnt(3)
	v_mfma_f32_16x16x32_bf16 v[124:127], v[154:157], v[88:91], v[124:127]
	v_mfma_f32_16x16x32_bf16 v[192:195], v[164:167], v[88:91], v[96:99]
	v_mfma_f32_16x16x32_bf16 v[196:199], v[172:175], v[88:91], v[64:67]
	v_mfma_f32_16x16x32_bf16 v[200:203], v[176:179], v[88:91], v[12:15]
	s_nop 2
	ds_read_b128 v[12:15], v161 offset:21504
	s_waitcnt vmcnt(1)
	ds_write_b128 v163, v[28:31] offset:49344
	s_waitcnt lgkmcnt(3)
	v_mfma_f32_16x16x32_bf16 v[116:119], v[154:157], v[40:43], v[116:119]
	v_mfma_f32_16x16x32_bf16 v[204:207], v[164:167], v[40:43], v[84:87]
	v_mfma_f32_16x16x32_bf16 v[56:59], v[172:175], v[40:43], v[56:59]
	v_mfma_f32_16x16x32_bf16 v[208:211], v[176:179], v[40:43], v[8:11]
	s_nop 2
	ds_read_b128 v[8:11], v161 offset:23040
	s_waitcnt vmcnt(0)
	ds_write_b128 v163, v[24:27] offset:49440
	s_waitcnt lgkmcnt(3)
	v_mfma_f32_16x16x32_bf16 v[212:215], v[154:157], v[12:15], v[104:107]
	v_mfma_f32_16x16x32_bf16 v[72:75], v[164:167], v[12:15], v[72:75]
	v_mfma_f32_16x16x32_bf16 v[220:223], v[172:175], v[12:15], v[52:55]
	v_mfma_f32_16x16x32_bf16 v[224:227], v[176:179], v[12:15], v[4:7]
	s_waitcnt lgkmcnt(1)
	v_mfma_f32_16x16x32_bf16 v[154:157], v[154:157], v[8:11], v[92:95]
	v_mfma_f32_16x16x32_bf16 v[60:63], v[164:167], v[8:11], v[60:63]
	v_mfma_f32_16x16x32_bf16 v[164:167], v[172:175], v[8:11], v[48:51]
	v_mfma_f32_16x16x32_bf16 v[172:175], v[176:179], v[8:11], v[0:3]
	s_setprio 0
	s_waitcnt lgkmcnt(0)
	s_barrier
; DI void store4(u16* dst, f32x4 v) { uint2 w; w.x = cvtpk(v[0], v[1]); w.y = cvtpk(v[2], v[3]); *(uint2*)dst = w; }
; DI f32x4 mfma16(bf16x8 a, bf16x8 b, f32x4 c) { return __builtin_amdgcn_mfma_f32_16x16x32_bf16(a, b, c, 0, 0, 0); }
; template <int NI, class XL, class EP>
; DI void gemm_tile(const u16* __restrict__ W, int ldw, int f0, int t0, int K, XL xl, EP ep, unsigned char* smem) {
;     ...
;   for (int it = 0; it < nk; ++it) {
;     const u16* Ws = S0 + (it & 1) * BUF; const u16* Xs = Ws + 128 * LST;
;     __builtin_amdgcn_s_setprio(1);
;     bf16x8 a[4];
; #pragma unroll
;     for (int mi = 0; mi < 4; ++mi) a[mi] = *(const bf16x8*)(Ws + (wf * 64 + mi * 16 + lr) * LST + lq * 8);
; #pragma unroll
;     for (int ni = 0; ni < NI; ++ni) {
;       const bf16x8 b = *(const bf16x8*)(Xs + (wt * (NI * 16) + ni * 16 + lr) * LST + lq * 8);
; #pragma unroll
;       for (int mi = 0; mi < 4; ++mi) acc[mi][ni] = mfma16(a[mi], b, acc[mi][ni]);
;     }
;     __builtin_amdgcn_sched_group_barrier(0x100, 6, 0);
; #pragma unroll
;     for (int ni = 0; ni < NI; ++ni) { __builtin_amdgcn_sched_group_barrier(0x008, 4, 0); if (ni + 2 < NI) __builtin_amdgcn_sched_group_barrier(0x100, 1, 0); }
;     __builtin_amdgcn_s_setprio(0);
; DI void phase6(const Params& p, const Sched& sched, unsigned char* smem) {
;     ...
;       constexpr int EST = 136;
;       u16* Ls = (u16*)smem;
;       const int b = tb >> 11;
;       __syncthreads();
; #pragma unroll
;       for (int mi = 0; mi < 4; ++mi) {
;         const int f = fb + mi * 16 + lq * 4; const float4 gm = *(const float4*)(mod + (size_t)b * 6144 + 2048 + f);
; #pragma unroll
;         for (int ni = 0; ni < 8; ++ni) {
;           const f32x4 o = {gm.x * acc[mi][ni][0], gm.y * acc[mi][ni][1], gm.z * acc[mi][ni][2], gm.w * acc[mi][ni][3]};
;           store4(Ls + (wt * 128 + ni * 16 + lr) * EST + wf * 64 + mi * 16 + lq * 4, o);
;         }
;       }
	s_lshl_b32 s34, s34, 7
	s_setprio 1
	ds_read_b128 v[28:31], v152 offset:36864
	ds_read_b128 v[176:179], v152 offset:38400
	ds_read_b128 v[228:231], v152 offset:39936
	ds_read_b128 v[232:235], v152 offset:41472
	ds_read_b128 v[0:3], v161 offset:49152
	ds_read_b128 v[4:7], v161 offset:50688
	s_waitcnt lgkmcnt(1)
	v_mfma_f32_16x16x32_bf16 v[88:91], v[28:31], v[0:3], v[148:151]
	v_mfma_f32_16x16x32_bf16 v[64:67], v[176:179], v[0:3], v[136:139]
	v_mfma_f32_16x16x32_bf16 v[32:35], v[228:231], v[0:3], v[112:115]
	v_mfma_f32_16x16x32_bf16 v[0:3], v[232:235], v[0:3], v[80:83]
	ds_read_b128 v[8:11], v161 offset:52224
	s_waitcnt lgkmcnt(1)
	v_mfma_f32_16x16x32_bf16 v[96:99], v[28:31], v[4:7], v[144:147]
	v_mfma_f32_16x16x32_bf16 v[76:79], v[176:179], v[4:7], v[128:131]
	v_mfma_f32_16x16x32_bf16 v[36:39], v[228:231], v[4:7], v[100:103]
	v_mfma_f32_16x16x32_bf16 v[4:7], v[232:235], v[4:7], v[68:71]
	ds_read_b128 v[12:15], v161 offset:53760
	s_waitcnt lgkmcnt(1)
	v_mfma_f32_16x16x32_bf16 v[104:107], v[28:31], v[8:11], v[140:143]
	v_mfma_f32_16x16x32_bf16 v[84:87], v[176:179], v[8:11], v[120:123]
	v_mfma_f32_16x16x32_bf16 v[40:43], v[228:231], v[8:11], v[184:187]
	v_mfma_f32_16x16x32_bf16 v[8:11], v[232:235], v[8:11], v[44:47]
	ds_read_b128 v[16:19], v161 offset:55296
	s_waitcnt lgkmcnt(1)
	v_mfma_f32_16x16x32_bf16 v[108:111], v[28:31], v[12:15], v[132:135]
	v_mfma_f32_16x16x32_bf16 v[92:95], v[176:179], v[12:15], v[168:171]
	v_mfma_f32_16x16x32_bf16 v[44:47], v[228:231], v[12:15], v[188:191]
	v_mfma_f32_16x16x32_bf16 v[12:15], v[232:235], v[12:15], v[180:183]
	ds_read_b128 v[20:23], v161 offset:56832
	s_waitcnt lgkmcnt(1)
	v_mfma_f32_16x16x32_bf16 v[112:115], v[28:31], v[16:19], v[124:127]
	v_mfma_f32_16x16x32_bf16 v[100:103], v[176:179], v[16:19], v[192:195]
	v_mfma_f32_16x16x32_bf16 v[48:51], v[228:231], v[16:19], v[196:199]
	v_mfma_f32_16x16x32_bf16 v[16:19], v[232:235], v[16:19], v[200:203]
	ds_read_b128 v[24:27], v161 offset:58368
	s_waitcnt lgkmcnt(1)
	v_mfma_f32_16x16x32_bf16 v[116:119], v[28:31], v[20:23], v[116:119]
	v_mfma_f32_16x16x32_bf16 v[68:71], v[176:179], v[20:23], v[204:207]
	v_mfma_f32_16x16x32_bf16 v[52:55], v[228:231], v[20:23], v[56:59]
	v_mfma_f32_16x16x32_bf16 v[20:23], v[232:235], v[20:23], v[208:211]
	ds_read_b128 v[128:131], v161 offset:59904
	s_waitcnt lgkmcnt(1)
	v_mfma_f32_16x16x32_bf16 v[120:123], v[28:31], v[24:27], v[212:215]
	v_mfma_f32_16x16x32_bf16 v[80:83], v[176:179], v[24:27], v[72:75]
	v_mfma_f32_16x16x32_bf16 v[56:59], v[228:231], v[24:27], v[220:223]
	v_mfma_f32_16x16x32_bf16 v[24:27], v[232:235], v[24:27], v[224:227]
	s_waitcnt lgkmcnt(0)
	v_mfma_f32_16x16x32_bf16 v[124:127], v[28:31], v[128:131], v[154:157]
	v_mfma_f32_16x16x32_bf16 v[72:75], v[176:179], v[128:131], v[60:63]
	v_mfma_f32_16x16x32_bf16 v[60:63], v[228:231], v[128:131], v[164:167]
	v_mfma_f32_16x16x32_bf16 v[28:31], v[232:235], v[128:131], v[172:175]
	s_setprio 0
	s_ashr_i32 s35, s35, 3
	v_add_u32_e32 v128, s34, v160
	s_mul_hi_i32 s37, s35, 0x6000
	s_mulk_i32 s35, 0x6000
	v_lshl_or_b32 v128, v158, 2, v128
	s_add_u32 s36, s72, s35
	s_addc_u32 s37, s73, s37
	v_ashrrev_i32_e32 v129, 31, v128
	v_lshl_add_u64 v[128:129], v[128:129], 2, s[36:37]
	v_add_co_u32_e32 v140, vcc, s26, v128
	v_mul_u32_u24_e32 v138, 0x88, v159
	s_nop 0
	v_addc_co_u32_e32 v141, vcc, 0, v129, vcc
	v_lshlrev_b32_e32 v136, 1, v160
	v_lshlrev_b32_e32 v137, 3, v158
	v_lshlrev_b32_e32 v138, 1, v138
	s_barrier
	global_load_dwordx4 v[128:131], v[140:141], off
	global_load_dwordx4 v[132:135], v[140:141], off offset:64
	v_add3_u32 v144, v136, v137, v138
	global_load_dwordx4 v[136:139], v[140:141], off offset:128
	v_add_u32_e32 v145, 0x1000, v144
	global_load_dwordx4 v[140:143], v[140:141], off offset:192
	v_add_u32_e32 v146, 0x2000, v144
	v_add_u32_e32 v147, 0x3000, v144
	v_add_u32_e32 v148, 0x4000, v144
	s_add_i32 s31, s31, s78
	s_add_i32 s30, s30, s78
	s_cmp_gt_i32 s31, 63
	s_waitcnt vmcnt(3)
	v_pk_mul_f32 v[88:89], v[88:89], v[128:129]
	v_pk_mul_f32 v[90:91], v[90:91], v[130:131]
	v_pk_mul_f32 v[96:97], v[96:97], v[128:129]
	s_waitcnt vmcnt(1)
	v_pk_mul_f32 v[32:33], v[32:33], v[136:137]
	v_pk_mul_f32 v[34:35], v[34:35], v[138:139]
	s_waitcnt vmcnt(0)
	v_pk_mul_f32 v[0:1], v[0:1], v[140:141]
	v_pk_mul_f32 v[2:3], v[2:3], v[142:143]
	v_cvt_pk_bf16_f32 v32, v32, v33
	v_cvt_pk_bf16_f32 v33, v34, v35
	v_cvt_pk_bf16_f32 v0, v0, v1
	v_cvt_pk_bf16_f32 v1, v2, v3
	v_pk_mul_f32 v[34:35], v[36:37], v[136:137]
	v_pk_mul_f32 v[36:37], v[38:39], v[138:139]
	ds_write2_b64 v144, v[32:33], v[0:1] offset0:8 offset1:12
	v_pk_mul_f32 v[0:1], v[4:5], v[140:141]
	v_pk_mul_f32 v[2:3], v[6:7], v[142:143]
	v_cvt_pk_bf16_f32 v34, v34, v35
	v_cvt_pk_bf16_f32 v35, v36, v37
	v_cvt_pk_bf16_f32 v0, v0, v1
	v_cvt_pk_bf16_f32 v1, v2, v3
	v_pk_mul_f32 v[36:37], v[40:41], v[136:137]
	v_pk_mul_f32 v[38:39], v[42:43], v[138:139]
	ds_write2_b64 v145, v[34:35], v[0:1] offset0:40 offset1:44
	v_pk_mul_f32 v[0:1], v[8:9], v[140:141]
	v_pk_mul_f32 v[2:3], v[10:11], v[142:143]
	v_cvt_pk_bf16_f32 v36, v36, v37
	v_cvt_pk_bf16_f32 v37, v38, v39
	v_cvt_pk_bf16_f32 v0, v0, v1
	v_cvt_pk_bf16_f32 v1, v2, v3
	v_pk_mul_f32 v[38:39], v[44:45], v[136:137]
	v_pk_mul_f32 v[40:41], v[46:47], v[138:139]
	ds_write2_b64 v146, v[36:37], v[0:1] offset0:72 offset1:76
	v_pk_mul_f32 v[0:1], v[12:13], v[140:141]
	v_pk_mul_f32 v[2:3], v[14:15], v[142:143]
	v_cvt_pk_bf16_f32 v38, v38, v39
	v_cvt_pk_bf16_f32 v39, v40, v41
	v_cvt_pk_bf16_f32 v0, v0, v1
	v_cvt_pk_bf16_f32 v1, v2, v3
	v_pk_mul_f32 v[98:99], v[98:99], v[130:131]
	v_pk_mul_f32 v[64:65], v[64:65], v[132:133]
	v_pk_mul_f32 v[66:67], v[66:67], v[134:135]
	v_pk_mul_f32 v[76:77], v[76:77], v[132:133]
; DI void store4(u16* dst, f32x4 v) { uint2 w; w.x = cvtpk(v[0], v[1]); w.y = cvtpk(v[2], v[3]); *(uint2*)dst = w; }
; DI void phase6(const Params& p, const Sched& sched, unsigned char* smem) {
;     ...
; #pragma unroll
;       for (int mi = 0; mi < 4; ++mi) {
;         const int f = fb + mi * 16 + lq * 4; const float4 gm = *(const float4*)(mod + (size_t)b * 6144 + 2048 + f);
; #pragma unroll
;         for (int ni = 0; ni < 8; ++ni) {
;           const f32x4 o = {gm.x * acc[mi][ni][0], gm.y * acc[mi][ni][1], gm.z * acc[mi][ni][2], gm.w * acc[mi][ni][3]};
;           store4(Ls + (wt * 128 + ni * 16 + lr) * EST + wf * 64 + mi * 16 + lq * 4, o);
;         }
;       }
;       __syncthreads();
	v_pk_mul_f32 v[78:79], v[78:79], v[134:135]
	v_pk_mul_f32 v[40:41], v[48:49], v[136:137]
	v_pk_mul_f32 v[42:43], v[50:51], v[138:139]
	ds_write2_b64 v147, v[38:39], v[0:1] offset0:104 offset1:108
	v_pk_mul_f32 v[0:1], v[16:17], v[140:141]
	v_pk_mul_f32 v[2:3], v[18:19], v[142:143]
	v_cvt_pk_bf16_f32 v88, v88, v89
	v_cvt_pk_bf16_f32 v89, v90, v91
	v_cvt_pk_bf16_f32 v90, v96, v97
	v_cvt_pk_bf16_f32 v91, v98, v99
	v_cvt_pk_bf16_f32 v64, v64, v65
	v_cvt_pk_bf16_f32 v65, v66, v67
	v_cvt_pk_bf16_f32 v66, v76, v77
	v_cvt_pk_bf16_f32 v67, v78, v79
	v_cvt_pk_bf16_f32 v40, v40, v41
	v_cvt_pk_bf16_f32 v41, v42, v43
	v_cvt_pk_bf16_f32 v0, v0, v1
	v_cvt_pk_bf16_f32 v1, v2, v3
	v_pk_mul_f32 v[106:107], v[106:107], v[130:131]
	v_pk_mul_f32 v[116:117], v[116:117], v[128:129]
	v_pk_mul_f32 v[118:119], v[118:119], v[130:131]
	ds_write2_b64 v144, v[88:89], v[64:65] offset1:4
	ds_write2_b64 v145, v[90:91], v[66:67] offset0:32 offset1:36
	v_pk_mul_f32 v[64:65], v[68:69], v[132:133]
	v_pk_mul_f32 v[66:67], v[70:71], v[134:135]
	v_pk_mul_f32 v[42:43], v[52:53], v[136:137]
	v_pk_mul_f32 v[44:45], v[54:55], v[138:139]
	ds_write2_b64 v148, v[40:41], v[0:1] offset0:136 offset1:140
	v_pk_mul_f32 v[0:1], v[20:21], v[140:141]
	v_pk_mul_f32 v[2:3], v[22:23], v[142:143]
	v_cvt_pk_bf16_f32 v97, v106, v107
	v_cvt_pk_bf16_f32 v106, v116, v117
	v_cvt_pk_bf16_f32 v107, v118, v119
	v_cvt_pk_bf16_f32 v64, v64, v65
	v_cvt_pk_bf16_f32 v65, v66, v67
	v_add_u32_e32 v68, 0x5000, v144
	v_cvt_pk_bf16_f32 v42, v42, v43
	v_cvt_pk_bf16_f32 v43, v44, v45
	v_cvt_pk_bf16_f32 v0, v0, v1
	v_cvt_pk_bf16_f32 v1, v2, v3
	v_pk_mul_f32 v[108:109], v[108:109], v[128:129]
	v_pk_mul_f32 v[120:121], v[120:121], v[128:129]
	v_pk_mul_f32 v[122:123], v[122:123], v[130:131]
	ds_write2_b64 v68, v[106:107], v[64:65] offset0:160 offset1:164
	v_pk_mul_f32 v[64:65], v[80:81], v[132:133]
	v_pk_mul_f32 v[66:67], v[82:83], v[134:135]
	v_pk_mul_f32 v[44:45], v[56:57], v[136:137]
	v_pk_mul_f32 v[46:47], v[58:59], v[138:139]
	ds_write2_b64 v68, v[42:43], v[0:1] offset0:168 offset1:172
	v_pk_mul_f32 v[0:1], v[24:25], v[140:141]
	v_pk_mul_f32 v[2:3], v[26:27], v[142:143]
	v_cvt_pk_bf16_f32 v98, v108, v109
	v_cvt_pk_bf16_f32 v108, v120, v121
	v_cvt_pk_bf16_f32 v109, v122, v123
	v_cvt_pk_bf16_f32 v64, v64, v65
	v_cvt_pk_bf16_f32 v65, v66, v67
	v_add_u32_e32 v69, 0x6000, v144
	v_cvt_pk_bf16_f32 v44, v44, v45
	v_cvt_pk_bf16_f32 v45, v46, v47
	v_cvt_pk_bf16_f32 v0, v0, v1
	v_cvt_pk_bf16_f32 v1, v2, v3
	v_pk_mul_f32 v[104:105], v[104:105], v[128:129]
	v_pk_mul_f32 v[110:111], v[110:111], v[130:131]
	v_pk_mul_f32 v[112:113], v[112:113], v[128:129]
	v_pk_mul_f32 v[114:115], v[114:115], v[130:131]
	v_pk_mul_f32 v[124:125], v[124:125], v[128:129]
	v_pk_mul_f32 v[126:127], v[126:127], v[130:131]
	v_pk_mul_f32 v[84:85], v[84:85], v[132:133]
	v_pk_mul_f32 v[86:87], v[86:87], v[134:135]
	v_pk_mul_f32 v[92:93], v[92:93], v[132:133]
	v_pk_mul_f32 v[94:95], v[94:95], v[134:135]
	v_pk_mul_f32 v[100:101], v[100:101], v[132:133]
	v_pk_mul_f32 v[102:103], v[102:103], v[134:135]
	ds_write2_b64 v69, v[108:109], v[64:65] offset0:192 offset1:196
	v_pk_mul_f32 v[64:65], v[72:73], v[132:133]
	v_pk_mul_f32 v[66:67], v[74:75], v[134:135]
	v_pk_mul_f32 v[46:47], v[60:61], v[136:137]
	v_pk_mul_f32 v[48:49], v[62:63], v[138:139]
	ds_write2_b64 v69, v[44:45], v[0:1] offset0:200 offset1:204
	v_pk_mul_f32 v[0:1], v[28:29], v[140:141]
	v_pk_mul_f32 v[2:3], v[30:31], v[142:143]
	v_cvt_pk_bf16_f32 v96, v104, v105
	v_cvt_pk_bf16_f32 v99, v110, v111
	v_cvt_pk_bf16_f32 v104, v112, v113
	v_cvt_pk_bf16_f32 v105, v114, v115
	v_cvt_pk_bf16_f32 v110, v124, v125
	v_cvt_pk_bf16_f32 v111, v126, v127
	v_cvt_pk_bf16_f32 v76, v84, v85
	v_cvt_pk_bf16_f32 v77, v86, v87
	v_cvt_pk_bf16_f32 v78, v92, v93
	v_cvt_pk_bf16_f32 v79, v94, v95
	v_cvt_pk_bf16_f32 v84, v100, v101
	v_cvt_pk_bf16_f32 v85, v102, v103
	v_cvt_pk_bf16_f32 v64, v64, v65
	v_cvt_pk_bf16_f32 v65, v66, v67
	v_add_u32_e32 v66, 0x7000, v144
	v_cvt_pk_bf16_f32 v46, v46, v47
	v_cvt_pk_bf16_f32 v47, v48, v49
	v_cvt_pk_bf16_f32 v0, v0, v1
	v_cvt_pk_bf16_f32 v1, v2, v3
	v_mov_b32_e32 v2, v218
	ds_write2_b64 v146, v[96:97], v[76:77] offset0:64 offset1:68
	ds_write2_b64 v147, v[98:99], v[78:79] offset0:96 offset1:100
	ds_write2_b64 v148, v[104:105], v[84:85] offset0:128 offset1:132
	ds_write2_b64 v66, v[110:111], v[64:65] offset0:224 offset1:228
	ds_write2_b64 v66, v[46:47], v[0:1] offset0:232 offset1:236
	s_waitcnt lgkmcnt(0)
	s_barrier
; DI int tidx() { int t = __builtin_amdgcn_workitem_id_x(); asm volatile("" : "+v"(t)); return t; }
; DI unsigned cvtpk(float lo, float hi) { const f32x2_ v = {lo, hi}; return __builtin_bit_cast(unsigned, __builtin_convertvector(v, bf16x2_)); }
; DI float bflo(unsigned w) { return __uint_as_float(w << 16); }
; DI float bfhi(unsigned w) { return __uint_as_float(w & 0xffff0000u); }
; DI void phase6(const Params& p, const Sched& sched, unsigned char* smem) {
;     ...
;       const int tid = tidx();
; #pragma unroll
;       for (int i = 0; i < 16; ++i) {
;         const int c = tid + 256 * i, row = c >> 4, ch = (c & 15) * 8;
;         const size_t gi = (size_t)(tm * 256 + row) * 1024 + tn * 128 + ch;
;         const u32x4 sv = *(const u32x4*)(Ls + row * EST + ch);
;         const f32x4 x0 = *(const f32x4*)(p.x + gi), x1 = *(const f32x4*)(p.x + gi + 4);
;         u32x4 w;
;         w.x = cvtpk(x0[0] + bflo(sv.x), x0[1] + bfhi(sv.x)); w.y = cvtpk(x0[2] + bflo(sv.y), x0[3] + bfhi(sv.y));
;         w.z = cvtpk(x1[0] + bflo(sv.z), x1[1] + bfhi(sv.z)); w.w = cvtpk(x1[2] + bflo(sv.w), x1[3] + bfhi(sv.w));
;         *(u32x4*)(x1b + gi) = w;
;       }
	s_nop 0
	v_ashrrev_i32_e32 v3, 4, v2
	v_add_u32_e32 v4, s33, v3
	v_lshlrev_b32_e32 v0, 3, v2
	v_ashrrev_i32_e32 v5, 31, v4
	v_and_b32_e32 v1, 0x78, v0
	v_lshlrev_b64 v[16:17], 10, v[4:5]
	v_or3_b32 v16, v16, s34, v1
	v_lshl_add_u64 v[8:9], v[16:17], 2, s[76:77]
	global_load_dwordx4 v[4:7], v[8:9], off
	v_lshlrev_b32_e32 v0, 1, v1
	global_load_dwordx4 v[8:11], v[8:9], off offset:16
	v_mad_u64_u32 v[12:13], s[36:37], v3, s27, v[0:1]
	ds_read_b128 v[12:15], v12
	v_add_u32_e32 v3, 0x100, v2
	v_ashrrev_i32_e32 v3, 4, v3
	s_waitcnt lgkmcnt(0)
	v_lshlrev_b32_e32 v18, 16, v12
	v_and_b32_e32 v19, 0xffff0000, v12
	v_lshlrev_b32_e32 v12, 16, v13
	v_and_b32_e32 v13, 0xffff0000, v13
	s_waitcnt vmcnt(1)
	v_pk_add_f32 v[4:5], v[4:5], v[18:19]
	v_pk_add_f32 v[6:7], v[6:7], v[12:13]
	v_cvt_pk_bf16_f32 v4, v4, v5
	v_cvt_pk_bf16_f32 v5, v6, v7
	v_lshlrev_b32_e32 v6, 16, v14
	v_and_b32_e32 v7, 0xffff0000, v14
	s_waitcnt vmcnt(0)
	v_pk_add_f32 v[6:7], v[8:9], v[6:7]
	v_lshlrev_b32_e32 v8, 16, v15
	v_and_b32_e32 v9, 0xffff0000, v15
	v_pk_add_f32 v[8:9], v[10:11], v[8:9]
	v_cvt_pk_bf16_f32 v6, v6, v7
	v_cvt_pk_bf16_f32 v7, v8, v9
	v_lshl_add_u64 v[8:9], v[16:17], 1, s[12:13]
	global_store_dwordx4 v[8:9], v[4:7], off
	v_add_u32_e32 v12, 0x200, v2
	v_ashrrev_i32_e32 v26, 4, v12
	v_add_u32_e32 v4, s33, v3
	v_ashrrev_i32_e32 v5, 31, v4
	v_lshlrev_b64 v[16:17], 10, v[4:5]
	v_or3_b32 v16, v16, s34, v1
	v_lshl_add_u64 v[8:9], v[16:17], 2, s[76:77]
	global_load_dwordx4 v[4:7], v[8:9], off
	v_mad_u64_u32 v[12:13], s[36:37], v3, s27, v[0:1]
	global_load_dwordx4 v[8:11], v[8:9], off offset:16
	ds_read_b128 v[12:15], v12
	v_add_u32_e32 v18, s33, v26
	v_ashrrev_i32_e32 v19, 31, v18
	v_lshlrev_b64 v[18:19], 10, v[18:19]
	v_or3_b32 v18, v18, s34, v1
	s_waitcnt lgkmcnt(0)
	v_lshlrev_b32_e32 v22, 16, v12
	v_and_b32_e32 v23, 0xffff0000, v12
	v_lshlrev_b32_e32 v12, 16, v13
	v_and_b32_e32 v13, 0xffff0000, v13
	v_lshlrev_b32_e32 v24, 16, v14
	v_and_b32_e32 v25, 0xffff0000, v14
	v_lshlrev_b32_e32 v14, 16, v15
	v_and_b32_e32 v15, 0xffff0000, v15
	v_lshl_add_u64 v[16:17], v[16:17], 1, s[12:13]
	v_lshl_add_u64 v[20:21], v[18:19], 2, s[76:77]
	v_add_u32_e32 v3, 0x300, v2
	v_ashrrev_i32_e32 v3, 4, v3
	v_lshl_add_u64 v[18:19], v[18:19], 1, s[12:13]
	s_waitcnt vmcnt(1)
	v_pk_add_f32 v[4:5], v[4:5], v[22:23]
	v_pk_add_f32 v[6:7], v[6:7], v[12:13]
	v_cvt_pk_bf16_f32 v4, v4, v5
	s_waitcnt vmcnt(0)
	v_pk_add_f32 v[8:9], v[8:9], v[24:25]
	v_pk_add_f32 v[10:11], v[10:11], v[14:15]
	v_cvt_pk_bf16_f32 v5, v6, v7
	v_cvt_pk_bf16_f32 v6, v8, v9
	v_cvt_pk_bf16_f32 v7, v10, v11
	global_store_dwordx4 v[16:17], v[4:7], off
	global_load_dwordx4 v[4:7], v[20:21], off
	v_mad_u64_u32 v[12:13], s[36:37], v26, s27, v[0:1]
	global_load_dwordx4 v[8:11], v[20:21], off offset:16
	ds_read_b128 v[12:15], v12
	v_add_u32_e32 v16, s33, v3
	v_ashrrev_i32_e32 v17, 31, v16
	v_lshlrev_b64 v[16:17], 10, v[16:17]
	v_or3_b32 v16, v16, s34, v1
	s_waitcnt lgkmcnt(0)
	v_lshlrev_b32_e32 v22, 16, v12
	v_and_b32_e32 v23, 0xffff0000, v12
	v_lshlrev_b32_e32 v12, 16, v13
	v_and_b32_e32 v13, 0xffff0000, v13
	v_lshlrev_b32_e32 v24, 16, v14
	v_and_b32_e32 v25, 0xffff0000, v14
	v_lshlrev_b32_e32 v14, 16, v15
	v_and_b32_e32 v15, 0xffff0000, v15
	v_lshl_add_u64 v[20:21], v[16:17], 2, s[76:77]
	v_lshl_add_u64 v[16:17], v[16:17], 1, s[12:13]
	s_waitcnt vmcnt(1)
	v_pk_add_f32 v[4:5], v[4:5], v[22:23]
	v_pk_add_f32 v[6:7], v[6:7], v[12:13]
	v_cvt_pk_bf16_f32 v4, v4, v5
	s_waitcnt vmcnt(0)
	v_pk_add_f32 v[8:9], v[8:9], v[24:25]
	v_pk_add_f32 v[10:11], v[10:11], v[14:15]
	v_cvt_pk_bf16_f32 v5, v6, v7
	v_cvt_pk_bf16_f32 v6, v8, v9
	v_cvt_pk_bf16_f32 v7, v10, v11
	global_store_dwordx4 v[18:19], v[4:7], off
	global_load_dwordx4 v[4:7], v[20:21], off
	v_add_u32_e32 v12, 0x400, v2
	global_load_dwordx4 v[8:11], v[20:21], off offset:16
	v_ashrrev_i32_e32 v26, 4, v12
	v_mad_u64_u32 v[12:13], s[36:37], v3, s27, v[0:1]
	ds_read_b128 v[12:15], v12
	v_add_u32_e32 v18, s33, v26
	v_ashrrev_i32_e32 v19, 31, v18
	v_lshlrev_b64 v[18:19], 10, v[18:19]
	v_or3_b32 v18, v18, s34, v1
	s_waitcnt lgkmcnt(0)
	v_lshlrev_b32_e32 v22, 16, v12
	v_and_b32_e32 v23, 0xffff0000, v12
	v_lshlrev_b32_e32 v12, 16, v13
	v_and_b32_e32 v13, 0xffff0000, v13
	v_lshlrev_b32_e32 v24, 16, v14
	v_and_b32_e32 v25, 0xffff0000, v14
	v_lshlrev_b32_e32 v14, 16, v15
	v_and_b32_e32 v15, 0xffff0000, v15
	v_lshl_add_u64 v[20:21], v[18:19], 2, s[76:77]
	v_add_u32_e32 v3, 0x500, v2
	v_ashrrev_i32_e32 v3, 4, v3
	v_lshl_add_u64 v[18:19], v[18:19], 1, s[12:13]
	s_waitcnt vmcnt(1)
	v_pk_add_f32 v[4:5], v[4:5], v[22:23]
	v_pk_add_f32 v[6:7], v[6:7], v[12:13]
	s_waitcnt vmcnt(0)
	v_pk_add_f32 v[8:9], v[8:9], v[24:25]
	v_pk_add_f32 v[10:11], v[10:11], v[14:15]
	v_cvt_pk_bf16_f32 v4, v4, v5
	v_cvt_pk_bf16_f32 v5, v6, v7
	v_cvt_pk_bf16_f32 v6, v8, v9
	v_cvt_pk_bf16_f32 v7, v10, v11
	global_store_dwordx4 v[16:17], v[4:7], off
	global_load_dwordx4 v[4:7], v[20:21], off
	v_mad_u64_u32 v[12:13], s[36:37], v26, s27, v[0:1]
	global_load_dwordx4 v[8:11], v[20:21], off offset:16
	ds_read_b128 v[12:15], v12
	v_add_u32_e32 v16, s33, v3
	v_ashrrev_i32_e32 v17, 31, v16
	v_lshlrev_b64 v[16:17], 10, v[16:17]
	v_or3_b32 v16, v16, s34, v1
	s_waitcnt lgkmcnt(0)
	v_lshlrev_b32_e32 v22, 16, v12
	v_and_b32_e32 v23, 0xffff0000, v12
	v_lshlrev_b32_e32 v12, 16, v13
	v_and_b32_e32 v13, 0xffff0000, v13
	v_lshlrev_b32_e32 v24, 16, v14
	v_and_b32_e32 v25, 0xffff0000, v14
	v_lshlrev_b32_e32 v14, 16, v15
	v_and_b32_e32 v15, 0xffff0000, v15
	v_lshl_add_u64 v[20:21], v[16:17], 2, s[76:77]
	v_lshl_add_u64 v[16:17], v[16:17], 1, s[12:13]
	s_waitcnt vmcnt(1)
	v_pk_add_f32 v[4:5], v[4:5], v[22:23]
	v_pk_add_f32 v[6:7], v[6:7], v[12:13]
	v_cvt_pk_bf16_f32 v4, v4, v5
	s_waitcnt vmcnt(0)
; DI int tidx() { int t = __builtin_amdgcn_workitem_id_x(); asm volatile("" : "+v"(t)); return t; }
; DI unsigned cvtpk(float lo, float hi) { const f32x2_ v = {lo, hi}; return __builtin_bit_cast(unsigned, __builtin_convertvector(v, bf16x2_)); }
; DI float bflo(unsigned w) { return __uint_as_float(w << 16); }
; DI float bfhi(unsigned w) { return __uint_as_float(w & 0xffff0000u); }
; DI void phase6(const Params& p, const Sched& sched, unsigned char* smem) {
;     ...
;       const int tid = tidx();
; #pragma unroll
;       for (int i = 0; i < 16; ++i) {
;         const int c = tid + 256 * i, row = c >> 4, ch = (c & 15) * 8;
;         const size_t gi = (size_t)(tm * 256 + row) * 1024 + tn * 128 + ch;
;         const u32x4 sv = *(const u32x4*)(Ls + row * EST + ch);
;         const f32x4 x0 = *(const f32x4*)(p.x + gi), x1 = *(const f32x4*)(p.x + gi + 4);
;         u32x4 w;
;         w.x = cvtpk(x0[0] + bflo(sv.x), x0[1] + bfhi(sv.x)); w.y = cvtpk(x0[2] + bflo(sv.y), x0[3] + bfhi(sv.y));
;         w.z = cvtpk(x1[0] + bflo(sv.z), x1[1] + bfhi(sv.z)); w.w = cvtpk(x1[2] + bflo(sv.w), x1[3] + bfhi(sv.w));
;         *(u32x4*)(x1b + gi) = w;
;       }
	v_pk_add_f32 v[8:9], v[8:9], v[24:25]
	v_pk_add_f32 v[10:11], v[10:11], v[14:15]
	v_cvt_pk_bf16_f32 v5, v6, v7
	v_cvt_pk_bf16_f32 v6, v8, v9
	v_cvt_pk_bf16_f32 v7, v10, v11
	global_store_dwordx4 v[18:19], v[4:7], off
	global_load_dwordx4 v[4:7], v[20:21], off
	v_add_u32_e32 v12, 0x600, v2
	global_load_dwordx4 v[8:11], v[20:21], off offset:16
	v_ashrrev_i32_e32 v26, 4, v12
	v_mad_u64_u32 v[12:13], s[36:37], v3, s27, v[0:1]
	ds_read_b128 v[12:15], v12
	v_add_u32_e32 v18, s33, v26
	v_ashrrev_i32_e32 v19, 31, v18
	v_lshlrev_b64 v[18:19], 10, v[18:19]
	v_or3_b32 v18, v18, s34, v1
	s_waitcnt lgkmcnt(0)
	v_lshlrev_b32_e32 v22, 16, v12
	v_and_b32_e32 v23, 0xffff0000, v12
	v_lshlrev_b32_e32 v12, 16, v13
	v_and_b32_e32 v13, 0xffff0000, v13
	v_lshlrev_b32_e32 v24, 16, v14
	v_and_b32_e32 v25, 0xffff0000, v14
	v_lshlrev_b32_e32 v14, 16, v15
	v_and_b32_e32 v15, 0xffff0000, v15
	v_lshl_add_u64 v[20:21], v[18:19], 2, s[76:77]
	v_add_u32_e32 v3, 0x700, v2
	v_ashrrev_i32_e32 v3, 4, v3
	v_lshl_add_u64 v[18:19], v[18:19], 1, s[12:13]
	s_waitcnt vmcnt(1)
	v_pk_add_f32 v[4:5], v[4:5], v[22:23]
	v_pk_add_f32 v[6:7], v[6:7], v[12:13]
	s_waitcnt vmcnt(0)
	v_pk_add_f32 v[8:9], v[8:9], v[24:25]
	v_pk_add_f32 v[10:11], v[10:11], v[14:15]
	v_cvt_pk_bf16_f32 v4, v4, v5
	v_cvt_pk_bf16_f32 v5, v6, v7
	v_cvt_pk_bf16_f32 v6, v8, v9
	v_cvt_pk_bf16_f32 v7, v10, v11
	global_store_dwordx4 v[16:17], v[4:7], off
	global_load_dwordx4 v[4:7], v[20:21], off
	v_mad_u64_u32 v[12:13], s[36:37], v26, s27, v[0:1]
	global_load_dwordx4 v[8:11], v[20:21], off offset:16
	ds_read_b128 v[12:15], v12
	v_add_u32_e32 v16, s33, v3
	v_ashrrev_i32_e32 v17, 31, v16
	v_lshlrev_b64 v[16:17], 10, v[16:17]
	v_or3_b32 v16, v16, s34, v1
	s_waitcnt lgkmcnt(0)
	v_lshlrev_b32_e32 v22, 16, v12
	v_and_b32_e32 v23, 0xffff0000, v12
	v_lshlrev_b32_e32 v12, 16, v13
	v_and_b32_e32 v13, 0xffff0000, v13
	v_lshlrev_b32_e32 v24, 16, v14
	v_and_b32_e32 v25, 0xffff0000, v14
	v_lshlrev_b32_e32 v14, 16, v15
	v_and_b32_e32 v15, 0xffff0000, v15
	v_lshl_add_u64 v[20:21], v[16:17], 2, s[76:77]
	v_lshl_add_u64 v[16:17], v[16:17], 1, s[12:13]
	s_waitcnt vmcnt(1)
	v_pk_add_f32 v[4:5], v[4:5], v[22:23]
	v_pk_add_f32 v[6:7], v[6:7], v[12:13]
	v_cvt_pk_bf16_f32 v4, v4, v5
	s_waitcnt vmcnt(0)
	v_pk_add_f32 v[8:9], v[8:9], v[24:25]
	v_pk_add_f32 v[10:11], v[10:11], v[14:15]
	v_cvt_pk_bf16_f32 v5, v6, v7
	v_cvt_pk_bf16_f32 v6, v8, v9
	v_cvt_pk_bf16_f32 v7, v10, v11
	global_store_dwordx4 v[18:19], v[4:7], off
	global_load_dwordx4 v[4:7], v[20:21], off
	v_add_u32_e32 v12, 0x800, v2
	global_load_dwordx4 v[8:11], v[20:21], off offset:16
	v_ashrrev_i32_e32 v26, 4, v12
	v_mad_u64_u32 v[12:13], s[36:37], v3, s27, v[0:1]
	ds_read_b128 v[12:15], v12
	v_add_u32_e32 v18, s33, v26
	v_ashrrev_i32_e32 v19, 31, v18
	v_lshlrev_b64 v[18:19], 10, v[18:19]
	v_or3_b32 v18, v18, s34, v1
	s_waitcnt lgkmcnt(0)
	v_lshlrev_b32_e32 v22, 16, v12
	v_and_b32_e32 v23, 0xffff0000, v12
	v_lshlrev_b32_e32 v12, 16, v13
	v_and_b32_e32 v13, 0xffff0000, v13
	v_lshlrev_b32_e32 v24, 16, v14
	v_and_b32_e32 v25, 0xffff0000, v14
	v_lshlrev_b32_e32 v14, 16, v15
	v_and_b32_e32 v15, 0xffff0000, v15
	v_lshl_add_u64 v[20:21], v[18:19], 2, s[76:77]
	v_add_u32_e32 v3, 0x900, v2
	v_ashrrev_i32_e32 v3, 4, v3
	v_lshl_add_u64 v[18:19], v[18:19], 1, s[12:13]
	s_waitcnt vmcnt(1)
	v_pk_add_f32 v[4:5], v[4:5], v[22:23]
	v_pk_add_f32 v[6:7], v[6:7], v[12:13]
	s_waitcnt vmcnt(0)
	v_pk_add_f32 v[8:9], v[8:9], v[24:25]
	v_pk_add_f32 v[10:11], v[10:11], v[14:15]
	v_cvt_pk_bf16_f32 v4, v4, v5
	v_cvt_pk_bf16_f32 v5, v6, v7
	v_cvt_pk_bf16_f32 v6, v8, v9
	v_cvt_pk_bf16_f32 v7, v10, v11
	global_store_dwordx4 v[16:17], v[4:7], off
	global_load_dwordx4 v[4:7], v[20:21], off
	v_mad_u64_u32 v[12:13], s[36:37], v26, s27, v[0:1]
	global_load_dwordx4 v[8:11], v[20:21], off offset:16
	ds_read_b128 v[12:15], v12
	v_add_u32_e32 v16, s33, v3
	v_ashrrev_i32_e32 v17, 31, v16
	v_lshlrev_b64 v[16:17], 10, v[16:17]
	v_or3_b32 v16, v16, s34, v1
	s_waitcnt lgkmcnt(0)
	v_lshlrev_b32_e32 v22, 16, v12
	v_and_b32_e32 v23, 0xffff0000, v12
	v_lshlrev_b32_e32 v12, 16, v13
	v_and_b32_e32 v13, 0xffff0000, v13
	v_lshlrev_b32_e32 v24, 16, v14
	v_and_b32_e32 v25, 0xffff0000, v14
	v_lshlrev_b32_e32 v14, 16, v15
	v_and_b32_e32 v15, 0xffff0000, v15
	v_lshl_add_u64 v[20:21], v[16:17], 2, s[76:77]
	v_lshl_add_u64 v[16:17], v[16:17], 1, s[12:13]
	s_waitcnt vmcnt(1)
	v_pk_add_f32 v[4:5], v[4:5], v[22:23]
	v_pk_add_f32 v[6:7], v[6:7], v[12:13]
	v_cvt_pk_bf16_f32 v4, v4, v5
	s_waitcnt vmcnt(0)
	v_pk_add_f32 v[8:9], v[8:9], v[24:25]
	v_pk_add_f32 v[10:11], v[10:11], v[14:15]
	v_cvt_pk_bf16_f32 v5, v6, v7
	v_cvt_pk_bf16_f32 v6, v8, v9
	v_cvt_pk_bf16_f32 v7, v10, v11
	global_store_dwordx4 v[18:19], v[4:7], off
	global_load_dwordx4 v[4:7], v[20:21], off
	v_add_u32_e32 v12, 0xa00, v2
	global_load_dwordx4 v[8:11], v[20:21], off offset:16
	v_ashrrev_i32_e32 v26, 4, v12
	v_mad_u64_u32 v[12:13], s[36:37], v3, s27, v[0:1]
	ds_read_b128 v[12:15], v12
	v_add_u32_e32 v18, s33, v26
	v_ashrrev_i32_e32 v19, 31, v18
	v_lshlrev_b64 v[18:19], 10, v[18:19]
	v_or3_b32 v18, v18, s34, v1
	s_waitcnt lgkmcnt(0)
	v_lshlrev_b32_e32 v22, 16, v12
	v_and_b32_e32 v23, 0xffff0000, v12
	v_lshlrev_b32_e32 v12, 16, v13
	v_and_b32_e32 v13, 0xffff0000, v13
	v_lshlrev_b32_e32 v24, 16, v14
	v_and_b32_e32 v25, 0xffff0000, v14
	v_lshlrev_b32_e32 v14, 16, v15
	v_and_b32_e32 v15, 0xffff0000, v15
	v_lshl_add_u64 v[20:21], v[18:19], 2, s[76:77]
	v_add_u32_e32 v3, 0xb00, v2
	v_ashrrev_i32_e32 v3, 4, v3
	v_lshl_add_u64 v[18:19], v[18:19], 1, s[12:13]
	s_waitcnt vmcnt(1)
	v_pk_add_f32 v[4:5], v[4:5], v[22:23]
	v_pk_add_f32 v[6:7], v[6:7], v[12:13]
	s_waitcnt vmcnt(0)
; DI int tidx() { int t = __builtin_amdgcn_workitem_id_x(); asm volatile("" : "+v"(t)); return t; }
; DI unsigned cvtpk(float lo, float hi) { const f32x2_ v = {lo, hi}; return __builtin_bit_cast(unsigned, __builtin_convertvector(v, bf16x2_)); }
; DI float bflo(unsigned w) { return __uint_as_float(w << 16); }
; DI float bfhi(unsigned w) { return __uint_as_float(w & 0xffff0000u); }
; DI void phase6(const Params& p, const Sched& sched, unsigned char* smem) {
;     ...
;       const int tid = tidx();
; #pragma unroll
;       for (int i = 0; i < 16; ++i) {
;         const int c = tid + 256 * i, row = c >> 4, ch = (c & 15) * 8;
;         const size_t gi = (size_t)(tm * 256 + row) * 1024 + tn * 128 + ch;
;         const u32x4 sv = *(const u32x4*)(Ls + row * EST + ch);
;         const f32x4 x0 = *(const f32x4*)(p.x + gi), x1 = *(const f32x4*)(p.x + gi + 4);
;         u32x4 w;
;         w.x = cvtpk(x0[0] + bflo(sv.x), x0[1] + bfhi(sv.x)); w.y = cvtpk(x0[2] + bflo(sv.y), x0[3] + bfhi(sv.y));
;         w.z = cvtpk(x1[0] + bflo(sv.z), x1[1] + bfhi(sv.z)); w.w = cvtpk(x1[2] + bflo(sv.w), x1[3] + bfhi(sv.w));
;         *(u32x4*)(x1b + gi) = w;
;       }
	v_pk_add_f32 v[8:9], v[8:9], v[24:25]
	v_pk_add_f32 v[10:11], v[10:11], v[14:15]
	v_cvt_pk_bf16_f32 v4, v4, v5
	v_cvt_pk_bf16_f32 v5, v6, v7
	v_cvt_pk_bf16_f32 v6, v8, v9
	v_cvt_pk_bf16_f32 v7, v10, v11
	global_store_dwordx4 v[16:17], v[4:7], off
	global_load_dwordx4 v[4:7], v[20:21], off
	v_mad_u64_u32 v[12:13], s[36:37], v26, s27, v[0:1]
	global_load_dwordx4 v[8:11], v[20:21], off offset:16
	ds_read_b128 v[12:15], v12
	v_add_u32_e32 v16, s33, v3
	v_ashrrev_i32_e32 v17, 31, v16
	v_lshlrev_b64 v[16:17], 10, v[16:17]
	v_or3_b32 v16, v16, s34, v1
	s_waitcnt lgkmcnt(0)
	v_lshlrev_b32_e32 v22, 16, v12
	v_and_b32_e32 v23, 0xffff0000, v12
	v_lshlrev_b32_e32 v12, 16, v13
	v_and_b32_e32 v13, 0xffff0000, v13
	v_lshlrev_b32_e32 v24, 16, v14
	v_and_b32_e32 v25, 0xffff0000, v14
	v_lshlrev_b32_e32 v14, 16, v15
	v_and_b32_e32 v15, 0xffff0000, v15
	v_lshl_add_u64 v[20:21], v[16:17], 2, s[76:77]
	v_lshl_add_u64 v[16:17], v[16:17], 1, s[12:13]
	s_waitcnt vmcnt(1)
	v_pk_add_f32 v[4:5], v[4:5], v[22:23]
	v_pk_add_f32 v[6:7], v[6:7], v[12:13]
	v_cvt_pk_bf16_f32 v4, v4, v5
	s_waitcnt vmcnt(0)
	v_pk_add_f32 v[8:9], v[8:9], v[24:25]
	v_pk_add_f32 v[10:11], v[10:11], v[14:15]
	v_cvt_pk_bf16_f32 v5, v6, v7
	v_cvt_pk_bf16_f32 v6, v8, v9
	v_cvt_pk_bf16_f32 v7, v10, v11
	global_store_dwordx4 v[18:19], v[4:7], off
	global_load_dwordx4 v[4:7], v[20:21], off
	v_add_u32_e32 v12, 0xc00, v2
	global_load_dwordx4 v[8:11], v[20:21], off offset:16
	v_ashrrev_i32_e32 v26, 4, v12
	v_mad_u64_u32 v[12:13], s[36:37], v3, s27, v[0:1]
	ds_read_b128 v[12:15], v12
	v_add_u32_e32 v18, s33, v26
	v_ashrrev_i32_e32 v19, 31, v18
	v_lshlrev_b64 v[18:19], 10, v[18:19]
	v_or3_b32 v18, v18, s34, v1
	s_waitcnt lgkmcnt(0)
	v_lshlrev_b32_e32 v22, 16, v12
	v_and_b32_e32 v23, 0xffff0000, v12
	v_lshlrev_b32_e32 v12, 16, v13
	v_and_b32_e32 v13, 0xffff0000, v13
	v_lshlrev_b32_e32 v24, 16, v14
	v_and_b32_e32 v25, 0xffff0000, v14
	v_lshlrev_b32_e32 v14, 16, v15
	v_and_b32_e32 v15, 0xffff0000, v15
	v_lshl_add_u64 v[20:21], v[18:19], 2, s[76:77]
	v_add_u32_e32 v3, 0xd00, v2
	v_ashrrev_i32_e32 v3, 4, v3
	v_lshl_add_u64 v[18:19], v[18:19], 1, s[12:13]
	s_waitcnt vmcnt(1)
	v_pk_add_f32 v[4:5], v[4:5], v[22:23]
	v_pk_add_f32 v[6:7], v[6:7], v[12:13]
	s_waitcnt vmcnt(0)
	v_pk_add_f32 v[8:9], v[8:9], v[24:25]
	v_pk_add_f32 v[10:11], v[10:11], v[14:15]
	v_cvt_pk_bf16_f32 v4, v4, v5
	v_cvt_pk_bf16_f32 v5, v6, v7
	v_cvt_pk_bf16_f32 v6, v8, v9
	v_cvt_pk_bf16_f32 v7, v10, v11
	global_store_dwordx4 v[16:17], v[4:7], off
	global_load_dwordx4 v[4:7], v[20:21], off
	v_mad_u64_u32 v[12:13], s[36:37], v26, s27, v[0:1]
	global_load_dwordx4 v[8:11], v[20:21], off offset:16
	ds_read_b128 v[12:15], v12
	v_add_u32_e32 v16, s33, v3
	v_ashrrev_i32_e32 v17, 31, v16
	v_lshlrev_b64 v[16:17], 10, v[16:17]
	v_or3_b32 v16, v16, s34, v1
	s_waitcnt lgkmcnt(0)
	v_lshlrev_b32_e32 v22, 16, v12
	v_and_b32_e32 v23, 0xffff0000, v12
	v_lshlrev_b32_e32 v12, 16, v13
	v_and_b32_e32 v13, 0xffff0000, v13
	v_lshlrev_b32_e32 v24, 16, v14
	v_and_b32_e32 v25, 0xffff0000, v14
	v_lshlrev_b32_e32 v14, 16, v15
	v_and_b32_e32 v15, 0xffff0000, v15
	v_lshl_add_u64 v[20:21], v[16:17], 2, s[76:77]
	v_lshl_add_u64 v[16:17], v[16:17], 1, s[12:13]
	s_waitcnt vmcnt(1)
	v_pk_add_f32 v[4:5], v[4:5], v[22:23]
	v_pk_add_f32 v[6:7], v[6:7], v[12:13]
	v_cvt_pk_bf16_f32 v4, v4, v5
	s_waitcnt vmcnt(0)
	v_pk_add_f32 v[8:9], v[8:9], v[24:25]
	v_pk_add_f32 v[10:11], v[10:11], v[14:15]
	v_cvt_pk_bf16_f32 v5, v6, v7
	v_cvt_pk_bf16_f32 v6, v8, v9
	v_cvt_pk_bf16_f32 v7, v10, v11
	global_store_dwordx4 v[18:19], v[4:7], off
	global_load_dwordx4 v[4:7], v[20:21], off
	v_add_u32_e32 v12, 0xe00, v2
	global_load_dwordx4 v[8:11], v[20:21], off offset:16
	v_ashrrev_i32_e32 v26, 4, v12
	v_mad_u64_u32 v[12:13], s[36:37], v3, s27, v[0:1]
	ds_read_b128 v[12:15], v12
	v_add_u32_e32 v18, s33, v26
	v_ashrrev_i32_e32 v19, 31, v18
	v_lshlrev_b64 v[18:19], 10, v[18:19]
	v_or3_b32 v18, v18, s34, v1
	s_waitcnt lgkmcnt(0)
	v_lshlrev_b32_e32 v22, 16, v12
	v_and_b32_e32 v23, 0xffff0000, v12
	v_lshlrev_b32_e32 v12, 16, v13
	v_and_b32_e32 v13, 0xffff0000, v13
	v_lshlrev_b32_e32 v24, 16, v14
	v_and_b32_e32 v25, 0xffff0000, v14
	v_lshlrev_b32_e32 v14, 16, v15
	v_and_b32_e32 v15, 0xffff0000, v15
	v_lshl_add_u64 v[20:21], v[18:19], 2, s[76:77]
	v_add_u32_e32 v2, 0xf00, v2
	v_lshl_add_u64 v[18:19], v[18:19], 1, s[12:13]
	s_waitcnt vmcnt(1)
	v_pk_add_f32 v[4:5], v[4:5], v[22:23]
	v_pk_add_f32 v[6:7], v[6:7], v[12:13]
	s_waitcnt vmcnt(0)
	v_pk_add_f32 v[8:9], v[8:9], v[24:25]
	v_pk_add_f32 v[10:11], v[10:11], v[14:15]
	v_cvt_pk_bf16_f32 v4, v4, v5
	v_cvt_pk_bf16_f32 v5, v6, v7
	v_cvt_pk_bf16_f32 v6, v8, v9
	v_cvt_pk_bf16_f32 v7, v10, v11
	global_store_dwordx4 v[16:17], v[4:7], off
	global_load_dwordx4 v[4:7], v[20:21], off
	v_mad_u64_u32 v[12:13], s[36:37], v26, s27, v[0:1]
	global_load_dwordx4 v[8:11], v[20:21], off offset:16
	ds_read_b128 v[12:15], v12
	v_ashrrev_i32_e32 v24, 4, v2
	v_add_u32_e32 v2, s33, v24
	v_ashrrev_i32_e32 v3, 31, v2
	v_lshlrev_b64 v[16:17], 10, v[2:3]
	s_waitcnt lgkmcnt(0)
	v_lshlrev_b32_e32 v2, 16, v12
	v_and_b32_e32 v3, 0xffff0000, v12
	v_lshlrev_b32_e32 v12, 16, v13
	v_and_b32_e32 v13, 0xffff0000, v13
	v_lshlrev_b32_e32 v22, 16, v14
	v_and_b32_e32 v23, 0xffff0000, v14
	v_lshlrev_b32_e32 v14, 16, v15
	v_and_b32_e32 v15, 0xffff0000, v15
	v_or3_b32 v16, v16, s34, v1
	v_lshl_add_u64 v[20:21], v[16:17], 2, s[76:77]
	v_mad_u64_u32 v[0:1], s[34:35], v24, s27, v[0:1]
	s_waitcnt vmcnt(1)
	v_pk_add_f32 v[2:3], v[4:5], v[2:3]
	v_pk_add_f32 v[4:5], v[6:7], v[12:13]
	v_cvt_pk_bf16_f32 v2, v2, v3
	s_waitcnt vmcnt(0)
	v_pk_add_f32 v[6:7], v[8:9], v[22:23]
	v_pk_add_f32 v[8:9], v[10:11], v[14:15]
	v_cvt_pk_bf16_f32 v3, v4, v5
	v_cvt_pk_bf16_f32 v4, v6, v7
	v_cvt_pk_bf16_f32 v5, v8, v9
	global_store_dwordx4 v[18:19], v[2:5], off
	global_load_dwordx4 v[2:5], v[20:21], off
	ds_read_b128 v[10:13], v0
	global_load_dwordx4 v[6:9], v[20:21], off offset:16
	v_lshl_add_u64 v[14:15], v[16:17], 1, s[12:13]
	s_waitcnt lgkmcnt(0)
	v_lshlrev_b32_e32 v0, 16, v10
	v_and_b32_e32 v1, 0xffff0000, v10
	v_lshlrev_b32_e32 v10, 16, v11
	v_and_b32_e32 v11, 0xffff0000, v11
	v_lshlrev_b32_e32 v16, 16, v12
	v_and_b32_e32 v17, 0xffff0000, v12
	v_lshlrev_b32_e32 v12, 16, v13
	v_and_b32_e32 v13, 0xffff0000, v13
	s_waitcnt vmcnt(1)
	v_pk_add_f32 v[0:1], v[2:3], v[0:1]
	v_pk_add_f32 v[2:3], v[4:5], v[10:11]
	s_waitcnt vmcnt(0)
	v_pk_add_f32 v[4:5], v[6:7], v[16:17]
	v_pk_add_f32 v[6:7], v[8:9], v[12:13]
	v_cvt_pk_bf16_f32 v0, v0, v1
	v_cvt_pk_bf16_f32 v1, v2, v3
	v_cvt_pk_bf16_f32 v2, v4, v5
	v_cvt_pk_bf16_f32 v3, v6, v7
	global_store_dwordx4 v[14:15], v[0:3], off
	s_cbranch_scc0 .LBB0_811
	s_branch .LBB0_808

; DI f32x4 mfma16(bf16x8 a, bf16x8 b, f32x4 c) { return __builtin_amdgcn_mfma_f32_16x16x32_bf16(a, b, c, 0, 0, 0); }
; template <int NI, class XL, class EP>
; DI void gemm_tile(const u16* __restrict__ W, int ldw, int f0, int t0, int K, XL xl, EP ep, unsigned char* smem) {
;     ...
;   auto gload = [&](int it) {
;     const int k = it * 32;
;     const char* wb = (const char*)(W + (size_t)(k >> 5) * ldw * 32);
;     const char* xb = (const char*)xl.kbase(k);
; #pragma unroll
;     for (int i = 0; i < 2; ++i) wr[i] = *(const u32x4*)(wb + wbyte + i * 64);
; #pragma unroll
;     for (int i = 0; i < XR; ++i) xr[i] = *(const u32x4*)(xb + xbyte + i * xrs);
;   };
;   auto lstore = [&](int buf) {
;     u16* Ws = S0 + buf * BUF; u16* Xs = Ws + 128 * LST;
; #pragma unroll
;     for (int i = 0; i < 2; ++i) *(u32x4*)(Ws + (srow * 2 + i) * LST + sch) = wr[i];
; #pragma unroll
;     for (int i = 0; i < XR; ++i) *(u32x4*)(Xs + (srow * XR + i) * LST + sch) = xr[i];
;   };
;   gload(0);
;   __syncthreads();
;   lstore(0);
;   __syncthreads();
;   if (nk > 1) gload(1);
;   for (int it = 0; it < nk; ++it) {
;     const u16* Ws = S0 + (it & 1) * BUF; const u16* Xs = Ws + 128 * LST;
;     __builtin_amdgcn_s_setprio(1);
;     bf16x8 a[4];
; #pragma unroll
;     for (int mi = 0; mi < 4; ++mi) a[mi] = *(const bf16x8*)(Ws + (wf * 64 + mi * 16 + lr) * LST + lq * 8);
; #pragma unroll
;     for (int ni = 0; ni < NI; ++ni) {
;       const bf16x8 b = *(const bf16x8*)(Xs + (wt * (NI * 16) + ni * 16 + lr) * LST + lq * 8);
; #pragma unroll
;       for (int mi = 0; mi < 4; ++mi) acc[mi][ni] = mfma16(a[mi], b, acc[mi][ni]);
;     }
;     __builtin_amdgcn_sched_group_barrier(0x100, 6, 0);
; #pragma unroll
;     for (int ni = 0; ni < NI; ++ni) { __builtin_amdgcn_sched_group_barrier(0x008, 4, 0); if (ni + 2 < NI) __builtin_amdgcn_sched_group_barrier(0x100, 1, 0); }
;     __builtin_amdgcn_s_setprio(0);
;     if (it + 1 < nk) lstore((it + 1) & 1);
;     if (it + 2 < nk) gload(it + 2);
;     __syncthreads();
.LBB0_945:
	s_setprio 1
	ds_read_b128 v[176:179], v228 offset:0
	ds_read_b128 v[180:183], v228 offset:1536
	ds_read_b128 v[188:191], v228 offset:3072
	ds_read_b128 v[192:195], v228 offset:4608
	ds_read_b128 v[184:187], v152 offset:12288
	ds_read_b128 v[196:199], v152 offset:13824
	s_waitcnt lgkmcnt(1)
	v_mfma_f32_16x16x32_bf16 v[148:151], v[176:179], v[184:187], v[148:151]
	v_mfma_f32_16x16x32_bf16 v[136:139], v[180:183], v[184:187], v[136:139]
	v_mfma_f32_16x16x32_bf16 v[112:115], v[188:191], v[184:187], v[112:115]
	v_mfma_f32_16x16x32_bf16 v[80:83], v[192:195], v[184:187], v[80:83]
	ds_read_b128 v[184:187], v152 offset:15360
	s_waitcnt vmcnt(6)
	ds_write_b128 v229, v[20:23] offset:36864
	s_waitcnt lgkmcnt(2)
	v_mfma_f32_16x16x32_bf16 v[144:147], v[176:179], v[196:199], v[144:147]
	v_mfma_f32_16x16x32_bf16 v[128:131], v[180:183], v[196:199], v[128:131]
	v_mfma_f32_16x16x32_bf16 v[100:103], v[188:191], v[196:199], v[100:103]
	v_mfma_f32_16x16x32_bf16 v[52:55], v[192:195], v[196:199], v[52:55]
	ds_read_b128 v[196:199], v152 offset:16896
	ds_write_b128 v229, v[16:19] offset:36960
	global_load_dwordx4 v[20:23], v156, s[98:99]
	global_load_dwordx4 v[16:19], v156, s[98:99] offset:64
	s_waitcnt lgkmcnt(3)
	v_mfma_f32_16x16x32_bf16 v[140:143], v[176:179], v[184:187], v[140:143]
	v_mfma_f32_16x16x32_bf16 v[120:123], v[180:183], v[184:187], v[120:123]
	v_mfma_f32_16x16x32_bf16 v[88:91], v[188:191], v[184:187], v[88:91]
	v_mfma_f32_16x16x32_bf16 v[44:47], v[192:195], v[184:187], v[44:47]
	ds_read_b128 v[184:187], v152 offset:18432
	ds_write_b128 v230, v[36:39] offset:49152
	global_load_dwordx4 v[36:39], v158, s[100:101] offset:2048
	s_waitcnt lgkmcnt(3)
	v_mfma_f32_16x16x32_bf16 v[132:135], v[176:179], v[196:199], v[132:135]
	v_mfma_f32_16x16x32_bf16 v[108:111], v[180:183], v[196:199], v[108:111]
	v_mfma_f32_16x16x32_bf16 v[76:79], v[188:191], v[196:199], v[76:79]
	v_mfma_f32_16x16x32_bf16 v[40:43], v[192:195], v[196:199], v[40:43]
	ds_read_b128 v[196:199], v152 offset:19968
	ds_write_b128 v230, v[32:35] offset:49248
	global_load_dwordx4 v[32:35], v158, s[100:101] offset:2112
	s_waitcnt lgkmcnt(3)
	v_mfma_f32_16x16x32_bf16 v[124:127], v[176:179], v[184:187], v[124:127]
	v_mfma_f32_16x16x32_bf16 v[96:99], v[180:183], v[184:187], v[96:99]
	v_mfma_f32_16x16x32_bf16 v[68:71], v[188:191], v[184:187], v[68:71]
	v_mfma_f32_16x16x32_bf16 v[12:15], v[192:195], v[184:187], v[12:15]
	ds_read_b128 v[184:187], v152 offset:21504
	ds_write_b128 v230, v[28:31] offset:49344
	global_load_dwordx4 v[28:31], v158, s[100:101] offset:2176
	s_waitcnt lgkmcnt(3)
	v_mfma_f32_16x16x32_bf16 v[116:119], v[176:179], v[196:199], v[116:119]
	v_mfma_f32_16x16x32_bf16 v[84:87], v[180:183], v[196:199], v[84:87]
	v_mfma_f32_16x16x32_bf16 v[60:63], v[188:191], v[196:199], v[60:63]
	v_mfma_f32_16x16x32_bf16 v[8:11], v[192:195], v[196:199], v[8:11]
	ds_read_b128 v[196:199], v152 offset:23040
	ds_write_b128 v230, v[24:27] offset:49440
	global_load_dwordx4 v[24:27], v158, s[100:101] offset:2240
	s_waitcnt lgkmcnt(3)
	v_mfma_f32_16x16x32_bf16 v[104:107], v[176:179], v[184:187], v[104:107]
	v_mfma_f32_16x16x32_bf16 v[72:75], v[180:183], v[184:187], v[72:75]
	v_mfma_f32_16x16x32_bf16 v[56:59], v[188:191], v[184:187], v[56:59]
	v_mfma_f32_16x16x32_bf16 v[4:7], v[192:195], v[184:187], v[4:7]
	s_add_u32 s98, s98, s28
	s_addc_u32 s99, s99, s29
	s_add_u32 s100, s100, s26
	s_addc_u32 s101, s101, s27
	s_waitcnt lgkmcnt(1)
	v_mfma_f32_16x16x32_bf16 v[92:95], v[176:179], v[196:199], v[92:95]
	v_mfma_f32_16x16x32_bf16 v[64:67], v[180:183], v[196:199], v[64:67]
	v_mfma_f32_16x16x32_bf16 v[48:51], v[188:191], v[196:199], v[48:51]
	v_mfma_f32_16x16x32_bf16 v[0:3], v[192:195], v[196:199], v[0:3]
	s_setprio 0
	s_waitcnt lgkmcnt(0)
	s_barrier
	s_setprio 1
	ds_read_b128 v[176:179], v228 offset:36864
	ds_read_b128 v[180:183], v228 offset:38400
	ds_read_b128 v[188:191], v228 offset:39936
	ds_read_b128 v[192:195], v228 offset:41472
	ds_read_b128 v[184:187], v152 offset:49152
	ds_read_b128 v[196:199], v152 offset:50688
	s_waitcnt lgkmcnt(1)
	v_mfma_f32_16x16x32_bf16 v[148:151], v[176:179], v[184:187], v[148:151]
	v_mfma_f32_16x16x32_bf16 v[136:139], v[180:183], v[184:187], v[136:139]
	v_mfma_f32_16x16x32_bf16 v[112:115], v[188:191], v[184:187], v[112:115]
	v_mfma_f32_16x16x32_bf16 v[80:83], v[192:195], v[184:187], v[80:83]
	ds_read_b128 v[184:187], v152 offset:52224
	s_waitcnt vmcnt(6)
	ds_write_b128 v229, v[200:203] offset:0
	s_waitcnt lgkmcnt(2)
	v_mfma_f32_16x16x32_bf16 v[144:147], v[176:179], v[196:199], v[144:147]
	v_mfma_f32_16x16x32_bf16 v[128:131], v[180:183], v[196:199], v[128:131]
	v_mfma_f32_16x16x32_bf16 v[100:103], v[188:191], v[196:199], v[100:103]
	v_mfma_f32_16x16x32_bf16 v[52:55], v[192:195], v[196:199], v[52:55]
	ds_read_b128 v[196:199], v152 offset:53760
	ds_write_b128 v229, v[204:207] offset:96
	global_load_dwordx4 v[200:203], v156, s[98:99]
	global_load_dwordx4 v[204:207], v156, s[98:99] offset:64
	s_waitcnt lgkmcnt(3)
	v_mfma_f32_16x16x32_bf16 v[140:143], v[176:179], v[184:187], v[140:143]
	v_mfma_f32_16x16x32_bf16 v[120:123], v[180:183], v[184:187], v[120:123]
	v_mfma_f32_16x16x32_bf16 v[88:91], v[188:191], v[184:187], v[88:91]
	v_mfma_f32_16x16x32_bf16 v[44:47], v[192:195], v[184:187], v[44:47]
	ds_read_b128 v[184:187], v152 offset:55296
	ds_write_b128 v230, v[208:211] offset:12288
	global_load_dwordx4 v[208:211], v158, s[100:101] offset:2048
	s_waitcnt lgkmcnt(3)
; DI f32x4 mfma16(bf16x8 a, bf16x8 b, f32x4 c) { return __builtin_amdgcn_mfma_f32_16x16x32_bf16(a, b, c, 0, 0, 0); }
; template <int NI, class XL, class EP>
; DI void gemm_tile(const u16* __restrict__ W, int ldw, int f0, int t0, int K, XL xl, EP ep, unsigned char* smem) {
;     ...
;   auto gload = [&](int it) {
;     const int k = it * 32;
;     const char* wb = (const char*)(W + (size_t)(k >> 5) * ldw * 32);
;     const char* xb = (const char*)xl.kbase(k);
; #pragma unroll
;     for (int i = 0; i < 2; ++i) wr[i] = *(const u32x4*)(wb + wbyte + i * 64);
; #pragma unroll
;     for (int i = 0; i < XR; ++i) xr[i] = *(const u32x4*)(xb + xbyte + i * xrs);
;   };
;   auto lstore = [&](int buf) {
;     u16* Ws = S0 + buf * BUF; u16* Xs = Ws + 128 * LST;
; #pragma unroll
;     for (int i = 0; i < 2; ++i) *(u32x4*)(Ws + (srow * 2 + i) * LST + sch) = wr[i];
; #pragma unroll
;     for (int i = 0; i < XR; ++i) *(u32x4*)(Xs + (srow * XR + i) * LST + sch) = xr[i];
;   };
;   gload(0);
;   __syncthreads();
;   lstore(0);
;   __syncthreads();
;   if (nk > 1) gload(1);
;   for (int it = 0; it < nk; ++it) {
;     const u16* Ws = S0 + (it & 1) * BUF; const u16* Xs = Ws + 128 * LST;
;     __builtin_amdgcn_s_setprio(1);
;     bf16x8 a[4];
; #pragma unroll
;     for (int mi = 0; mi < 4; ++mi) a[mi] = *(const bf16x8*)(Ws + (wf * 64 + mi * 16 + lr) * LST + lq * 8);
; #pragma unroll
;     for (int ni = 0; ni < NI; ++ni) {
;       const bf16x8 b = *(const bf16x8*)(Xs + (wt * (NI * 16) + ni * 16 + lr) * LST + lq * 8);
; #pragma unroll
;       for (int mi = 0; mi < 4; ++mi) acc[mi][ni] = mfma16(a[mi], b, acc[mi][ni]);
;     }
;     __builtin_amdgcn_sched_group_barrier(0x100, 6, 0);
; #pragma unroll
;     for (int ni = 0; ni < NI; ++ni) { __builtin_amdgcn_sched_group_barrier(0x008, 4, 0); if (ni + 2 < NI) __builtin_amdgcn_sched_group_barrier(0x100, 1, 0); }
;     __builtin_amdgcn_s_setprio(0);
;     if (it + 1 < nk) lstore((it + 1) & 1);
;     if (it + 2 < nk) gload(it + 2);
;     __syncthreads();
	v_mfma_f32_16x16x32_bf16 v[132:135], v[176:179], v[196:199], v[132:135]
	v_mfma_f32_16x16x32_bf16 v[108:111], v[180:183], v[196:199], v[108:111]
	v_mfma_f32_16x16x32_bf16 v[76:79], v[188:191], v[196:199], v[76:79]
	v_mfma_f32_16x16x32_bf16 v[40:43], v[192:195], v[196:199], v[40:43]
	ds_read_b128 v[196:199], v152 offset:56832
	ds_write_b128 v230, v[212:215] offset:12384
	global_load_dwordx4 v[212:215], v158, s[100:101] offset:2112
	s_waitcnt lgkmcnt(3)
	v_mfma_f32_16x16x32_bf16 v[124:127], v[176:179], v[184:187], v[124:127]
	v_mfma_f32_16x16x32_bf16 v[96:99], v[180:183], v[184:187], v[96:99]
	v_mfma_f32_16x16x32_bf16 v[68:71], v[188:191], v[184:187], v[68:71]
	v_mfma_f32_16x16x32_bf16 v[12:15], v[192:195], v[184:187], v[12:15]
	ds_read_b128 v[184:187], v152 offset:58368
	ds_write_b128 v230, v[220:223] offset:12480
	global_load_dwordx4 v[220:223], v158, s[100:101] offset:2176
	s_waitcnt lgkmcnt(3)
	v_mfma_f32_16x16x32_bf16 v[116:119], v[176:179], v[196:199], v[116:119]
	v_mfma_f32_16x16x32_bf16 v[84:87], v[180:183], v[196:199], v[84:87]
	v_mfma_f32_16x16x32_bf16 v[60:63], v[188:191], v[196:199], v[60:63]
	v_mfma_f32_16x16x32_bf16 v[8:11], v[192:195], v[196:199], v[8:11]
	ds_read_b128 v[196:199], v152 offset:59904
	ds_write_b128 v230, v[224:227] offset:12576
	global_load_dwordx4 v[224:227], v158, s[100:101] offset:2240
	s_waitcnt lgkmcnt(3)
	v_mfma_f32_16x16x32_bf16 v[104:107], v[176:179], v[184:187], v[104:107]
	v_mfma_f32_16x16x32_bf16 v[72:75], v[180:183], v[184:187], v[72:75]
	v_mfma_f32_16x16x32_bf16 v[56:59], v[188:191], v[184:187], v[56:59]
	v_mfma_f32_16x16x32_bf16 v[4:7], v[192:195], v[184:187], v[4:7]
	s_add_u32 s98, s98, s28
	s_addc_u32 s99, s99, s29
	s_add_u32 s100, s100, s26
	s_addc_u32 s101, s101, s27
	s_add_i32 s4, s4, 2
	s_waitcnt lgkmcnt(1)
	v_mfma_f32_16x16x32_bf16 v[92:95], v[176:179], v[196:199], v[92:95]
	v_mfma_f32_16x16x32_bf16 v[64:67], v[180:183], v[196:199], v[64:67]
	v_mfma_f32_16x16x32_bf16 v[48:51], v[188:191], v[196:199], v[48:51]
	v_mfma_f32_16x16x32_bf16 v[0:3], v[192:195], v[196:199], v[0:3]
	s_setprio 0
	s_cmp_eq_u32 s4, 29
	s_waitcnt lgkmcnt(0)
	s_barrier
	s_cbranch_scc0 .LBB0_945
	s_setprio 1
	ds_read_b128 v[176:179], v228 offset:0
	ds_read_b128 v[180:183], v228 offset:1536
	ds_read_b128 v[188:191], v228 offset:3072
	ds_read_b128 v[192:195], v228 offset:4608
	ds_read_b128 v[184:187], v152 offset:12288
	ds_read_b128 v[196:199], v152 offset:13824
	s_waitcnt lgkmcnt(1)
	v_mfma_f32_16x16x32_bf16 v[148:151], v[176:179], v[184:187], v[148:151]
	v_mfma_f32_16x16x32_bf16 v[136:139], v[180:183], v[184:187], v[136:139]
	v_mfma_f32_16x16x32_bf16 v[112:115], v[188:191], v[184:187], v[112:115]
	v_mfma_f32_16x16x32_bf16 v[80:83], v[192:195], v[184:187], v[80:83]
	ds_read_b128 v[184:187], v152 offset:15360
	s_waitcnt vmcnt(6)
	ds_write_b128 v229, v[20:23] offset:36864
	s_waitcnt lgkmcnt(2)
	v_mfma_f32_16x16x32_bf16 v[144:147], v[176:179], v[196:199], v[144:147]
	v_mfma_f32_16x16x32_bf16 v[128:131], v[180:183], v[196:199], v[128:131]
	v_mfma_f32_16x16x32_bf16 v[100:103], v[188:191], v[196:199], v[100:103]
	v_mfma_f32_16x16x32_bf16 v[52:55], v[192:195], v[196:199], v[52:55]
	ds_read_b128 v[196:199], v152 offset:16896
	ds_write_b128 v229, v[16:19] offset:36960
	global_load_dwordx4 v[20:23], v156, s[98:99]
	global_load_dwordx4 v[16:19], v156, s[98:99] offset:64
	s_waitcnt lgkmcnt(3)
	v_mfma_f32_16x16x32_bf16 v[140:143], v[176:179], v[184:187], v[140:143]
	v_mfma_f32_16x16x32_bf16 v[120:123], v[180:183], v[184:187], v[120:123]
	v_mfma_f32_16x16x32_bf16 v[88:91], v[188:191], v[184:187], v[88:91]
	v_mfma_f32_16x16x32_bf16 v[44:47], v[192:195], v[184:187], v[44:47]
	ds_read_b128 v[184:187], v152 offset:18432
	ds_write_b128 v230, v[36:39] offset:49152
	global_load_dwordx4 v[36:39], v158, s[100:101] offset:2048
	s_waitcnt lgkmcnt(3)
	v_mfma_f32_16x16x32_bf16 v[132:135], v[176:179], v[196:199], v[132:135]
	v_mfma_f32_16x16x32_bf16 v[108:111], v[180:183], v[196:199], v[108:111]
	v_mfma_f32_16x16x32_bf16 v[76:79], v[188:191], v[196:199], v[76:79]
	v_mfma_f32_16x16x32_bf16 v[40:43], v[192:195], v[196:199], v[40:43]
	ds_read_b128 v[196:199], v152 offset:19968
	ds_write_b128 v230, v[32:35] offset:49248
	global_load_dwordx4 v[32:35], v158, s[100:101] offset:2112
	s_waitcnt lgkmcnt(3)
	v_mfma_f32_16x16x32_bf16 v[124:127], v[176:179], v[184:187], v[124:127]
	v_mfma_f32_16x16x32_bf16 v[96:99], v[180:183], v[184:187], v[96:99]
	v_mfma_f32_16x16x32_bf16 v[68:71], v[188:191], v[184:187], v[68:71]
	v_mfma_f32_16x16x32_bf16 v[12:15], v[192:195], v[184:187], v[12:15]
	ds_read_b128 v[184:187], v152 offset:21504
	ds_write_b128 v230, v[28:31] offset:49344
	global_load_dwordx4 v[28:31], v158, s[100:101] offset:2176
	s_waitcnt lgkmcnt(3)
	v_mfma_f32_16x16x32_bf16 v[116:119], v[176:179], v[196:199], v[116:119]
	v_mfma_f32_16x16x32_bf16 v[84:87], v[180:183], v[196:199], v[84:87]
	v_mfma_f32_16x16x32_bf16 v[60:63], v[188:191], v[196:199], v[60:63]
	v_mfma_f32_16x16x32_bf16 v[8:11], v[192:195], v[196:199], v[8:11]
	ds_read_b128 v[196:199], v152 offset:23040
	ds_write_b128 v230, v[24:27] offset:49440
	global_load_dwordx4 v[24:27], v158, s[100:101] offset:2240
	s_waitcnt lgkmcnt(3)
	v_mfma_f32_16x16x32_bf16 v[104:107], v[176:179], v[184:187], v[104:107]
	v_mfma_f32_16x16x32_bf16 v[72:75], v[180:183], v[184:187], v[72:75]
	v_mfma_f32_16x16x32_bf16 v[56:59], v[188:191], v[184:187], v[56:59]
	v_mfma_f32_16x16x32_bf16 v[4:7], v[192:195], v[184:187], v[4:7]
	s_add_u32 s98, s98, s28
	s_addc_u32 s99, s99, s29
	s_add_u32 s100, s100, s26
	s_addc_u32 s101, s101, s27
	s_waitcnt lgkmcnt(1)
	v_mfma_f32_16x16x32_bf16 v[92:95], v[176:179], v[196:199], v[92:95]
	v_mfma_f32_16x16x32_bf16 v[64:67], v[180:183], v[196:199], v[64:67]
	v_mfma_f32_16x16x32_bf16 v[48:51], v[188:191], v[196:199], v[48:51]
	v_mfma_f32_16x16x32_bf16 v[0:3], v[192:195], v[196:199], v[0:3]
	s_setprio 0
	s_waitcnt lgkmcnt(0)
	s_barrier
; DI f32x4 mfma16(bf16x8 a, bf16x8 b, f32x4 c) { return __builtin_amdgcn_mfma_f32_16x16x32_bf16(a, b, c, 0, 0, 0); }
; template <int NI, class XL, class EP>
; DI void gemm_tile(const u16* __restrict__ W, int ldw, int f0, int t0, int K, XL xl, EP ep, unsigned char* smem) {
;     ...
;   for (int it = 0; it < nk; ++it) {
;     const u16* Ws = S0 + (it & 1) * BUF; const u16* Xs = Ws + 128 * LST;
;     __builtin_amdgcn_s_setprio(1);
;     bf16x8 a[4];
; #pragma unroll
;     for (int mi = 0; mi < 4; ++mi) a[mi] = *(const bf16x8*)(Ws + (wf * 64 + mi * 16 + lr) * LST + lq * 8);
; #pragma unroll
;     for (int ni = 0; ni < NI; ++ni) {
;       const bf16x8 b = *(const bf16x8*)(Xs + (wt * (NI * 16) + ni * 16 + lr) * LST + lq * 8);
; #pragma unroll
;       for (int mi = 0; mi < 4; ++mi) acc[mi][ni] = mfma16(a[mi], b, acc[mi][ni]);
;     }
;     __builtin_amdgcn_sched_group_barrier(0x100, 6, 0);
; #pragma unroll
;     for (int ni = 0; ni < NI; ++ni) { __builtin_amdgcn_sched_group_barrier(0x008, 4, 0); if (ni + 2 < NI) __builtin_amdgcn_sched_group_barrier(0x100, 1, 0); }
;     __builtin_amdgcn_s_setprio(0);
;     if (it + 1 < nk) lstore((it + 1) & 1);
;     if (it + 2 < nk) gload(it + 2);
;     __syncthreads();
	s_setprio 1
	ds_read_b128 v[176:179], v228 offset:36864
	ds_read_b128 v[180:183], v228 offset:38400
	ds_read_b128 v[188:191], v228 offset:39936
	ds_read_b128 v[192:195], v228 offset:41472
	ds_read_b128 v[184:187], v152 offset:49152
	ds_read_b128 v[196:199], v152 offset:50688
	s_waitcnt lgkmcnt(1)
	v_mfma_f32_16x16x32_bf16 v[148:151], v[176:179], v[184:187], v[148:151]
	v_mfma_f32_16x16x32_bf16 v[136:139], v[180:183], v[184:187], v[136:139]
	v_mfma_f32_16x16x32_bf16 v[112:115], v[188:191], v[184:187], v[112:115]
	v_mfma_f32_16x16x32_bf16 v[80:83], v[192:195], v[184:187], v[80:83]
	ds_read_b128 v[184:187], v152 offset:52224
	s_waitcnt vmcnt(6)
	ds_write_b128 v229, v[200:203] offset:0
	s_waitcnt lgkmcnt(2)
	v_mfma_f32_16x16x32_bf16 v[144:147], v[176:179], v[196:199], v[144:147]
	v_mfma_f32_16x16x32_bf16 v[128:131], v[180:183], v[196:199], v[128:131]
	v_mfma_f32_16x16x32_bf16 v[100:103], v[188:191], v[196:199], v[100:103]
	v_mfma_f32_16x16x32_bf16 v[52:55], v[192:195], v[196:199], v[52:55]
	ds_read_b128 v[196:199], v152 offset:53760
	ds_write_b128 v229, v[204:207] offset:96
	s_waitcnt lgkmcnt(3)
	v_mfma_f32_16x16x32_bf16 v[140:143], v[176:179], v[184:187], v[140:143]
	v_mfma_f32_16x16x32_bf16 v[120:123], v[180:183], v[184:187], v[120:123]
	v_mfma_f32_16x16x32_bf16 v[88:91], v[188:191], v[184:187], v[88:91]
	v_mfma_f32_16x16x32_bf16 v[44:47], v[192:195], v[184:187], v[44:47]
	ds_read_b128 v[184:187], v152 offset:55296
	ds_write_b128 v230, v[208:211] offset:12288
	s_waitcnt lgkmcnt(3)
	v_mfma_f32_16x16x32_bf16 v[132:135], v[176:179], v[196:199], v[132:135]
	v_mfma_f32_16x16x32_bf16 v[108:111], v[180:183], v[196:199], v[108:111]
	v_mfma_f32_16x16x32_bf16 v[76:79], v[188:191], v[196:199], v[76:79]
	v_mfma_f32_16x16x32_bf16 v[40:43], v[192:195], v[196:199], v[40:43]
	ds_read_b128 v[196:199], v152 offset:56832
	ds_write_b128 v230, v[212:215] offset:12384
	s_waitcnt lgkmcnt(3)
	v_mfma_f32_16x16x32_bf16 v[124:127], v[176:179], v[184:187], v[124:127]
	v_mfma_f32_16x16x32_bf16 v[96:99], v[180:183], v[184:187], v[96:99]
	v_mfma_f32_16x16x32_bf16 v[68:71], v[188:191], v[184:187], v[68:71]
	v_mfma_f32_16x16x32_bf16 v[12:15], v[192:195], v[184:187], v[12:15]
	ds_read_b128 v[184:187], v152 offset:58368
	ds_write_b128 v230, v[220:223] offset:12480
	s_waitcnt lgkmcnt(3)
	v_mfma_f32_16x16x32_bf16 v[116:119], v[176:179], v[196:199], v[116:119]
	v_mfma_f32_16x16x32_bf16 v[84:87], v[180:183], v[196:199], v[84:87]
	v_mfma_f32_16x16x32_bf16 v[60:63], v[188:191], v[196:199], v[60:63]
	v_mfma_f32_16x16x32_bf16 v[8:11], v[192:195], v[196:199], v[8:11]
	ds_read_b128 v[196:199], v152 offset:59904
	ds_write_b128 v230, v[224:227] offset:12576
	s_waitcnt lgkmcnt(3)
	v_mfma_f32_16x16x32_bf16 v[104:107], v[176:179], v[184:187], v[104:107]
	v_mfma_f32_16x16x32_bf16 v[72:75], v[180:183], v[184:187], v[72:75]
	v_mfma_f32_16x16x32_bf16 v[56:59], v[188:191], v[184:187], v[56:59]
	v_mfma_f32_16x16x32_bf16 v[4:7], v[192:195], v[184:187], v[4:7]
	s_add_i32 s4, s4, 2
	s_waitcnt lgkmcnt(1)
	v_mfma_f32_16x16x32_bf16 v[92:95], v[176:179], v[196:199], v[92:95]
	v_mfma_f32_16x16x32_bf16 v[64:67], v[180:183], v[196:199], v[64:67]
	v_mfma_f32_16x16x32_bf16 v[48:51], v[188:191], v[196:199], v[48:51]
	v_mfma_f32_16x16x32_bf16 v[0:3], v[192:195], v[196:199], v[0:3]
	s_setprio 0
	s_waitcnt lgkmcnt(0)
	s_barrier
	s_setprio 1
	v_lshl_add_u32 v152, v175, 1, v172
	ds_read_b128 v[156:159], v152
	v_lshl_add_u32 v171, v173, 1, v172
	ds_read_b128 v[172:175], v152 offset:1536
	ds_read_b128 v[180:183], v152 offset:3072
	ds_read_b128 v[184:187], v152 offset:4608
	ds_read_b128 v[176:179], v171 offset:12288
	ds_read_b128 v[188:191], v171 offset:13824
	s_waitcnt lgkmcnt(1)
	v_mfma_f32_16x16x32_bf16 v[148:151], v[156:159], v[176:179], v[148:151]
	v_mfma_f32_16x16x32_bf16 v[136:139], v[172:175], v[176:179], v[136:139]
	v_mfma_f32_16x16x32_bf16 v[112:115], v[180:183], v[176:179], v[112:115]
	v_mfma_f32_16x16x32_bf16 v[80:83], v[184:187], v[176:179], v[80:83]
	ds_read_b128 v[176:179], v171 offset:15360
	s_waitcnt vmcnt(5)
	ds_write_b128 v170, v[20:23] offset:36864
	s_waitcnt lgkmcnt(2)
	v_mfma_f32_16x16x32_bf16 v[144:147], v[156:159], v[188:191], v[144:147]
	v_mfma_f32_16x16x32_bf16 v[128:131], v[172:175], v[188:191], v[128:131]
	v_mfma_f32_16x16x32_bf16 v[100:103], v[180:183], v[188:191], v[100:103]
	v_mfma_f32_16x16x32_bf16 v[188:191], v[184:187], v[188:191], v[52:55]
	s_nop 2
	ds_read_b128 v[52:55], v171 offset:16896
	s_waitcnt vmcnt(4)
	ds_write_b128 v170, v[16:19] offset:36960
	s_waitcnt lgkmcnt(3)
	v_mfma_f32_16x16x32_bf16 v[192:195], v[156:159], v[176:179], v[140:143]
	v_mfma_f32_16x16x32_bf16 v[120:123], v[172:175], v[176:179], v[120:123]
	v_mfma_f32_16x16x32_bf16 v[88:91], v[180:183], v[176:179], v[88:91]
	v_mfma_f32_16x16x32_bf16 v[176:179], v[184:187], v[176:179], v[44:47]
	s_nop 2
	ds_read_b128 v[44:47], v171 offset:18432
	s_waitcnt vmcnt(3)
	ds_write_b128 v169, v[36:39] offset:49152
	s_waitcnt lgkmcnt(3)
	v_mfma_f32_16x16x32_bf16 v[196:199], v[156:159], v[52:55], v[132:135]
	v_mfma_f32_16x16x32_bf16 v[108:111], v[172:175], v[52:55], v[108:111]
	v_mfma_f32_16x16x32_bf16 v[76:79], v[180:183], v[52:55], v[76:79]
	v_mfma_f32_16x16x32_bf16 v[200:203], v[184:187], v[52:55], v[40:43]
	s_nop 2
	ds_read_b128 v[40:43], v171 offset:19968
	s_waitcnt vmcnt(2)
	ds_write_b128 v169, v[32:35] offset:49248
	s_waitcnt lgkmcnt(3)
	v_mfma_f32_16x16x32_bf16 v[204:207], v[156:159], v[44:47], v[124:127]
	v_mfma_f32_16x16x32_bf16 v[96:99], v[172:175], v[44:47], v[96:99]
	v_mfma_f32_16x16x32_bf16 v[68:71], v[180:183], v[44:47], v[68:71]
	v_mfma_f32_16x16x32_bf16 v[12:15], v[184:187], v[44:47], v[12:15]
	ds_read_b128 v[44:47], v171 offset:21504
	s_waitcnt vmcnt(1)
	ds_write_b128 v169, v[28:31] offset:49344
	s_waitcnt lgkmcnt(3)
	v_mfma_f32_16x16x32_bf16 v[208:211], v[156:159], v[40:43], v[116:119]
	v_mfma_f32_16x16x32_bf16 v[84:87], v[172:175], v[40:43], v[84:87]
	v_mfma_f32_16x16x32_bf16 v[212:215], v[180:183], v[40:43], v[60:63]
	v_mfma_f32_16x16x32_bf16 v[8:11], v[184:187], v[40:43], v[8:11]
	ds_read_b128 v[40:43], v171 offset:23040
	s_waitcnt vmcnt(0)
	ds_write_b128 v169, v[24:27] offset:49440
	s_waitcnt lgkmcnt(3)
	v_mfma_f32_16x16x32_bf16 v[220:223], v[156:159], v[44:47], v[104:107]
	v_mfma_f32_16x16x32_bf16 v[72:75], v[172:175], v[44:47], v[72:75]
	v_mfma_f32_16x16x32_bf16 v[224:227], v[180:183], v[44:47], v[56:59]
	v_mfma_f32_16x16x32_bf16 v[4:7], v[184:187], v[44:47], v[4:7]
	s_waitcnt lgkmcnt(1)
	v_mfma_f32_16x16x32_bf16 v[156:159], v[156:159], v[40:43], v[92:95]
	v_mfma_f32_16x16x32_bf16 v[172:175], v[172:175], v[40:43], v[64:67]
	v_mfma_f32_16x16x32_bf16 v[180:183], v[180:183], v[40:43], v[48:51]
	v_mfma_f32_16x16x32_bf16 v[184:187], v[184:187], v[40:43], v[0:3]
	s_setprio 0
	s_waitcnt lgkmcnt(0)
	s_barrier
; template <int NI, class XL, class EP>
; DI void gemm_tile(const u16* __restrict__ W, int ldw, int f0, int t0, int K, XL xl, EP ep, unsigned char* smem) {
;     ...
;   for (int it = 0; it < nk; ++it) {
;     const u16* Ws = S0 + (it & 1) * BUF; const u16* Xs = Ws + 128 * LST;
;     __builtin_amdgcn_s_setprio(1);
;     bf16x8 a[4];
; #pragma unroll
;     for (int mi = 0; mi < 4; ++mi) a[mi] = *(const bf16x8*)(Ws + (wf * 64 + mi * 16 + lr) * LST + lq * 8);
; #pragma unroll
;     for (int ni = 0; ni < NI; ++ni) {
;       const bf16x8 b = *(const bf16x8*)(Xs + (wt * (NI * 16) + ni * 16 + lr) * LST + lq * 8);
; #pragma unroll
;       for (int mi = 0; mi < 4; ++mi) acc[mi][ni] = mfma16(a[mi], b, acc[mi][ni]);
;     }
;     __builtin_amdgcn_sched_group_barrier(0x100, 6, 0);
; #pragma unroll
;     for (int ni = 0; ni < NI; ++ni) { __builtin_amdgcn_sched_group_barrier(0x008, 4, 0); if (ni + 2 < NI) __builtin_amdgcn_sched_group_barrier(0x100, 1, 0); }
;     __builtin_amdgcn_s_setprio(0);
; DI void phase8(const Params& p, const Sched& sched, unsigned char* smem) {
;     ...
;       for (int h2 = 0; h2 < 2; ++h2) {
;         const int fl = wf * 16 + lq * 4, fc = (2 * wf + h2) * 16 + lq * 4, F = tn * 64 + fc;
;         __syncthreads();
; #pragma unroll
;         for (int ni = 0; ni < 8; ++ni) *(f32x4*)(gl + (wt * 128 + ni * 16 + lr) * 36 + fl) = acc[2 * h2][ni];
;         __syncthreads();
;         const float4 w0 = *(const float4*)(p.conv_w + F), w1 = *(const float4*)(p.conv_w + FF + F), w2 = *(const float4*)(p.conv_w + 2 * FF + F), cb = *(const float4*)(p.conv_b + F);
; #pragma unroll
;         for (int ni = 0; ni < 8; ++ni) {
;           const int row = wt * 128 + ni * 16 + lr;
;           const f32x4 gv = acc[2 * h2][ni], uv = acc[2 * h2 + 1][ni];
;           if (row >= 2) {
;             const f32x4 g1 = *(const f32x4*)(gl + (row - 1) * 36 + fl), g2 = *(const f32x4*)(gl + (row - 2) * 36 + fl);
;             f32x4 o;
;             o[0] = cb.x + w0.x * g2[0] + w1.x * g1[0] + w2.x * gv[0];
;             o[1] = cb.y + w0.y * g2[1] + w1.y * g1[1] + w2.y * gv[1];
;             o[2] = cb.z + w0.z * g2[2] + w1.z * g1[2] + w2.z * gv[2];
;             o[3] = cb.w + w0.w * g2[3] + w1.w * g1[3] + w2.w * gv[3];
; #pragma unroll
;             for (int j = 0; j < 4; ++j) o[j] = o[j] * sigmoidf_(o[j]) * uv[j];
;             store4(Ls + row * 72 + fc, o);
;           } else {
	s_setprio 1
	ds_read_b128 v[0:3], v152 offset:36864
	ds_read_b128 v[228:231], v152 offset:38400
	ds_read_b128 v[232:235], v152 offset:39936
	ds_read_b128 v[236:239], v152 offset:41472
	ds_read_b128 v[16:19], v171 offset:49152
	ds_read_b128 v[20:23], v171 offset:50688
	s_waitcnt lgkmcnt(1)
	v_mfma_f32_16x16x32_bf16 v[140:143], v[0:3], v[16:19], v[148:151]
	v_mfma_f32_16x16x32_bf16 v[136:139], v[228:231], v[16:19], v[136:139]
	v_mfma_f32_16x16x32_bf16 v[60:63], v[232:235], v[16:19], v[112:115]
	v_mfma_f32_16x16x32_bf16 v[56:59], v[236:239], v[16:19], v[80:83]
	ds_read_b128 v[16:19], v171 offset:52224
	s_waitcnt lgkmcnt(1)
	v_mfma_f32_16x16x32_bf16 v[132:135], v[0:3], v[20:23], v[144:147]
	v_mfma_f32_16x16x32_bf16 v[128:131], v[228:231], v[20:23], v[128:131]
	v_mfma_f32_16x16x32_bf16 v[52:55], v[232:235], v[20:23], v[100:103]
	v_mfma_f32_16x16x32_bf16 v[48:51], v[236:239], v[20:23], v[188:191]
	ds_read_b128 v[20:23], v171 offset:53760
	s_waitcnt lgkmcnt(1)
	v_mfma_f32_16x16x32_bf16 v[124:127], v[0:3], v[16:19], v[192:195]
	v_mfma_f32_16x16x32_bf16 v[120:123], v[228:231], v[16:19], v[120:123]
	v_mfma_f32_16x16x32_bf16 v[44:47], v[232:235], v[16:19], v[88:91]
	v_mfma_f32_16x16x32_bf16 v[40:43], v[236:239], v[16:19], v[176:179]
	ds_read_b128 v[16:19], v171 offset:55296
	s_waitcnt lgkmcnt(1)
	v_mfma_f32_16x16x32_bf16 v[116:119], v[0:3], v[20:23], v[196:199]
	v_mfma_f32_16x16x32_bf16 v[112:115], v[228:231], v[20:23], v[108:111]
	v_mfma_f32_16x16x32_bf16 v[36:39], v[232:235], v[20:23], v[76:79]
	v_mfma_f32_16x16x32_bf16 v[32:35], v[236:239], v[20:23], v[200:203]
	ds_read_b128 v[64:67], v171 offset:56832
	s_waitcnt lgkmcnt(1)
	v_mfma_f32_16x16x32_bf16 v[108:111], v[0:3], v[16:19], v[204:207]
	v_mfma_f32_16x16x32_bf16 v[104:107], v[228:231], v[16:19], v[96:99]
	v_mfma_f32_16x16x32_bf16 v[28:31], v[232:235], v[16:19], v[68:71]
	v_mfma_f32_16x16x32_bf16 v[24:27], v[236:239], v[16:19], v[12:15]
	s_nop 1
	ds_read_b128 v[68:71], v171 offset:58368
	s_waitcnt lgkmcnt(1)
	v_mfma_f32_16x16x32_bf16 v[100:103], v[0:3], v[64:67], v[208:211]
	v_mfma_f32_16x16x32_bf16 v[96:99], v[228:231], v[64:67], v[84:87]
	v_mfma_f32_16x16x32_bf16 v[20:23], v[232:235], v[64:67], v[212:215]
	v_mfma_f32_16x16x32_bf16 v[16:19], v[236:239], v[64:67], v[8:11]
	ds_read_b128 v[76:79], v171 offset:59904
	s_waitcnt lgkmcnt(1)
	v_mfma_f32_16x16x32_bf16 v[92:95], v[0:3], v[68:71], v[220:223]
	v_mfma_f32_16x16x32_bf16 v[72:75], v[228:231], v[68:71], v[72:75]
	v_mfma_f32_16x16x32_bf16 v[12:15], v[232:235], v[68:71], v[224:227]
	v_mfma_f32_16x16x32_bf16 v[8:11], v[236:239], v[68:71], v[4:7]
	s_waitcnt lgkmcnt(0)
	v_mfma_f32_16x16x32_bf16 v[64:67], v[0:3], v[76:79], v[156:159]
	v_mfma_f32_16x16x32_bf16 v[68:71], v[228:231], v[76:79], v[172:175]
	v_mfma_f32_16x16x32_bf16 v[0:3], v[232:235], v[76:79], v[180:183]
	v_mfma_f32_16x16x32_bf16 v[4:7], v[236:239], v[76:79], v[184:187]
	s_setprio 0
	v_lshlrev_b32_e32 v76, 2, v168
	v_lshl_or_b32 v152, v155, 4, v76
	v_lshl_or_b32 v156, v155, 5, v76
	v_lshlrev_b32_e32 v76, 2, v152
	v_mad_u32_u24 v77, v154, s47, v160
	v_add_u32_e32 v159, v77, v76
	v_mad_u32_u24 v77, v154, s47, v161
	v_add_u32_e32 v168, v77, v76
	v_mad_u32_u24 v77, v154, s47, v162
	s_lshl_b32 s57, s56, 6
	v_add_u32_e32 v169, v77, v76
	v_mad_u32_u24 v77, v154, s47, v163
	v_add_u32_e32 v170, v77, v76
	v_mad_u32_u24 v77, v154, s47, v164
	v_add_u32_e32 v144, s57, v156
	v_add_u32_e32 v171, v77, v76
	v_mad_u32_u24 v77, v154, s47, v165
	v_ashrrev_i32_e32 v145, 31, v144
	v_add_u32_e32 v172, v77, v76
	v_mad_u32_u24 v77, v154, s47, v166
	v_lshlrev_b64 v[146:147], 2, v[144:145]
	v_mad_u32_u24 v158, v154, s47, v76
	v_add_u32_e32 v173, v77, v76
	v_lshl_add_u64 v[148:149], s[68:69], 0, v[146:147]
	v_lshl_add_u64 v[76:77], s[22:23], 0, v[146:147]
	v_lshl_add_u64 v[78:79], s[24:25], 0, v[146:147]
	v_lshl_add_u64 v[150:151], s[70:71], 0, v[146:147]
	global_load_dwordx4 v[84:87], v[148:149], off
	global_load_dwordx4 v[80:83], v[76:77], off
	global_load_dwordx4 v[88:91], v[150:151], off
	global_load_dwordx4 v[76:79], v[78:79], off
	s_barrier
	ds_write_b128 v158, v[140:143]
	ds_write_b128 v159, v[132:135]
	ds_write_b128 v168, v[124:127]
	ds_write_b128 v169, v[116:119]
	ds_write_b128 v170, v[108:111]
	ds_write_b128 v171, v[100:103]
	ds_write_b128 v172, v[92:95]
	ds_write_b128 v173, v[64:67]
	s_waitcnt lgkmcnt(0)
	s_barrier
	v_cmp_gt_u32_e64 s[4:5], 2, v154
	v_lshl_or_b32 v157, s30, 1, v154
	s_and_saveexec_b64 s[6:7], s[4:5]
	s_xor_b64 s[6:7], exec, s[6:7]
	s_cbranch_execz .LBB0_948
	s_ashr_i32 s31, s30, 31
	s_lshl_b64 s[34:35], s[30:31], 2
	v_or_b32_e32 v155, s34, v154
	v_mov_b64_e32 v[174:175], s[16:17]
	v_mad_u64_u32 v[174:175], s[58:59], v155, s48, v[174:175]
	v_mad_i32_i24 v175, s35, v167, v175
	v_lshl_add_u64 v[174:175], v[174:175], 0, v[146:147]
	global_store_dwordx4 v[174:175], v[140:143], off
	s_nop 1
	v_mov_b64_e32 v[140:141], s[10:11]
	v_mad_u64_u32 v[140:141], s[34:35], v157, s48, v[140:141]
	v_mad_i32_i24 v141, s31, v167, v141
	v_lshl_add_u64 v[140:141], v[140:141], 0, v[146:147]
	global_store_dwordx4 v[140:141], v[136:139], off

; DI float sigmoidf_(float x) { return 1.0f / (1.0f + __expf(-x)); }
; DI void store4(u16* dst, f32x4 v) { uint2 w; w.x = cvtpk(v[0], v[1]); w.y = cvtpk(v[2], v[3]); *(uint2*)dst = w; }
; DI void phase8(const Params& p, const Sched& sched, unsigned char* smem) {
;     ...
;       for (int h2 = 0; h2 < 2; ++h2) {
;         const int fl = wf * 16 + lq * 4, fc = (2 * wf + h2) * 16 + lq * 4, F = tn * 64 + fc;
;         __syncthreads();
; #pragma unroll
;         for (int ni = 0; ni < 8; ++ni) *(f32x4*)(gl + (wt * 128 + ni * 16 + lr) * 36 + fl) = acc[2 * h2][ni];
;         __syncthreads();
;         const float4 w0 = *(const float4*)(p.conv_w + F), w1 = *(const float4*)(p.conv_w + FF + F), w2 = *(const float4*)(p.conv_w + 2 * FF + F), cb = *(const float4*)(p.conv_b + F);
; #pragma unroll
;         for (int ni = 0; ni < 8; ++ni) {
;           const int row = wt * 128 + ni * 16 + lr;
;           const f32x4 gv = acc[2 * h2][ni], uv = acc[2 * h2 + 1][ni];
;           if (row >= 2) {
;             const f32x4 g1 = *(const f32x4*)(gl + (row - 1) * 36 + fl), g2 = *(const f32x4*)(gl + (row - 2) * 36 + fl);
;             f32x4 o;
;             o[0] = cb.x + w0.x * g2[0] + w1.x * g1[0] + w2.x * gv[0];
;             o[1] = cb.y + w0.y * g2[1] + w1.y * g1[1] + w2.y * gv[1];
;             o[2] = cb.z + w0.z * g2[2] + w1.z * g1[2] + w2.z * gv[2];
;             o[3] = cb.w + w0.w * g2[3] + w1.w * g1[3] + w2.w * gv[3];
; #pragma unroll
;             for (int j = 0; j < 4; ++j) o[j] = o[j] * sigmoidf_(o[j]) * uv[j];
;             store4(Ls + row * 72 + fc, o);
;           } else {
;             *(f32x4*)(gside + ((size_t)tm * 4 + row) * FF + F) = gv;
;             *(f32x4*)(uside + ((size_t)tm * 2 + row) * FF + F) = uv;
;           }
;           if (row >= 254) *(f32x4*)(gside + ((size_t)tm * 4 + 2 + (row - 254)) * FF + F) = gv;
.LBB0_952:
	s_or_b64 exec, exec, s[34:35]
	s_nop 0
	v_add3_u32 v64, s57, v156, 16
	v_ashrrev_i32_e32 v65, 31, v64
	v_lshlrev_b64 v[64:65], 2, v[64:65]
	v_lshl_add_u64 v[66:67], s[22:23], 0, v[64:65]
	v_lshl_add_u64 v[64:65], s[24:25], 0, v[64:65]
	global_load_dwordx4 v[72:75], v[148:149], off offset:64
	global_load_dwordx4 v[68:71], v[66:67], off
	s_nop 0
	global_load_dwordx4 v[64:67], v[64:65], off
	s_nop 0
	global_load_dwordx4 v[76:79], v[150:151], off offset:64
	s_waitcnt lgkmcnt(0)
	s_barrier
	ds_write_b128 v158, v[60:63]
	ds_write_b128 v159, v[52:55]
	ds_write_b128 v168, v[44:47]
	ds_write_b128 v169, v[36:39]
	ds_write_b128 v170, v[28:31]
	ds_write_b128 v171, v[20:23]
	ds_write_b128 v172, v[12:15]
	ds_write_b128 v173, v[0:3]
	s_waitcnt lgkmcnt(0)
	s_barrier
	s_and_saveexec_b64 s[34:35], s[4:5]
	s_xor_b64 s[4:5], exec, s[34:35]
	s_cbranch_execz .LBB0_954
	s_ashr_i32 s31, s30, 31
	s_lshl_b64 s[34:35], s[30:31], 2
	v_or_b32_e32 v82, s34, v154
	v_mov_b64_e32 v[80:81], s[16:17]
	v_mad_u64_u32 v[80:81], s[58:59], v82, s48, v[80:81]
	v_mad_i32_i24 v81, s35, v167, v81
	v_lshl_add_u64 v[80:81], v[80:81], 0, v[146:147]
	global_store_dwordx4 v[80:81], v[60:63], off offset:64
	s_nop 1
	v_mov_b64_e32 v[60:61], s[10:11]
	v_mad_u64_u32 v[60:61], s[34:35], v157, s48, v[60:61]
	v_mad_i32_i24 v61, s31, v167, v61
	v_lshl_add_u64 v[60:61], v[60:61], 0, v[146:147]
	global_store_dwordx4 v[60:61], v[56:59], off offset:64

; DI f32x4 mfma16(bf16x8 a, bf16x8 b, f32x4 c) { return __builtin_amdgcn_mfma_f32_16x16x32_bf16(a, b, c, 0, 0, 0); }
; template <int NI, class XL, class EP>
; DI void gemm_tile(const u16* __restrict__ W, int ldw, int f0, int t0, int K, XL xl, EP ep, unsigned char* smem) {
;     ...
;   auto gload = [&](int it) {
;     const int k = it * 32;
;     const char* wb = (const char*)(W + (size_t)(k >> 5) * ldw * 32);
;     const char* xb = (const char*)xl.kbase(k);
; #pragma unroll
;     for (int i = 0; i < 2; ++i) wr[i] = *(const u32x4*)(wb + wbyte + i * 64);
; #pragma unroll
;     for (int i = 0; i < XR; ++i) xr[i] = *(const u32x4*)(xb + xbyte + i * xrs);
;   };
;   auto lstore = [&](int buf) {
;     u16* Ws = S0 + buf * BUF; u16* Xs = Ws + 128 * LST;
; #pragma unroll
;     for (int i = 0; i < 2; ++i) *(u32x4*)(Ws + (srow * 2 + i) * LST + sch) = wr[i];
; #pragma unroll
;     for (int i = 0; i < XR; ++i) *(u32x4*)(Xs + (srow * XR + i) * LST + sch) = xr[i];
;   };
;   gload(0);
;   __syncthreads();
;   lstore(0);
;   __syncthreads();
;   if (nk > 1) gload(1);
;   for (int it = 0; it < nk; ++it) {
;     const u16* Ws = S0 + (it & 1) * BUF; const u16* Xs = Ws + 128 * LST;
;     __builtin_amdgcn_s_setprio(1);
;     bf16x8 a[4];
; #pragma unroll
;     for (int mi = 0; mi < 4; ++mi) a[mi] = *(const bf16x8*)(Ws + (wf * 64 + mi * 16 + lr) * LST + lq * 8);
; #pragma unroll
;     for (int ni = 0; ni < NI; ++ni) {
;       const bf16x8 b = *(const bf16x8*)(Xs + (wt * (NI * 16) + ni * 16 + lr) * LST + lq * 8);
; #pragma unroll
;       for (int mi = 0; mi < 4; ++mi) acc[mi][ni] = mfma16(a[mi], b, acc[mi][ni]);
;     }
;     __builtin_amdgcn_sched_group_barrier(0x100, 6, 0);
; #pragma unroll
;     for (int ni = 0; ni < NI; ++ni) { __builtin_amdgcn_sched_group_barrier(0x008, 4, 0); if (ni + 2 < NI) __builtin_amdgcn_sched_group_barrier(0x100, 1, 0); }
;     __builtin_amdgcn_s_setprio(0);
;     if (it + 1 < nk) lstore((it + 1) & 1);
;     if (it + 2 < nk) gload(it + 2);
;     __syncthreads();
.LBB0_1095:
	s_setprio 1
	ds_read_b128 v[168:171], v228 offset:0
	ds_read_b128 v[172:175], v228 offset:1536
	ds_read_b128 v[180:183], v228 offset:3072
	ds_read_b128 v[184:187], v228 offset:4608
	ds_read_b128 v[176:179], v152 offset:12288
	ds_read_b128 v[188:191], v152 offset:13824
	s_waitcnt lgkmcnt(1)
	v_mfma_f32_16x16x32_bf16 v[148:151], v[168:171], v[176:179], v[148:151]
	v_mfma_f32_16x16x32_bf16 v[136:139], v[172:175], v[176:179], v[136:139]
	v_mfma_f32_16x16x32_bf16 v[112:115], v[180:183], v[176:179], v[112:115]
	v_mfma_f32_16x16x32_bf16 v[80:83], v[184:187], v[176:179], v[80:83]
	ds_read_b128 v[176:179], v152 offset:15360
	s_waitcnt vmcnt(6)
	ds_write_b128 v229, v[20:23] offset:36864
	s_waitcnt lgkmcnt(2)
	v_mfma_f32_16x16x32_bf16 v[144:147], v[168:171], v[188:191], v[144:147]
	v_mfma_f32_16x16x32_bf16 v[128:131], v[172:175], v[188:191], v[128:131]
	v_mfma_f32_16x16x32_bf16 v[100:103], v[180:183], v[188:191], v[100:103]
	v_mfma_f32_16x16x32_bf16 v[68:71], v[184:187], v[188:191], v[68:71]
	ds_read_b128 v[188:191], v152 offset:16896
	ds_write_b128 v229, v[16:19] offset:36960
	global_load_dwordx4 v[20:23], v154, s[98:99]
	global_load_dwordx4 v[16:19], v154, s[98:99] offset:64
	s_waitcnt lgkmcnt(3)
	v_mfma_f32_16x16x32_bf16 v[140:143], v[168:171], v[176:179], v[140:143]
	v_mfma_f32_16x16x32_bf16 v[120:123], v[172:175], v[176:179], v[120:123]
	v_mfma_f32_16x16x32_bf16 v[88:91], v[180:183], v[176:179], v[88:91]
	v_mfma_f32_16x16x32_bf16 v[44:47], v[184:187], v[176:179], v[44:47]
	ds_read_b128 v[176:179], v152 offset:18432
	ds_write_b128 v230, v[36:39] offset:49152
	global_load_dwordx4 v[36:39], v156, s[100:101] offset:2048
	s_waitcnt lgkmcnt(3)
	v_mfma_f32_16x16x32_bf16 v[132:135], v[168:171], v[188:191], v[132:135]
	v_mfma_f32_16x16x32_bf16 v[108:111], v[172:175], v[188:191], v[108:111]
	v_mfma_f32_16x16x32_bf16 v[76:79], v[180:183], v[188:191], v[76:79]
	v_mfma_f32_16x16x32_bf16 v[40:43], v[184:187], v[188:191], v[40:43]
	ds_read_b128 v[188:191], v152 offset:19968
	ds_write_b128 v230, v[32:35] offset:49248
	global_load_dwordx4 v[32:35], v156, s[100:101] offset:2112
	s_waitcnt lgkmcnt(3)
	v_mfma_f32_16x16x32_bf16 v[124:127], v[168:171], v[176:179], v[124:127]
	v_mfma_f32_16x16x32_bf16 v[96:99], v[172:175], v[176:179], v[96:99]
	v_mfma_f32_16x16x32_bf16 v[64:67], v[180:183], v[176:179], v[64:67]
	v_mfma_f32_16x16x32_bf16 v[12:15], v[184:187], v[176:179], v[12:15]
	ds_read_b128 v[176:179], v152 offset:21504
	ds_write_b128 v230, v[28:31] offset:49344
	global_load_dwordx4 v[28:31], v156, s[100:101] offset:2176
	s_waitcnt lgkmcnt(3)
	v_mfma_f32_16x16x32_bf16 v[116:119], v[168:171], v[188:191], v[116:119]
	v_mfma_f32_16x16x32_bf16 v[84:87], v[172:175], v[188:191], v[84:87]
	v_mfma_f32_16x16x32_bf16 v[56:59], v[180:183], v[188:191], v[56:59]
	v_mfma_f32_16x16x32_bf16 v[8:11], v[184:187], v[188:191], v[8:11]
	ds_read_b128 v[188:191], v152 offset:23040
	ds_write_b128 v230, v[24:27] offset:49440
	global_load_dwordx4 v[24:27], v156, s[100:101] offset:2240
	s_waitcnt lgkmcnt(3)
	v_mfma_f32_16x16x32_bf16 v[104:107], v[168:171], v[176:179], v[104:107]
	v_mfma_f32_16x16x32_bf16 v[72:75], v[172:175], v[176:179], v[72:75]
	v_mfma_f32_16x16x32_bf16 v[52:55], v[180:183], v[176:179], v[52:55]
	v_mfma_f32_16x16x32_bf16 v[4:7], v[184:187], v[176:179], v[4:7]
	s_add_u32 s98, s98, s16
	s_addc_u32 s99, s99, s17
	s_add_u32 s100, s100, s14
	s_addc_u32 s101, s101, s15
	s_waitcnt lgkmcnt(1)
	v_mfma_f32_16x16x32_bf16 v[92:95], v[168:171], v[188:191], v[92:95]
	v_mfma_f32_16x16x32_bf16 v[60:63], v[172:175], v[188:191], v[60:63]
	v_mfma_f32_16x16x32_bf16 v[48:51], v[180:183], v[188:191], v[48:51]
	v_mfma_f32_16x16x32_bf16 v[0:3], v[184:187], v[188:191], v[0:3]
	s_setprio 0
	s_waitcnt lgkmcnt(0)
	s_barrier
	s_setprio 1
	ds_read_b128 v[168:171], v228 offset:36864
	ds_read_b128 v[172:175], v228 offset:38400
	ds_read_b128 v[180:183], v228 offset:39936
	ds_read_b128 v[184:187], v228 offset:41472
	ds_read_b128 v[176:179], v152 offset:49152
	ds_read_b128 v[188:191], v152 offset:50688
	s_waitcnt lgkmcnt(1)
	v_mfma_f32_16x16x32_bf16 v[148:151], v[168:171], v[176:179], v[148:151]
	v_mfma_f32_16x16x32_bf16 v[136:139], v[172:175], v[176:179], v[136:139]
	v_mfma_f32_16x16x32_bf16 v[112:115], v[180:183], v[176:179], v[112:115]
	v_mfma_f32_16x16x32_bf16 v[80:83], v[184:187], v[176:179], v[80:83]
	ds_read_b128 v[176:179], v152 offset:52224
	s_waitcnt vmcnt(6)
	ds_write_b128 v229, v[200:203] offset:0
	s_waitcnt lgkmcnt(2)
	v_mfma_f32_16x16x32_bf16 v[144:147], v[168:171], v[188:191], v[144:147]
	v_mfma_f32_16x16x32_bf16 v[128:131], v[172:175], v[188:191], v[128:131]
	v_mfma_f32_16x16x32_bf16 v[100:103], v[180:183], v[188:191], v[100:103]
	v_mfma_f32_16x16x32_bf16 v[68:71], v[184:187], v[188:191], v[68:71]
	ds_read_b128 v[188:191], v152 offset:53760
	ds_write_b128 v229, v[204:207] offset:96
	global_load_dwordx4 v[200:203], v154, s[98:99]
	global_load_dwordx4 v[204:207], v154, s[98:99] offset:64
	s_waitcnt lgkmcnt(3)
	v_mfma_f32_16x16x32_bf16 v[140:143], v[168:171], v[176:179], v[140:143]
	v_mfma_f32_16x16x32_bf16 v[120:123], v[172:175], v[176:179], v[120:123]
	v_mfma_f32_16x16x32_bf16 v[88:91], v[180:183], v[176:179], v[88:91]
	v_mfma_f32_16x16x32_bf16 v[44:47], v[184:187], v[176:179], v[44:47]
	ds_read_b128 v[176:179], v152 offset:55296
	ds_write_b128 v230, v[208:211] offset:12288
	global_load_dwordx4 v[208:211], v156, s[100:101] offset:2048
	s_waitcnt lgkmcnt(3)
; DI f32x4 mfma16(bf16x8 a, bf16x8 b, f32x4 c) { return __builtin_amdgcn_mfma_f32_16x16x32_bf16(a, b, c, 0, 0, 0); }
; template <int NI, class XL, class EP>
; DI void gemm_tile(const u16* __restrict__ W, int ldw, int f0, int t0, int K, XL xl, EP ep, unsigned char* smem) {
;     ...
;   auto gload = [&](int it) {
;     const int k = it * 32;
;     const char* wb = (const char*)(W + (size_t)(k >> 5) * ldw * 32);
;     const char* xb = (const char*)xl.kbase(k);
; #pragma unroll
;     for (int i = 0; i < 2; ++i) wr[i] = *(const u32x4*)(wb + wbyte + i * 64);
; #pragma unroll
;     for (int i = 0; i < XR; ++i) xr[i] = *(const u32x4*)(xb + xbyte + i * xrs);
;   };
;   auto lstore = [&](int buf) {
;     u16* Ws = S0 + buf * BUF; u16* Xs = Ws + 128 * LST;
; #pragma unroll
;     for (int i = 0; i < 2; ++i) *(u32x4*)(Ws + (srow * 2 + i) * LST + sch) = wr[i];
; #pragma unroll
;     for (int i = 0; i < XR; ++i) *(u32x4*)(Xs + (srow * XR + i) * LST + sch) = xr[i];
;   };
;   gload(0);
;   __syncthreads();
;   lstore(0);
;   __syncthreads();
;   if (nk > 1) gload(1);
;   for (int it = 0; it < nk; ++it) {
;     const u16* Ws = S0 + (it & 1) * BUF; const u16* Xs = Ws + 128 * LST;
;     __builtin_amdgcn_s_setprio(1);
;     bf16x8 a[4];
; #pragma unroll
;     for (int mi = 0; mi < 4; ++mi) a[mi] = *(const bf16x8*)(Ws + (wf * 64 + mi * 16 + lr) * LST + lq * 8);
; #pragma unroll
;     for (int ni = 0; ni < NI; ++ni) {
;       const bf16x8 b = *(const bf16x8*)(Xs + (wt * (NI * 16) + ni * 16 + lr) * LST + lq * 8);
; #pragma unroll
;       for (int mi = 0; mi < 4; ++mi) acc[mi][ni] = mfma16(a[mi], b, acc[mi][ni]);
;     }
;     __builtin_amdgcn_sched_group_barrier(0x100, 6, 0);
; #pragma unroll
;     for (int ni = 0; ni < NI; ++ni) { __builtin_amdgcn_sched_group_barrier(0x008, 4, 0); if (ni + 2 < NI) __builtin_amdgcn_sched_group_barrier(0x100, 1, 0); }
;     __builtin_amdgcn_s_setprio(0);
;     if (it + 1 < nk) lstore((it + 1) & 1);
;     if (it + 2 < nk) gload(it + 2);
;     __syncthreads();
	v_mfma_f32_16x16x32_bf16 v[132:135], v[168:171], v[188:191], v[132:135]
	v_mfma_f32_16x16x32_bf16 v[108:111], v[172:175], v[188:191], v[108:111]
	v_mfma_f32_16x16x32_bf16 v[76:79], v[180:183], v[188:191], v[76:79]
	v_mfma_f32_16x16x32_bf16 v[40:43], v[184:187], v[188:191], v[40:43]
	ds_read_b128 v[188:191], v152 offset:56832
	ds_write_b128 v230, v[212:215] offset:12384
	global_load_dwordx4 v[212:215], v156, s[100:101] offset:2112
	s_waitcnt lgkmcnt(3)
	v_mfma_f32_16x16x32_bf16 v[124:127], v[168:171], v[176:179], v[124:127]
	v_mfma_f32_16x16x32_bf16 v[96:99], v[172:175], v[176:179], v[96:99]
	v_mfma_f32_16x16x32_bf16 v[64:67], v[180:183], v[176:179], v[64:67]
	v_mfma_f32_16x16x32_bf16 v[12:15], v[184:187], v[176:179], v[12:15]
	ds_read_b128 v[176:179], v152 offset:58368
	ds_write_b128 v230, v[220:223] offset:12480
	global_load_dwordx4 v[220:223], v156, s[100:101] offset:2176
	s_waitcnt lgkmcnt(3)
	v_mfma_f32_16x16x32_bf16 v[116:119], v[168:171], v[188:191], v[116:119]
	v_mfma_f32_16x16x32_bf16 v[84:87], v[172:175], v[188:191], v[84:87]
	v_mfma_f32_16x16x32_bf16 v[56:59], v[180:183], v[188:191], v[56:59]
	v_mfma_f32_16x16x32_bf16 v[8:11], v[184:187], v[188:191], v[8:11]
	ds_read_b128 v[188:191], v152 offset:59904
	ds_write_b128 v230, v[224:227] offset:12576
	global_load_dwordx4 v[224:227], v156, s[100:101] offset:2240
	s_waitcnt lgkmcnt(3)
	v_mfma_f32_16x16x32_bf16 v[104:107], v[168:171], v[176:179], v[104:107]
	v_mfma_f32_16x16x32_bf16 v[72:75], v[172:175], v[176:179], v[72:75]
	v_mfma_f32_16x16x32_bf16 v[52:55], v[180:183], v[176:179], v[52:55]
	v_mfma_f32_16x16x32_bf16 v[4:7], v[184:187], v[176:179], v[4:7]
	s_add_u32 s98, s98, s16
	s_addc_u32 s99, s99, s17
	s_add_u32 s100, s100, s14
	s_addc_u32 s101, s101, s15
	s_add_i32 s33, s33, 2
	s_waitcnt lgkmcnt(1)
	v_mfma_f32_16x16x32_bf16 v[92:95], v[168:171], v[188:191], v[92:95]
	v_mfma_f32_16x16x32_bf16 v[60:63], v[172:175], v[188:191], v[60:63]
	v_mfma_f32_16x16x32_bf16 v[48:51], v[180:183], v[188:191], v[48:51]
	v_mfma_f32_16x16x32_bf16 v[0:3], v[184:187], v[188:191], v[0:3]
	s_setprio 0
	s_cmpk_lg_i32 s33, 85
	s_waitcnt lgkmcnt(0)
	s_barrier
	s_cbranch_scc1 .LBB0_1095
	s_setprio 1
	ds_read_b128 v[168:171], v228 offset:0
	ds_read_b128 v[172:175], v228 offset:1536
	ds_read_b128 v[180:183], v228 offset:3072
	ds_read_b128 v[184:187], v228 offset:4608
	ds_read_b128 v[176:179], v152 offset:12288
	ds_read_b128 v[188:191], v152 offset:13824
	s_waitcnt lgkmcnt(1)
	v_mfma_f32_16x16x32_bf16 v[148:151], v[168:171], v[176:179], v[148:151]
	v_mfma_f32_16x16x32_bf16 v[136:139], v[172:175], v[176:179], v[136:139]
	v_mfma_f32_16x16x32_bf16 v[112:115], v[180:183], v[176:179], v[112:115]
	v_mfma_f32_16x16x32_bf16 v[80:83], v[184:187], v[176:179], v[80:83]
	ds_read_b128 v[176:179], v152 offset:15360
	s_waitcnt vmcnt(6)
	ds_write_b128 v229, v[20:23] offset:36864
	s_waitcnt lgkmcnt(2)
	v_mfma_f32_16x16x32_bf16 v[144:147], v[168:171], v[188:191], v[144:147]
	v_mfma_f32_16x16x32_bf16 v[128:131], v[172:175], v[188:191], v[128:131]
	v_mfma_f32_16x16x32_bf16 v[100:103], v[180:183], v[188:191], v[100:103]
	v_mfma_f32_16x16x32_bf16 v[68:71], v[184:187], v[188:191], v[68:71]
	ds_read_b128 v[188:191], v152 offset:16896
	ds_write_b128 v229, v[16:19] offset:36960
	global_load_dwordx4 v[20:23], v154, s[98:99]
	global_load_dwordx4 v[16:19], v154, s[98:99] offset:64
	s_waitcnt lgkmcnt(3)
	v_mfma_f32_16x16x32_bf16 v[140:143], v[168:171], v[176:179], v[140:143]
	v_mfma_f32_16x16x32_bf16 v[120:123], v[172:175], v[176:179], v[120:123]
	v_mfma_f32_16x16x32_bf16 v[88:91], v[180:183], v[176:179], v[88:91]
	v_mfma_f32_16x16x32_bf16 v[44:47], v[184:187], v[176:179], v[44:47]
	ds_read_b128 v[176:179], v152 offset:18432
	ds_write_b128 v230, v[36:39] offset:49152
	global_load_dwordx4 v[36:39], v156, s[100:101] offset:2048
	s_waitcnt lgkmcnt(3)
	v_mfma_f32_16x16x32_bf16 v[132:135], v[168:171], v[188:191], v[132:135]
	v_mfma_f32_16x16x32_bf16 v[108:111], v[172:175], v[188:191], v[108:111]
	v_mfma_f32_16x16x32_bf16 v[76:79], v[180:183], v[188:191], v[76:79]
	v_mfma_f32_16x16x32_bf16 v[40:43], v[184:187], v[188:191], v[40:43]
	ds_read_b128 v[188:191], v152 offset:19968
	ds_write_b128 v230, v[32:35] offset:49248
	global_load_dwordx4 v[32:35], v156, s[100:101] offset:2112
	s_waitcnt lgkmcnt(3)
	v_mfma_f32_16x16x32_bf16 v[124:127], v[168:171], v[176:179], v[124:127]
	v_mfma_f32_16x16x32_bf16 v[96:99], v[172:175], v[176:179], v[96:99]
	v_mfma_f32_16x16x32_bf16 v[64:67], v[180:183], v[176:179], v[64:67]
	v_mfma_f32_16x16x32_bf16 v[12:15], v[184:187], v[176:179], v[12:15]
	ds_read_b128 v[176:179], v152 offset:21504
	ds_write_b128 v230, v[28:31] offset:49344
	global_load_dwordx4 v[28:31], v156, s[100:101] offset:2176
	s_waitcnt lgkmcnt(3)
	v_mfma_f32_16x16x32_bf16 v[116:119], v[168:171], v[188:191], v[116:119]
	v_mfma_f32_16x16x32_bf16 v[84:87], v[172:175], v[188:191], v[84:87]
	v_mfma_f32_16x16x32_bf16 v[56:59], v[180:183], v[188:191], v[56:59]
	v_mfma_f32_16x16x32_bf16 v[8:11], v[184:187], v[188:191], v[8:11]
	ds_read_b128 v[188:191], v152 offset:23040
	ds_write_b128 v230, v[24:27] offset:49440
	global_load_dwordx4 v[24:27], v156, s[100:101] offset:2240
	s_waitcnt lgkmcnt(3)
	v_mfma_f32_16x16x32_bf16 v[104:107], v[168:171], v[176:179], v[104:107]
	v_mfma_f32_16x16x32_bf16 v[72:75], v[172:175], v[176:179], v[72:75]
	v_mfma_f32_16x16x32_bf16 v[52:55], v[180:183], v[176:179], v[52:55]
	v_mfma_f32_16x16x32_bf16 v[4:7], v[184:187], v[176:179], v[4:7]
	s_add_u32 s98, s98, s16
	s_addc_u32 s99, s99, s17
	s_add_u32 s100, s100, s14
	s_addc_u32 s101, s101, s15
	s_waitcnt lgkmcnt(1)
	v_mfma_f32_16x16x32_bf16 v[92:95], v[168:171], v[188:191], v[92:95]
	v_mfma_f32_16x16x32_bf16 v[60:63], v[172:175], v[188:191], v[60:63]
	v_mfma_f32_16x16x32_bf16 v[48:51], v[180:183], v[188:191], v[48:51]
	v_mfma_f32_16x16x32_bf16 v[0:3], v[184:187], v[188:191], v[0:3]
	s_setprio 0
	s_waitcnt lgkmcnt(0)
	s_barrier
; DI f32x4 mfma16(bf16x8 a, bf16x8 b, f32x4 c) { return __builtin_amdgcn_mfma_f32_16x16x32_bf16(a, b, c, 0, 0, 0); }
; template <int NI, class XL, class EP>
; DI void gemm_tile(const u16* __restrict__ W, int ldw, int f0, int t0, int K, XL xl, EP ep, unsigned char* smem) {
;     ...
;   for (int it = 0; it < nk; ++it) {
;     const u16* Ws = S0 + (it & 1) * BUF; const u16* Xs = Ws + 128 * LST;
;     __builtin_amdgcn_s_setprio(1);
;     bf16x8 a[4];
; #pragma unroll
;     for (int mi = 0; mi < 4; ++mi) a[mi] = *(const bf16x8*)(Ws + (wf * 64 + mi * 16 + lr) * LST + lq * 8);
; #pragma unroll
;     for (int ni = 0; ni < NI; ++ni) {
;       const bf16x8 b = *(const bf16x8*)(Xs + (wt * (NI * 16) + ni * 16 + lr) * LST + lq * 8);
; #pragma unroll
;       for (int mi = 0; mi < 4; ++mi) acc[mi][ni] = mfma16(a[mi], b, acc[mi][ni]);
;     }
;     __builtin_amdgcn_sched_group_barrier(0x100, 6, 0);
; #pragma unroll
;     for (int ni = 0; ni < NI; ++ni) { __builtin_amdgcn_sched_group_barrier(0x008, 4, 0); if (ni + 2 < NI) __builtin_amdgcn_sched_group_barrier(0x100, 1, 0); }
;     __builtin_amdgcn_s_setprio(0);
;     if (it + 1 < nk) lstore((it + 1) & 1);
;     if (it + 2 < nk) gload(it + 2);
;     __syncthreads();
	s_setprio 1
	ds_read_b128 v[168:171], v228 offset:36864
	ds_read_b128 v[172:175], v228 offset:38400
	ds_read_b128 v[180:183], v228 offset:39936
	ds_read_b128 v[184:187], v228 offset:41472
	ds_read_b128 v[176:179], v152 offset:49152
	ds_read_b128 v[188:191], v152 offset:50688
	s_waitcnt lgkmcnt(1)
	v_mfma_f32_16x16x32_bf16 v[148:151], v[168:171], v[176:179], v[148:151]
	v_mfma_f32_16x16x32_bf16 v[136:139], v[172:175], v[176:179], v[136:139]
	v_mfma_f32_16x16x32_bf16 v[112:115], v[180:183], v[176:179], v[112:115]
	v_mfma_f32_16x16x32_bf16 v[80:83], v[184:187], v[176:179], v[80:83]
	ds_read_b128 v[176:179], v152 offset:52224
	s_waitcnt vmcnt(6)
	ds_write_b128 v229, v[200:203] offset:0
	s_waitcnt lgkmcnt(2)
	v_mfma_f32_16x16x32_bf16 v[144:147], v[168:171], v[188:191], v[144:147]
	v_mfma_f32_16x16x32_bf16 v[128:131], v[172:175], v[188:191], v[128:131]
	v_mfma_f32_16x16x32_bf16 v[100:103], v[180:183], v[188:191], v[100:103]
	v_mfma_f32_16x16x32_bf16 v[68:71], v[184:187], v[188:191], v[68:71]
	ds_read_b128 v[188:191], v152 offset:53760
	ds_write_b128 v229, v[204:207] offset:96
	s_waitcnt lgkmcnt(3)
	v_mfma_f32_16x16x32_bf16 v[140:143], v[168:171], v[176:179], v[140:143]
	v_mfma_f32_16x16x32_bf16 v[120:123], v[172:175], v[176:179], v[120:123]
	v_mfma_f32_16x16x32_bf16 v[88:91], v[180:183], v[176:179], v[88:91]
	v_mfma_f32_16x16x32_bf16 v[44:47], v[184:187], v[176:179], v[44:47]
	ds_read_b128 v[176:179], v152 offset:55296
	ds_write_b128 v230, v[208:211] offset:12288
	s_waitcnt lgkmcnt(3)
	v_mfma_f32_16x16x32_bf16 v[132:135], v[168:171], v[188:191], v[132:135]
	v_mfma_f32_16x16x32_bf16 v[108:111], v[172:175], v[188:191], v[108:111]
	v_mfma_f32_16x16x32_bf16 v[76:79], v[180:183], v[188:191], v[76:79]
	v_mfma_f32_16x16x32_bf16 v[40:43], v[184:187], v[188:191], v[40:43]
	ds_read_b128 v[188:191], v152 offset:56832
	ds_write_b128 v230, v[212:215] offset:12384
	s_waitcnt lgkmcnt(3)
	v_mfma_f32_16x16x32_bf16 v[124:127], v[168:171], v[176:179], v[124:127]
	v_mfma_f32_16x16x32_bf16 v[96:99], v[172:175], v[176:179], v[96:99]
	v_mfma_f32_16x16x32_bf16 v[64:67], v[180:183], v[176:179], v[64:67]
	v_mfma_f32_16x16x32_bf16 v[12:15], v[184:187], v[176:179], v[12:15]
	ds_read_b128 v[176:179], v152 offset:58368
	ds_write_b128 v230, v[220:223] offset:12480
	s_waitcnt lgkmcnt(3)
	v_mfma_f32_16x16x32_bf16 v[116:119], v[168:171], v[188:191], v[116:119]
	v_mfma_f32_16x16x32_bf16 v[84:87], v[172:175], v[188:191], v[84:87]
	v_mfma_f32_16x16x32_bf16 v[56:59], v[180:183], v[188:191], v[56:59]
	v_mfma_f32_16x16x32_bf16 v[8:11], v[184:187], v[188:191], v[8:11]
	ds_read_b128 v[188:191], v152 offset:59904
	ds_write_b128 v230, v[224:227] offset:12576
	s_waitcnt lgkmcnt(3)
	v_mfma_f32_16x16x32_bf16 v[104:107], v[168:171], v[176:179], v[104:107]
	v_mfma_f32_16x16x32_bf16 v[72:75], v[172:175], v[176:179], v[72:75]
	v_mfma_f32_16x16x32_bf16 v[52:55], v[180:183], v[176:179], v[52:55]
	v_mfma_f32_16x16x32_bf16 v[4:7], v[184:187], v[176:179], v[4:7]
	s_add_i32 s33, s33, 2
	s_waitcnt lgkmcnt(1)
	v_mfma_f32_16x16x32_bf16 v[92:95], v[168:171], v[188:191], v[92:95]
	v_mfma_f32_16x16x32_bf16 v[60:63], v[172:175], v[188:191], v[60:63]
	v_mfma_f32_16x16x32_bf16 v[48:51], v[180:183], v[188:191], v[48:51]
	v_mfma_f32_16x16x32_bf16 v[0:3], v[184:187], v[188:191], v[0:3]
	s_setprio 0
	s_waitcnt lgkmcnt(0)
	s_barrier
	s_setprio 1
	v_lshl_add_u32 v152, v167, 1, v164
	ds_read_b128 v[154:157], v152
	v_lshl_add_u32 v161, v165, 1, v164
	ds_read_b128 v[164:167], v152 offset:1536
	ds_read_b128 v[172:175], v152 offset:3072
	ds_read_b128 v[176:179], v152 offset:4608
	ds_read_b128 v[168:171], v161 offset:12288
	ds_read_b128 v[180:183], v161 offset:13824
	s_waitcnt lgkmcnt(1)
	v_mfma_f32_16x16x32_bf16 v[148:151], v[154:157], v[168:171], v[148:151]
	v_mfma_f32_16x16x32_bf16 v[136:139], v[164:167], v[168:171], v[136:139]
	v_mfma_f32_16x16x32_bf16 v[112:115], v[172:175], v[168:171], v[112:115]
	v_mfma_f32_16x16x32_bf16 v[80:83], v[176:179], v[168:171], v[80:83]
	ds_read_b128 v[168:171], v161 offset:15360
	s_waitcnt vmcnt(5)
	ds_write_b128 v162, v[20:23] offset:36864
	s_waitcnt lgkmcnt(2)
	v_mfma_f32_16x16x32_bf16 v[144:147], v[154:157], v[180:183], v[144:147]
	v_mfma_f32_16x16x32_bf16 v[128:131], v[164:167], v[180:183], v[128:131]
	v_mfma_f32_16x16x32_bf16 v[100:103], v[172:175], v[180:183], v[100:103]
	v_mfma_f32_16x16x32_bf16 v[68:71], v[176:179], v[180:183], v[68:71]
	ds_read_b128 v[180:183], v161 offset:16896
	s_waitcnt vmcnt(4)
	ds_write_b128 v162, v[16:19] offset:36960
	s_waitcnt lgkmcnt(3)
	v_mfma_f32_16x16x32_bf16 v[140:143], v[154:157], v[168:171], v[140:143]
	v_mfma_f32_16x16x32_bf16 v[120:123], v[164:167], v[168:171], v[120:123]
	v_mfma_f32_16x16x32_bf16 v[184:187], v[172:175], v[168:171], v[88:91]
	v_mfma_f32_16x16x32_bf16 v[44:47], v[176:179], v[168:171], v[44:47]
	s_nop 1
	ds_read_b128 v[88:91], v161 offset:18432
	s_waitcnt vmcnt(3)
	ds_write_b128 v163, v[36:39] offset:49152
	s_waitcnt lgkmcnt(3)
	v_mfma_f32_16x16x32_bf16 v[132:135], v[154:157], v[180:183], v[132:135]
	v_mfma_f32_16x16x32_bf16 v[168:171], v[164:167], v[180:183], v[108:111]
	v_mfma_f32_16x16x32_bf16 v[188:191], v[172:175], v[180:183], v[76:79]
	v_mfma_f32_16x16x32_bf16 v[180:183], v[176:179], v[180:183], v[40:43]
	s_nop 2
	ds_read_b128 v[40:43], v161 offset:19968
	s_waitcnt vmcnt(2)
	ds_write_b128 v163, v[32:35] offset:49248
	s_waitcnt lgkmcnt(3)
	v_mfma_f32_16x16x32_bf16 v[124:127], v[154:157], v[88:91], v[124:127]
	v_mfma_f32_16x16x32_bf16 v[192:195], v[164:167], v[88:91], v[96:99]
	v_mfma_f32_16x16x32_bf16 v[196:199], v[172:175], v[88:91], v[64:67]
	v_mfma_f32_16x16x32_bf16 v[200:203], v[176:179], v[88:91], v[12:15]
	s_nop 2
	ds_read_b128 v[12:15], v161 offset:21504
	s_waitcnt vmcnt(1)
	ds_write_b128 v163, v[28:31] offset:49344
	s_waitcnt lgkmcnt(3)
	v_mfma_f32_16x16x32_bf16 v[116:119], v[154:157], v[40:43], v[116:119]
	v_mfma_f32_16x16x32_bf16 v[204:207], v[164:167], v[40:43], v[84:87]
	v_mfma_f32_16x16x32_bf16 v[56:59], v[172:175], v[40:43], v[56:59]
	v_mfma_f32_16x16x32_bf16 v[208:211], v[176:179], v[40:43], v[8:11]
	s_nop 2
	ds_read_b128 v[8:11], v161 offset:23040
	s_waitcnt vmcnt(0)
	ds_write_b128 v163, v[24:27] offset:49440
	s_waitcnt lgkmcnt(3)
	v_mfma_f32_16x16x32_bf16 v[212:215], v[154:157], v[12:15], v[104:107]
	v_mfma_f32_16x16x32_bf16 v[72:75], v[164:167], v[12:15], v[72:75]
	v_mfma_f32_16x16x32_bf16 v[220:223], v[172:175], v[12:15], v[52:55]
	v_mfma_f32_16x16x32_bf16 v[224:227], v[176:179], v[12:15], v[4:7]
	s_waitcnt lgkmcnt(1)
	v_mfma_f32_16x16x32_bf16 v[154:157], v[154:157], v[8:11], v[92:95]
	v_mfma_f32_16x16x32_bf16 v[60:63], v[164:167], v[8:11], v[60:63]
	v_mfma_f32_16x16x32_bf16 v[164:167], v[172:175], v[8:11], v[48:51]
	v_mfma_f32_16x16x32_bf16 v[172:175], v[176:179], v[8:11], v[0:3]
	s_setprio 0
	s_waitcnt lgkmcnt(0)
	s_barrier
; DI void store4(u16* dst, f32x4 v) { uint2 w; w.x = cvtpk(v[0], v[1]); w.y = cvtpk(v[2], v[3]); *(uint2*)dst = w; }
; DI f32x4 mfma16(bf16x8 a, bf16x8 b, f32x4 c) { return __builtin_amdgcn_mfma_f32_16x16x32_bf16(a, b, c, 0, 0, 0); }
; template <int NI, class XL, class EP>
; DI void gemm_tile(const u16* __restrict__ W, int ldw, int f0, int t0, int K, XL xl, EP ep, unsigned char* smem) {
;     ...
;   for (int it = 0; it < nk; ++it) {
;     const u16* Ws = S0 + (it & 1) * BUF; const u16* Xs = Ws + 128 * LST;
;     __builtin_amdgcn_s_setprio(1);
;     bf16x8 a[4];
; #pragma unroll
;     for (int mi = 0; mi < 4; ++mi) a[mi] = *(const bf16x8*)(Ws + (wf * 64 + mi * 16 + lr) * LST + lq * 8);
; #pragma unroll
;     for (int ni = 0; ni < NI; ++ni) {
;       const bf16x8 b = *(const bf16x8*)(Xs + (wt * (NI * 16) + ni * 16 + lr) * LST + lq * 8);
; #pragma unroll
;       for (int mi = 0; mi < 4; ++mi) acc[mi][ni] = mfma16(a[mi], b, acc[mi][ni]);
;     }
;     __builtin_amdgcn_sched_group_barrier(0x100, 6, 0);
; #pragma unroll
;     for (int ni = 0; ni < NI; ++ni) { __builtin_amdgcn_sched_group_barrier(0x008, 4, 0); if (ni + 2 < NI) __builtin_amdgcn_sched_group_barrier(0x100, 1, 0); }
;     __builtin_amdgcn_s_setprio(0);
; DI void phase9(const Params& p, const Sched& sched, unsigned char* smem) {
;     ...
;       constexpr int EST = 136;
;       u16* Ls = (u16*)smem;
;       const int b = tb >> 11;
;       __syncthreads();
; #pragma unroll
;       for (int mi = 0; mi < 4; ++mi) {
;         const int f = fb + mi * 16 + lq * 4; const float4 gm = *(const float4*)(mod + (size_t)b * 6144 + 5120 + f);
; #pragma unroll
;         for (int ni = 0; ni < 8; ++ni) {
;           const f32x4 o = {gm.x * acc[mi][ni][0], gm.y * acc[mi][ni][1], gm.z * acc[mi][ni][2], gm.w * acc[mi][ni][3]};
;           store4(Ls + (wt * 128 + ni * 16 + lr) * EST + wf * 64 + mi * 16 + lq * 4, o);
;         }
;       }
	s_lshl_b32 s30, s30, 7
	s_setprio 1
	ds_read_b128 v[28:31], v152 offset:36864
	ds_read_b128 v[176:179], v152 offset:38400
	ds_read_b128 v[228:231], v152 offset:39936
	ds_read_b128 v[232:235], v152 offset:41472
	ds_read_b128 v[0:3], v161 offset:49152
	ds_read_b128 v[4:7], v161 offset:50688
	s_waitcnt lgkmcnt(1)
	v_mfma_f32_16x16x32_bf16 v[88:91], v[28:31], v[0:3], v[148:151]
	v_mfma_f32_16x16x32_bf16 v[64:67], v[176:179], v[0:3], v[136:139]
	v_mfma_f32_16x16x32_bf16 v[32:35], v[228:231], v[0:3], v[112:115]
	v_mfma_f32_16x16x32_bf16 v[0:3], v[232:235], v[0:3], v[80:83]
	ds_read_b128 v[8:11], v161 offset:52224
	s_waitcnt lgkmcnt(1)
	v_mfma_f32_16x16x32_bf16 v[96:99], v[28:31], v[4:7], v[144:147]
	v_mfma_f32_16x16x32_bf16 v[76:79], v[176:179], v[4:7], v[128:131]
	v_mfma_f32_16x16x32_bf16 v[36:39], v[228:231], v[4:7], v[100:103]
	v_mfma_f32_16x16x32_bf16 v[4:7], v[232:235], v[4:7], v[68:71]
	ds_read_b128 v[12:15], v161 offset:53760
	s_waitcnt lgkmcnt(1)
	v_mfma_f32_16x16x32_bf16 v[104:107], v[28:31], v[8:11], v[140:143]
	v_mfma_f32_16x16x32_bf16 v[84:87], v[176:179], v[8:11], v[120:123]
	v_mfma_f32_16x16x32_bf16 v[40:43], v[228:231], v[8:11], v[184:187]
	v_mfma_f32_16x16x32_bf16 v[8:11], v[232:235], v[8:11], v[44:47]
	ds_read_b128 v[16:19], v161 offset:55296
	s_waitcnt lgkmcnt(1)
	v_mfma_f32_16x16x32_bf16 v[108:111], v[28:31], v[12:15], v[132:135]
	v_mfma_f32_16x16x32_bf16 v[92:95], v[176:179], v[12:15], v[168:171]
	v_mfma_f32_16x16x32_bf16 v[44:47], v[228:231], v[12:15], v[188:191]
	v_mfma_f32_16x16x32_bf16 v[12:15], v[232:235], v[12:15], v[180:183]
	ds_read_b128 v[20:23], v161 offset:56832
	s_waitcnt lgkmcnt(1)
	v_mfma_f32_16x16x32_bf16 v[112:115], v[28:31], v[16:19], v[124:127]
	v_mfma_f32_16x16x32_bf16 v[100:103], v[176:179], v[16:19], v[192:195]
	v_mfma_f32_16x16x32_bf16 v[48:51], v[228:231], v[16:19], v[196:199]
	v_mfma_f32_16x16x32_bf16 v[16:19], v[232:235], v[16:19], v[200:203]
	ds_read_b128 v[24:27], v161 offset:58368
	s_waitcnt lgkmcnt(1)
	v_mfma_f32_16x16x32_bf16 v[116:119], v[28:31], v[20:23], v[116:119]
	v_mfma_f32_16x16x32_bf16 v[68:71], v[176:179], v[20:23], v[204:207]
	v_mfma_f32_16x16x32_bf16 v[52:55], v[228:231], v[20:23], v[56:59]
	v_mfma_f32_16x16x32_bf16 v[20:23], v[232:235], v[20:23], v[208:211]
	ds_read_b128 v[128:131], v161 offset:59904
	s_waitcnt lgkmcnt(1)
	v_mfma_f32_16x16x32_bf16 v[120:123], v[28:31], v[24:27], v[212:215]
	v_mfma_f32_16x16x32_bf16 v[80:83], v[176:179], v[24:27], v[72:75]
	v_mfma_f32_16x16x32_bf16 v[56:59], v[228:231], v[24:27], v[220:223]
	v_mfma_f32_16x16x32_bf16 v[24:27], v[232:235], v[24:27], v[224:227]
	s_waitcnt lgkmcnt(0)
	v_mfma_f32_16x16x32_bf16 v[124:127], v[28:31], v[128:131], v[154:157]
	v_mfma_f32_16x16x32_bf16 v[72:75], v[176:179], v[128:131], v[60:63]
	v_mfma_f32_16x16x32_bf16 v[60:63], v[228:231], v[128:131], v[164:167]
	v_mfma_f32_16x16x32_bf16 v[28:31], v[232:235], v[128:131], v[172:175]
	s_setprio 0
	s_ashr_i32 s31, s31, 3
	v_add_u32_e32 v128, s30, v160
	s_mul_hi_i32 s33, s31, 0x6000
	s_mulk_i32 s31, 0x6000
	v_lshl_or_b32 v128, v158, 2, v128
	s_add_u32 s34, s72, s31
	s_addc_u32 s35, s73, s33
	v_ashrrev_i32_e32 v129, 31, v128
	v_lshl_add_u64 v[128:129], v[128:129], 2, s[34:35]
	v_add_co_u32_e32 v140, vcc, s24, v128
	v_mul_u32_u24_e32 v138, 0x88, v159
	s_nop 0
	v_addc_co_u32_e32 v141, vcc, 0, v129, vcc
	v_lshlrev_b32_e32 v136, 1, v160
	v_lshlrev_b32_e32 v137, 3, v158
	v_lshlrev_b32_e32 v138, 1, v138
	s_barrier
	global_load_dwordx4 v[128:131], v[140:141], off
	global_load_dwordx4 v[132:135], v[140:141], off offset:64
	v_add3_u32 v144, v136, v137, v138
	global_load_dwordx4 v[136:139], v[140:141], off offset:128
	v_add_u32_e32 v145, 0x1000, v144
	global_load_dwordx4 v[140:143], v[140:141], off offset:192
	v_add_u32_e32 v146, 0x2000, v144
	v_add_u32_e32 v147, 0x3000, v144
	v_add_u32_e32 v148, 0x4000, v144
	s_add_i32 s28, s28, s78
	s_add_i32 s27, s27, s78
	s_cmp_gt_i32 s28, 63
	s_waitcnt vmcnt(3)
	v_pk_mul_f32 v[88:89], v[88:89], v[128:129]
	v_pk_mul_f32 v[90:91], v[90:91], v[130:131]
	v_pk_mul_f32 v[96:97], v[96:97], v[128:129]
	s_waitcnt vmcnt(1)
	v_pk_mul_f32 v[32:33], v[32:33], v[136:137]
	v_pk_mul_f32 v[34:35], v[34:35], v[138:139]
	s_waitcnt vmcnt(0)
	v_pk_mul_f32 v[0:1], v[0:1], v[140:141]
	v_pk_mul_f32 v[2:3], v[2:3], v[142:143]
	v_cvt_pk_bf16_f32 v32, v32, v33
	v_cvt_pk_bf16_f32 v33, v34, v35
	v_cvt_pk_bf16_f32 v0, v0, v1
	v_cvt_pk_bf16_f32 v1, v2, v3
	v_pk_mul_f32 v[34:35], v[36:37], v[136:137]
	v_pk_mul_f32 v[36:37], v[38:39], v[138:139]
	ds_write2_b64 v144, v[32:33], v[0:1] offset0:8 offset1:12
	v_pk_mul_f32 v[0:1], v[4:5], v[140:141]
	v_pk_mul_f32 v[2:3], v[6:7], v[142:143]
	v_cvt_pk_bf16_f32 v34, v34, v35
	v_cvt_pk_bf16_f32 v35, v36, v37
	v_cvt_pk_bf16_f32 v0, v0, v1
	v_cvt_pk_bf16_f32 v1, v2, v3
	v_pk_mul_f32 v[36:37], v[40:41], v[136:137]
	v_pk_mul_f32 v[38:39], v[42:43], v[138:139]
	ds_write2_b64 v145, v[34:35], v[0:1] offset0:40 offset1:44
	v_pk_mul_f32 v[0:1], v[8:9], v[140:141]
	v_pk_mul_f32 v[2:3], v[10:11], v[142:143]
	v_cvt_pk_bf16_f32 v36, v36, v37
	v_cvt_pk_bf16_f32 v37, v38, v39
	v_cvt_pk_bf16_f32 v0, v0, v1
	v_cvt_pk_bf16_f32 v1, v2, v3
	v_pk_mul_f32 v[38:39], v[44:45], v[136:137]
	v_pk_mul_f32 v[40:41], v[46:47], v[138:139]
	ds_write2_b64 v146, v[36:37], v[0:1] offset0:72 offset1:76
	v_pk_mul_f32 v[0:1], v[12:13], v[140:141]
	v_pk_mul_f32 v[2:3], v[14:15], v[142:143]
	v_cvt_pk_bf16_f32 v38, v38, v39
	v_cvt_pk_bf16_f32 v39, v40, v41
	v_cvt_pk_bf16_f32 v0, v0, v1
	v_cvt_pk_bf16_f32 v1, v2, v3
	v_pk_mul_f32 v[98:99], v[98:99], v[130:131]
	v_pk_mul_f32 v[64:65], v[64:65], v[132:133]
	v_pk_mul_f32 v[66:67], v[66:67], v[134:135]
	v_pk_mul_f32 v[76:77], v[76:77], v[132:133]
; DI void store4(u16* dst, f32x4 v) { uint2 w; w.x = cvtpk(v[0], v[1]); w.y = cvtpk(v[2], v[3]); *(uint2*)dst = w; }
; DI void phase9(const Params& p, const Sched& sched, unsigned char* smem) {
;     ...
; #pragma unroll
;       for (int mi = 0; mi < 4; ++mi) {
;         const int f = fb + mi * 16 + lq * 4; const float4 gm = *(const float4*)(mod + (size_t)b * 6144 + 5120 + f);
; #pragma unroll
;         for (int ni = 0; ni < 8; ++ni) {
;           const f32x4 o = {gm.x * acc[mi][ni][0], gm.y * acc[mi][ni][1], gm.z * acc[mi][ni][2], gm.w * acc[mi][ni][3]};
;           store4(Ls + (wt * 128 + ni * 16 + lr) * EST + wf * 64 + mi * 16 + lq * 4, o);
;         }
;       }
;       __syncthreads();
	v_pk_mul_f32 v[78:79], v[78:79], v[134:135]
	v_pk_mul_f32 v[40:41], v[48:49], v[136:137]
	v_pk_mul_f32 v[42:43], v[50:51], v[138:139]
	ds_write2_b64 v147, v[38:39], v[0:1] offset0:104 offset1:108
	v_pk_mul_f32 v[0:1], v[16:17], v[140:141]
	v_pk_mul_f32 v[2:3], v[18:19], v[142:143]
	v_cvt_pk_bf16_f32 v88, v88, v89
	v_cvt_pk_bf16_f32 v89, v90, v91
	v_cvt_pk_bf16_f32 v90, v96, v97
	v_cvt_pk_bf16_f32 v91, v98, v99
	v_cvt_pk_bf16_f32 v64, v64, v65
	v_cvt_pk_bf16_f32 v65, v66, v67
	v_cvt_pk_bf16_f32 v66, v76, v77
	v_cvt_pk_bf16_f32 v67, v78, v79
	v_cvt_pk_bf16_f32 v40, v40, v41
	v_cvt_pk_bf16_f32 v41, v42, v43
	v_cvt_pk_bf16_f32 v0, v0, v1
	v_cvt_pk_bf16_f32 v1, v2, v3
	v_pk_mul_f32 v[106:107], v[106:107], v[130:131]
	v_pk_mul_f32 v[116:117], v[116:117], v[128:129]
	v_pk_mul_f32 v[118:119], v[118:119], v[130:131]
	ds_write2_b64 v144, v[88:89], v[64:65] offset1:4
	ds_write2_b64 v145, v[90:91], v[66:67] offset0:32 offset1:36
	v_pk_mul_f32 v[64:65], v[68:69], v[132:133]
	v_pk_mul_f32 v[66:67], v[70:71], v[134:135]
	v_pk_mul_f32 v[42:43], v[52:53], v[136:137]
	v_pk_mul_f32 v[44:45], v[54:55], v[138:139]
	ds_write2_b64 v148, v[40:41], v[0:1] offset0:136 offset1:140
	v_pk_mul_f32 v[0:1], v[20:21], v[140:141]
	v_pk_mul_f32 v[2:3], v[22:23], v[142:143]
	v_cvt_pk_bf16_f32 v97, v106, v107
	v_cvt_pk_bf16_f32 v106, v116, v117
	v_cvt_pk_bf16_f32 v107, v118, v119
	v_cvt_pk_bf16_f32 v64, v64, v65
	v_cvt_pk_bf16_f32 v65, v66, v67
	v_add_u32_e32 v68, 0x5000, v144
	v_cvt_pk_bf16_f32 v42, v42, v43
	v_cvt_pk_bf16_f32 v43, v44, v45
	v_cvt_pk_bf16_f32 v0, v0, v1
	v_cvt_pk_bf16_f32 v1, v2, v3
	v_pk_mul_f32 v[108:109], v[108:109], v[128:129]
	v_pk_mul_f32 v[120:121], v[120:121], v[128:129]
	v_pk_mul_f32 v[122:123], v[122:123], v[130:131]
	ds_write2_b64 v68, v[106:107], v[64:65] offset0:160 offset1:164
	v_pk_mul_f32 v[64:65], v[80:81], v[132:133]
	v_pk_mul_f32 v[66:67], v[82:83], v[134:135]
	v_pk_mul_f32 v[44:45], v[56:57], v[136:137]
	v_pk_mul_f32 v[46:47], v[58:59], v[138:139]
	ds_write2_b64 v68, v[42:43], v[0:1] offset0:168 offset1:172
	v_pk_mul_f32 v[0:1], v[24:25], v[140:141]
	v_pk_mul_f32 v[2:3], v[26:27], v[142:143]
	v_cvt_pk_bf16_f32 v98, v108, v109
	v_cvt_pk_bf16_f32 v108, v120, v121
	v_cvt_pk_bf16_f32 v109, v122, v123
	v_cvt_pk_bf16_f32 v64, v64, v65
	v_cvt_pk_bf16_f32 v65, v66, v67
	v_add_u32_e32 v69, 0x6000, v144
	v_cvt_pk_bf16_f32 v44, v44, v45
	v_cvt_pk_bf16_f32 v45, v46, v47
	v_cvt_pk_bf16_f32 v0, v0, v1
	v_cvt_pk_bf16_f32 v1, v2, v3
	v_pk_mul_f32 v[104:105], v[104:105], v[128:129]
	v_pk_mul_f32 v[110:111], v[110:111], v[130:131]
	v_pk_mul_f32 v[112:113], v[112:113], v[128:129]
	v_pk_mul_f32 v[114:115], v[114:115], v[130:131]
	v_pk_mul_f32 v[124:125], v[124:125], v[128:129]
	v_pk_mul_f32 v[126:127], v[126:127], v[130:131]
	v_pk_mul_f32 v[84:85], v[84:85], v[132:133]
	v_pk_mul_f32 v[86:87], v[86:87], v[134:135]
	v_pk_mul_f32 v[92:93], v[92:93], v[132:133]
	v_pk_mul_f32 v[94:95], v[94:95], v[134:135]
	v_pk_mul_f32 v[100:101], v[100:101], v[132:133]
	v_pk_mul_f32 v[102:103], v[102:103], v[134:135]
	ds_write2_b64 v69, v[108:109], v[64:65] offset0:192 offset1:196
	v_pk_mul_f32 v[64:65], v[72:73], v[132:133]
	v_pk_mul_f32 v[66:67], v[74:75], v[134:135]
	v_pk_mul_f32 v[46:47], v[60:61], v[136:137]
	v_pk_mul_f32 v[48:49], v[62:63], v[138:139]
	ds_write2_b64 v69, v[44:45], v[0:1] offset0:200 offset1:204
	v_pk_mul_f32 v[0:1], v[28:29], v[140:141]
	v_pk_mul_f32 v[2:3], v[30:31], v[142:143]
	v_cvt_pk_bf16_f32 v96, v104, v105
	v_cvt_pk_bf16_f32 v99, v110, v111
	v_cvt_pk_bf16_f32 v104, v112, v113
	v_cvt_pk_bf16_f32 v105, v114, v115
	v_cvt_pk_bf16_f32 v110, v124, v125
	v_cvt_pk_bf16_f32 v111, v126, v127
	v_cvt_pk_bf16_f32 v76, v84, v85
	v_cvt_pk_bf16_f32 v77, v86, v87
	v_cvt_pk_bf16_f32 v78, v92, v93
	v_cvt_pk_bf16_f32 v79, v94, v95
	v_cvt_pk_bf16_f32 v84, v100, v101
	v_cvt_pk_bf16_f32 v85, v102, v103
	v_cvt_pk_bf16_f32 v64, v64, v65
	v_cvt_pk_bf16_f32 v65, v66, v67
	v_add_u32_e32 v66, 0x7000, v144
	v_cvt_pk_bf16_f32 v46, v46, v47
	v_cvt_pk_bf16_f32 v47, v48, v49
	v_cvt_pk_bf16_f32 v0, v0, v1
	v_cvt_pk_bf16_f32 v1, v2, v3
	v_mov_b32_e32 v2, v218
	ds_write2_b64 v146, v[96:97], v[76:77] offset0:64 offset1:68
	ds_write2_b64 v147, v[98:99], v[78:79] offset0:96 offset1:100
	ds_write2_b64 v148, v[104:105], v[84:85] offset0:128 offset1:132
	ds_write2_b64 v66, v[110:111], v[64:65] offset0:224 offset1:228
	ds_write2_b64 v66, v[46:47], v[0:1] offset0:232 offset1:236
	s_waitcnt lgkmcnt(0)
	s_barrier
; DI int tidx() { int t = __builtin_amdgcn_workitem_id_x(); asm volatile("" : "+v"(t)); return t; }
; DI unsigned cvtpk(float lo, float hi) { const f32x2_ v = {lo, hi}; return __builtin_bit_cast(unsigned, __builtin_convertvector(v, bf16x2_)); }
; DI float bflo(unsigned w) { return __uint_as_float(w << 16); }
; DI float bfhi(unsigned w) { return __uint_as_float(w & 0xffff0000u); }
; DI void phase9(const Params& p, const Sched& sched, unsigned char* smem) {
;     ...
;       const int tid = tidx();
; #pragma unroll
;       for (int i = 0; i < 16; ++i) {
;         const int c = tid + 256 * i, row = c >> 4, ch = (c & 15) * 8;
;         const size_t gi = (size_t)(tm * 256 + row) * 1024 + tn * 128 + ch;
;         const u32x4 sv = *(const u32x4*)(Ls + row * EST + ch), xv = *(const u32x4*)(x1b + gi);
;         u32x4 w;
;         w.x = cvtpk(bflo(xv.x) + bflo(sv.x), bfhi(xv.x) + bfhi(sv.x)); w.y = cvtpk(bflo(xv.y) + bflo(sv.y), bfhi(xv.y) + bfhi(sv.y));
;         w.z = cvtpk(bflo(xv.z) + bflo(sv.z), bfhi(xv.z) + bfhi(sv.z)); w.w = cvtpk(bflo(xv.w) + bflo(sv.w), bfhi(xv.w) + bfhi(sv.w));
;         *(u32x4*)(x2b + gi) = w;
;       }
	s_nop 0
	v_ashrrev_i32_e32 v3, 4, v2
	v_add_u32_e32 v4, s29, v3
	v_lshlrev_b32_e32 v0, 3, v2
	v_ashrrev_i32_e32 v5, 31, v4
	v_and_b32_e32 v1, 0x78, v0
	v_lshlrev_b64 v[4:5], 10, v[4:5]
	v_or3_b32 v4, v4, s30, v1
	v_lshlrev_b64 v[12:13], 1, v[4:5]
	v_lshl_add_u64 v[4:5], s[12:13], 0, v[12:13]
	global_load_dwordx4 v[4:7], v[4:5], off
	v_lshlrev_b32_e32 v0, 1, v1
	v_mad_u64_u32 v[8:9], s[34:35], v3, s25, v[0:1]
	ds_read_b128 v[8:11], v8
	v_add_u32_e32 v3, 0x100, v2
	v_ashrrev_i32_e32 v3, 4, v3
	s_waitcnt lgkmcnt(0)
	v_lshlrev_b32_e32 v16, 16, v8
	v_and_b32_e32 v17, 0xffff0000, v8
	v_lshlrev_b32_e32 v8, 16, v9
	v_and_b32_e32 v9, 0xffff0000, v9
	s_waitcnt vmcnt(0)
	v_lshlrev_b32_e32 v14, 16, v4
	v_and_b32_e32 v15, 0xffff0000, v4
	v_pk_add_f32 v[14:15], v[16:17], v[14:15]
	s_nop 0
	v_cvt_pk_bf16_f32 v4, v14, v15
	v_lshlrev_b32_e32 v14, 16, v5
	v_and_b32_e32 v15, 0xffff0000, v5
	v_pk_add_f32 v[8:9], v[8:9], v[14:15]
	v_lshlrev_b32_e32 v14, 16, v10
	v_cvt_pk_bf16_f32 v5, v8, v9
	v_lshlrev_b32_e32 v8, 16, v6
	v_and_b32_e32 v9, 0xffff0000, v6
	v_and_b32_e32 v15, 0xffff0000, v10
	v_pk_add_f32 v[8:9], v[14:15], v[8:9]
	v_lshlrev_b32_e32 v10, 16, v11
	v_cvt_pk_bf16_f32 v6, v8, v9
	v_lshlrev_b32_e32 v8, 16, v7
	v_and_b32_e32 v9, 0xffff0000, v7
	v_and_b32_e32 v11, 0xffff0000, v11
	v_pk_add_f32 v[8:9], v[10:11], v[8:9]
	s_nop 0
	v_cvt_pk_bf16_f32 v7, v8, v9
	v_lshl_add_u64 v[8:9], s[2:3], 0, v[12:13]
	global_store_dwordx4 v[8:9], v[4:7], off
	v_mad_u64_u32 v[8:9], s[34:35], v3, s25, v[0:1]
	s_nop 0
	v_add_u32_e32 v4, s29, v3
	v_ashrrev_i32_e32 v5, 31, v4
	v_lshlrev_b64 v[4:5], 10, v[4:5]
	v_or3_b32 v4, v4, s30, v1
	v_lshlrev_b64 v[12:13], 1, v[4:5]
	v_lshl_add_u64 v[4:5], s[12:13], 0, v[12:13]
	global_load_dwordx4 v[4:7], v[4:5], off
	ds_read_b128 v[8:11], v8
	v_add_u32_e32 v3, 0x200, v2
	v_ashrrev_i32_e32 v3, 4, v3
	v_lshl_add_u64 v[12:13], s[2:3], 0, v[12:13]
	s_waitcnt lgkmcnt(0)
	v_lshlrev_b32_e32 v14, 16, v8
	v_and_b32_e32 v15, 0xffff0000, v8
	v_lshlrev_b32_e32 v8, 16, v9
	v_and_b32_e32 v9, 0xffff0000, v9
	v_lshlrev_b32_e32 v16, 16, v10
	v_and_b32_e32 v17, 0xffff0000, v10
	v_lshlrev_b32_e32 v10, 16, v11
	v_and_b32_e32 v11, 0xffff0000, v11
	s_waitcnt vmcnt(0)
	v_lshlrev_b32_e32 v18, 16, v4
	v_and_b32_e32 v19, 0xffff0000, v4
	v_lshlrev_b32_e32 v4, 16, v5
	v_and_b32_e32 v5, 0xffff0000, v5
	v_lshlrev_b32_e32 v20, 16, v6
	v_and_b32_e32 v21, 0xffff0000, v6
	v_lshlrev_b32_e32 v6, 16, v7
	v_and_b32_e32 v7, 0xffff0000, v7
	v_pk_add_f32 v[14:15], v[14:15], v[18:19]
	v_pk_add_f32 v[8:9], v[8:9], v[4:5]
	v_pk_add_f32 v[16:17], v[16:17], v[20:21]
	v_pk_add_f32 v[10:11], v[10:11], v[6:7]
	v_cvt_pk_bf16_f32 v4, v14, v15
	v_cvt_pk_bf16_f32 v5, v8, v9
	v_cvt_pk_bf16_f32 v6, v16, v17
	v_cvt_pk_bf16_f32 v7, v10, v11
	global_store_dwordx4 v[12:13], v[4:7], off
	v_add_u32_e32 v8, 0x300, v2
	v_ashrrev_i32_e32 v26, 4, v8
	v_add_u32_e32 v4, s29, v3
	v_ashrrev_i32_e32 v5, 31, v4
	v_lshlrev_b64 v[4:5], 10, v[4:5]
	v_or3_b32 v4, v4, s30, v1
	v_lshlrev_b64 v[12:13], 1, v[4:5]
	v_lshl_add_u64 v[4:5], s[12:13], 0, v[12:13]
	global_load_dwordx4 v[4:7], v[4:5], off
	v_mad_u64_u32 v[8:9], s[34:35], v3, s25, v[0:1]
	ds_read_b128 v[8:11], v8
	v_add_u32_e32 v14, s29, v26
	v_ashrrev_i32_e32 v15, 31, v14
	v_lshlrev_b64 v[14:15], 10, v[14:15]
	v_or3_b32 v14, v14, s30, v1
	s_waitcnt lgkmcnt(0)
	v_lshlrev_b32_e32 v18, 16, v8
	v_and_b32_e32 v19, 0xffff0000, v8
	v_lshlrev_b32_e32 v8, 16, v9
	v_and_b32_e32 v9, 0xffff0000, v9
	v_lshlrev_b32_e32 v20, 16, v10
	v_and_b32_e32 v21, 0xffff0000, v10
	v_lshlrev_b32_e32 v10, 16, v11
	v_and_b32_e32 v11, 0xffff0000, v11
	v_lshlrev_b64 v[14:15], 1, v[14:15]
	v_lshl_add_u64 v[12:13], s[2:3], 0, v[12:13]
	v_lshl_add_u64 v[16:17], s[12:13], 0, v[14:15]
	v_add_u32_e32 v3, 0x400, v2
	v_ashrrev_i32_e32 v3, 4, v3
	v_lshl_add_u64 v[14:15], s[2:3], 0, v[14:15]
	s_waitcnt vmcnt(0)
	v_lshlrev_b32_e32 v22, 16, v4
	v_and_b32_e32 v23, 0xffff0000, v4
	v_lshlrev_b32_e32 v4, 16, v5
	v_and_b32_e32 v5, 0xffff0000, v5
	v_lshlrev_b32_e32 v24, 16, v6
	v_and_b32_e32 v25, 0xffff0000, v6
	v_lshlrev_b32_e32 v6, 16, v7
	v_and_b32_e32 v7, 0xffff0000, v7
	v_pk_add_f32 v[18:19], v[18:19], v[22:23]
	v_pk_add_f32 v[8:9], v[8:9], v[4:5]
	v_pk_add_f32 v[20:21], v[20:21], v[24:25]
	v_pk_add_f32 v[10:11], v[10:11], v[6:7]
	v_cvt_pk_bf16_f32 v4, v18, v19
	v_cvt_pk_bf16_f32 v5, v8, v9
	v_cvt_pk_bf16_f32 v6, v20, v21
	v_cvt_pk_bf16_f32 v7, v10, v11
	global_store_dwordx4 v[12:13], v[4:7], off
	global_load_dwordx4 v[4:7], v[16:17], off
	v_mad_u64_u32 v[8:9], s[34:35], v26, s25, v[0:1]
	ds_read_b128 v[8:11], v8
	v_add_u32_e32 v12, s29, v3
	v_ashrrev_i32_e32 v13, 31, v12
	v_lshlrev_b64 v[12:13], 10, v[12:13]
	v_or3_b32 v12, v12, s30, v1
	s_waitcnt lgkmcnt(0)
	v_lshlrev_b32_e32 v18, 16, v8
	v_and_b32_e32 v19, 0xffff0000, v8
	v_lshlrev_b32_e32 v8, 16, v9
	v_and_b32_e32 v9, 0xffff0000, v9
	v_lshlrev_b32_e32 v20, 16, v10
	v_and_b32_e32 v21, 0xffff0000, v10
	v_lshlrev_b32_e32 v10, 16, v11
	v_and_b32_e32 v11, 0xffff0000, v11
	v_lshlrev_b64 v[12:13], 1, v[12:13]
	v_lshl_add_u64 v[16:17], s[12:13], 0, v[12:13]
	v_lshl_add_u64 v[12:13], s[2:3], 0, v[12:13]
	s_waitcnt vmcnt(0)
	v_lshlrev_b32_e32 v22, 16, v4
	v_and_b32_e32 v23, 0xffff0000, v4
	v_lshlrev_b32_e32 v4, 16, v5
	v_and_b32_e32 v5, 0xffff0000, v5
	v_lshlrev_b32_e32 v24, 16, v6
	v_and_b32_e32 v25, 0xffff0000, v6
	v_lshlrev_b32_e32 v6, 16, v7
	v_and_b32_e32 v7, 0xffff0000, v7
	v_pk_add_f32 v[18:19], v[18:19], v[22:23]
	v_pk_add_f32 v[8:9], v[8:9], v[4:5]
	v_pk_add_f32 v[20:21], v[20:21], v[24:25]
	v_pk_add_f32 v[10:11], v[10:11], v[6:7]
	v_cvt_pk_bf16_f32 v4, v18, v19
	v_cvt_pk_bf16_f32 v5, v8, v9
	v_cvt_pk_bf16_f32 v6, v20, v21
	v_cvt_pk_bf16_f32 v7, v10, v11
	global_store_dwordx4 v[14:15], v[4:7], off
	global_load_dwordx4 v[4:7], v[16:17], off
	v_add_u32_e32 v8, 0x500, v2
	v_ashrrev_i32_e32 v26, 4, v8
	v_mad_u64_u32 v[8:9], s[34:35], v3, s25, v[0:1]
	ds_read_b128 v[8:11], v8
	v_add_u32_e32 v14, s29, v26
	v_ashrrev_i32_e32 v15, 31, v14
	v_lshlrev_b64 v[14:15], 10, v[14:15]
	v_or3_b32 v14, v14, s30, v1
	s_waitcnt lgkmcnt(0)
; DI int tidx() { int t = __builtin_amdgcn_workitem_id_x(); asm volatile("" : "+v"(t)); return t; }
; DI unsigned cvtpk(float lo, float hi) { const f32x2_ v = {lo, hi}; return __builtin_bit_cast(unsigned, __builtin_convertvector(v, bf16x2_)); }
; DI float bflo(unsigned w) { return __uint_as_float(w << 16); }
; DI float bfhi(unsigned w) { return __uint_as_float(w & 0xffff0000u); }
; DI void phase9(const Params& p, const Sched& sched, unsigned char* smem) {
;     ...
;       const int tid = tidx();
; #pragma unroll
;       for (int i = 0; i < 16; ++i) {
;         const int c = tid + 256 * i, row = c >> 4, ch = (c & 15) * 8;
;         const size_t gi = (size_t)(tm * 256 + row) * 1024 + tn * 128 + ch;
;         const u32x4 sv = *(const u32x4*)(Ls + row * EST + ch), xv = *(const u32x4*)(x1b + gi);
;         u32x4 w;
;         w.x = cvtpk(bflo(xv.x) + bflo(sv.x), bfhi(xv.x) + bfhi(sv.x)); w.y = cvtpk(bflo(xv.y) + bflo(sv.y), bfhi(xv.y) + bfhi(sv.y));
;         w.z = cvtpk(bflo(xv.z) + bflo(sv.z), bfhi(xv.z) + bfhi(sv.z)); w.w = cvtpk(bflo(xv.w) + bflo(sv.w), bfhi(xv.w) + bfhi(sv.w));
;         *(u32x4*)(x2b + gi) = w;
;       }
	v_lshlrev_b32_e32 v18, 16, v8
	v_and_b32_e32 v19, 0xffff0000, v8
	v_lshlrev_b32_e32 v8, 16, v9
	v_and_b32_e32 v9, 0xffff0000, v9
	v_lshlrev_b32_e32 v20, 16, v10
	v_and_b32_e32 v21, 0xffff0000, v10
	v_lshlrev_b32_e32 v10, 16, v11
	v_and_b32_e32 v11, 0xffff0000, v11
	v_lshlrev_b64 v[14:15], 1, v[14:15]
	v_lshl_add_u64 v[16:17], s[12:13], 0, v[14:15]
	v_add_u32_e32 v3, 0x600, v2
	v_ashrrev_i32_e32 v3, 4, v3
	v_lshl_add_u64 v[14:15], s[2:3], 0, v[14:15]
	s_waitcnt vmcnt(0)
	v_lshlrev_b32_e32 v22, 16, v4
	v_and_b32_e32 v23, 0xffff0000, v4
	v_lshlrev_b32_e32 v4, 16, v5
	v_and_b32_e32 v5, 0xffff0000, v5
	v_lshlrev_b32_e32 v24, 16, v6
	v_and_b32_e32 v25, 0xffff0000, v6
	v_lshlrev_b32_e32 v6, 16, v7
	v_and_b32_e32 v7, 0xffff0000, v7
	v_pk_add_f32 v[18:19], v[18:19], v[22:23]
	v_pk_add_f32 v[8:9], v[8:9], v[4:5]
	v_pk_add_f32 v[20:21], v[20:21], v[24:25]
	v_pk_add_f32 v[10:11], v[10:11], v[6:7]
	v_cvt_pk_bf16_f32 v4, v18, v19
	v_cvt_pk_bf16_f32 v5, v8, v9
	v_cvt_pk_bf16_f32 v6, v20, v21
	v_cvt_pk_bf16_f32 v7, v10, v11
	global_store_dwordx4 v[12:13], v[4:7], off
	global_load_dwordx4 v[4:7], v[16:17], off
	v_mad_u64_u32 v[8:9], s[34:35], v26, s25, v[0:1]
	ds_read_b128 v[8:11], v8
	v_add_u32_e32 v12, s29, v3
	v_ashrrev_i32_e32 v13, 31, v12
	v_lshlrev_b64 v[12:13], 10, v[12:13]
	v_or3_b32 v12, v12, s30, v1
	s_waitcnt lgkmcnt(0)
	v_lshlrev_b32_e32 v18, 16, v8
	v_and_b32_e32 v19, 0xffff0000, v8
	v_lshlrev_b32_e32 v8, 16, v9
	v_and_b32_e32 v9, 0xffff0000, v9
	v_lshlrev_b32_e32 v20, 16, v10
	v_and_b32_e32 v21, 0xffff0000, v10
	v_lshlrev_b32_e32 v10, 16, v11
	v_and_b32_e32 v11, 0xffff0000, v11
	v_lshlrev_b64 v[12:13], 1, v[12:13]
	v_lshl_add_u64 v[16:17], s[12:13], 0, v[12:13]
	v_lshl_add_u64 v[12:13], s[2:3], 0, v[12:13]
	s_waitcnt vmcnt(0)
	v_lshlrev_b32_e32 v22, 16, v4
	v_and_b32_e32 v23, 0xffff0000, v4
	v_lshlrev_b32_e32 v4, 16, v5
	v_and_b32_e32 v5, 0xffff0000, v5
	v_lshlrev_b32_e32 v24, 16, v6
	v_and_b32_e32 v25, 0xffff0000, v6
	v_lshlrev_b32_e32 v6, 16, v7
	v_and_b32_e32 v7, 0xffff0000, v7
	v_pk_add_f32 v[18:19], v[18:19], v[22:23]
	v_pk_add_f32 v[8:9], v[8:9], v[4:5]
	v_pk_add_f32 v[20:21], v[20:21], v[24:25]
	v_pk_add_f32 v[10:11], v[10:11], v[6:7]
	v_cvt_pk_bf16_f32 v4, v18, v19
	v_cvt_pk_bf16_f32 v5, v8, v9
	v_cvt_pk_bf16_f32 v6, v20, v21
	v_cvt_pk_bf16_f32 v7, v10, v11
	global_store_dwordx4 v[14:15], v[4:7], off
	global_load_dwordx4 v[4:7], v[16:17], off
	v_add_u32_e32 v8, 0x700, v2
	v_ashrrev_i32_e32 v26, 4, v8
	v_mad_u64_u32 v[8:9], s[34:35], v3, s25, v[0:1]
	ds_read_b128 v[8:11], v8
	v_add_u32_e32 v14, s29, v26
	v_ashrrev_i32_e32 v15, 31, v14
	v_lshlrev_b64 v[14:15], 10, v[14:15]
	v_or3_b32 v14, v14, s30, v1
	s_waitcnt lgkmcnt(0)
	v_lshlrev_b32_e32 v18, 16, v8
	v_and_b32_e32 v19, 0xffff0000, v8
	v_lshlrev_b32_e32 v8, 16, v9
	v_and_b32_e32 v9, 0xffff0000, v9
	v_lshlrev_b32_e32 v20, 16, v10
	v_and_b32_e32 v21, 0xffff0000, v10
	v_lshlrev_b32_e32 v10, 16, v11
	v_and_b32_e32 v11, 0xffff0000, v11
	v_lshlrev_b64 v[14:15], 1, v[14:15]
	v_lshl_add_u64 v[16:17], s[12:13], 0, v[14:15]
	v_add_u32_e32 v3, 0x800, v2
	v_ashrrev_i32_e32 v3, 4, v3
	v_lshl_add_u64 v[14:15], s[2:3], 0, v[14:15]
	s_waitcnt vmcnt(0)
	v_lshlrev_b32_e32 v22, 16, v4
	v_and_b32_e32 v23, 0xffff0000, v4
	v_lshlrev_b32_e32 v4, 16, v5
	v_and_b32_e32 v5, 0xffff0000, v5
	v_lshlrev_b32_e32 v24, 16, v6
	v_and_b32_e32 v25, 0xffff0000, v6
	v_lshlrev_b32_e32 v6, 16, v7
	v_and_b32_e32 v7, 0xffff0000, v7
	v_pk_add_f32 v[18:19], v[18:19], v[22:23]
	v_pk_add_f32 v[8:9], v[8:9], v[4:5]
	v_pk_add_f32 v[20:21], v[20:21], v[24:25]
	v_pk_add_f32 v[10:11], v[10:11], v[6:7]
	v_cvt_pk_bf16_f32 v4, v18, v19
	v_cvt_pk_bf16_f32 v5, v8, v9
	v_cvt_pk_bf16_f32 v6, v20, v21
	v_cvt_pk_bf16_f32 v7, v10, v11
	global_store_dwordx4 v[12:13], v[4:7], off
	global_load_dwordx4 v[4:7], v[16:17], off
	v_mad_u64_u32 v[8:9], s[34:35], v26, s25, v[0:1]
	ds_read_b128 v[8:11], v8
	v_add_u32_e32 v12, s29, v3
	v_ashrrev_i32_e32 v13, 31, v12
	v_lshlrev_b64 v[12:13], 10, v[12:13]
	v_or3_b32 v12, v12, s30, v1
	s_waitcnt lgkmcnt(0)
	v_lshlrev_b32_e32 v18, 16, v8
	v_and_b32_e32 v19, 0xffff0000, v8
	v_lshlrev_b32_e32 v8, 16, v9
	v_and_b32_e32 v9, 0xffff0000, v9
	v_lshlrev_b32_e32 v20, 16, v10
	v_and_b32_e32 v21, 0xffff0000, v10
	v_lshlrev_b32_e32 v10, 16, v11
	v_and_b32_e32 v11, 0xffff0000, v11
	v_lshlrev_b64 v[12:13], 1, v[12:13]
	v_lshl_add_u64 v[16:17], s[12:13], 0, v[12:13]
	v_lshl_add_u64 v[12:13], s[2:3], 0, v[12:13]
	s_waitcnt vmcnt(0)
	v_lshlrev_b32_e32 v22, 16, v4
	v_and_b32_e32 v23, 0xffff0000, v4
	v_lshlrev_b32_e32 v4, 16, v5
	v_and_b32_e32 v5, 0xffff0000, v5
	v_lshlrev_b32_e32 v24, 16, v6
	v_and_b32_e32 v25, 0xffff0000, v6
	v_lshlrev_b32_e32 v6, 16, v7
	v_and_b32_e32 v7, 0xffff0000, v7
	v_pk_add_f32 v[18:19], v[18:19], v[22:23]
	v_pk_add_f32 v[8:9], v[8:9], v[4:5]
	v_pk_add_f32 v[20:21], v[20:21], v[24:25]
	v_pk_add_f32 v[10:11], v[10:11], v[6:7]
	v_cvt_pk_bf16_f32 v4, v18, v19
	v_cvt_pk_bf16_f32 v5, v8, v9
	v_cvt_pk_bf16_f32 v6, v20, v21
	v_cvt_pk_bf16_f32 v7, v10, v11
	global_store_dwordx4 v[14:15], v[4:7], off
	global_load_dwordx4 v[4:7], v[16:17], off
	v_add_u32_e32 v8, 0x900, v2
	v_ashrrev_i32_e32 v26, 4, v8
	v_mad_u64_u32 v[8:9], s[34:35], v3, s25, v[0:1]
	ds_read_b128 v[8:11], v8
	v_add_u32_e32 v14, s29, v26
	v_ashrrev_i32_e32 v15, 31, v14
	v_lshlrev_b64 v[14:15], 10, v[14:15]
	v_or3_b32 v14, v14, s30, v1
	s_waitcnt lgkmcnt(0)
	v_lshlrev_b32_e32 v18, 16, v8
	v_and_b32_e32 v19, 0xffff0000, v8
	v_lshlrev_b32_e32 v8, 16, v9
	v_and_b32_e32 v9, 0xffff0000, v9
	v_lshlrev_b32_e32 v20, 16, v10
	v_and_b32_e32 v21, 0xffff0000, v10
	v_lshlrev_b32_e32 v10, 16, v11
	v_and_b32_e32 v11, 0xffff0000, v11
	v_lshlrev_b64 v[14:15], 1, v[14:15]
	v_lshl_add_u64 v[16:17], s[12:13], 0, v[14:15]
	v_add_u32_e32 v3, 0xa00, v2
	v_ashrrev_i32_e32 v3, 4, v3
	v_lshl_add_u64 v[14:15], s[2:3], 0, v[14:15]
	s_waitcnt vmcnt(0)
; DI int tidx() { int t = __builtin_amdgcn_workitem_id_x(); asm volatile("" : "+v"(t)); return t; }
; DI unsigned cvtpk(float lo, float hi) { const f32x2_ v = {lo, hi}; return __builtin_bit_cast(unsigned, __builtin_convertvector(v, bf16x2_)); }
; DI float bflo(unsigned w) { return __uint_as_float(w << 16); }
; DI float bfhi(unsigned w) { return __uint_as_float(w & 0xffff0000u); }
; DI void phase9(const Params& p, const Sched& sched, unsigned char* smem) {
;     ...
;       const int tid = tidx();
; #pragma unroll
;       for (int i = 0; i < 16; ++i) {
;         const int c = tid + 256 * i, row = c >> 4, ch = (c & 15) * 8;
;         const size_t gi = (size_t)(tm * 256 + row) * 1024 + tn * 128 + ch;
;         const u32x4 sv = *(const u32x4*)(Ls + row * EST + ch), xv = *(const u32x4*)(x1b + gi);
;         u32x4 w;
;         w.x = cvtpk(bflo(xv.x) + bflo(sv.x), bfhi(xv.x) + bfhi(sv.x)); w.y = cvtpk(bflo(xv.y) + bflo(sv.y), bfhi(xv.y) + bfhi(sv.y));
;         w.z = cvtpk(bflo(xv.z) + bflo(sv.z), bfhi(xv.z) + bfhi(sv.z)); w.w = cvtpk(bflo(xv.w) + bflo(sv.w), bfhi(xv.w) + bfhi(sv.w));
;         *(u32x4*)(x2b + gi) = w;
;       }
	v_lshlrev_b32_e32 v22, 16, v4
	v_and_b32_e32 v23, 0xffff0000, v4
	v_lshlrev_b32_e32 v4, 16, v5
	v_and_b32_e32 v5, 0xffff0000, v5
	v_lshlrev_b32_e32 v24, 16, v6
	v_and_b32_e32 v25, 0xffff0000, v6
	v_lshlrev_b32_e32 v6, 16, v7
	v_and_b32_e32 v7, 0xffff0000, v7
	v_pk_add_f32 v[18:19], v[18:19], v[22:23]
	v_pk_add_f32 v[8:9], v[8:9], v[4:5]
	v_pk_add_f32 v[20:21], v[20:21], v[24:25]
	v_pk_add_f32 v[10:11], v[10:11], v[6:7]
	v_cvt_pk_bf16_f32 v4, v18, v19
	v_cvt_pk_bf16_f32 v5, v8, v9
	v_cvt_pk_bf16_f32 v6, v20, v21
	v_cvt_pk_bf16_f32 v7, v10, v11
	global_store_dwordx4 v[12:13], v[4:7], off
	global_load_dwordx4 v[4:7], v[16:17], off
	v_mad_u64_u32 v[8:9], s[34:35], v26, s25, v[0:1]
	ds_read_b128 v[8:11], v8
	v_add_u32_e32 v12, s29, v3
	v_ashrrev_i32_e32 v13, 31, v12
	v_lshlrev_b64 v[12:13], 10, v[12:13]
	v_or3_b32 v12, v12, s30, v1
	s_waitcnt lgkmcnt(0)
	v_lshlrev_b32_e32 v18, 16, v8
	v_and_b32_e32 v19, 0xffff0000, v8
	v_lshlrev_b32_e32 v8, 16, v9
	v_and_b32_e32 v9, 0xffff0000, v9
	v_lshlrev_b32_e32 v20, 16, v10
	v_and_b32_e32 v21, 0xffff0000, v10
	v_lshlrev_b32_e32 v10, 16, v11
	v_and_b32_e32 v11, 0xffff0000, v11
	v_lshlrev_b64 v[12:13], 1, v[12:13]
	v_lshl_add_u64 v[16:17], s[12:13], 0, v[12:13]
	v_lshl_add_u64 v[12:13], s[2:3], 0, v[12:13]
	s_waitcnt vmcnt(0)
	v_lshlrev_b32_e32 v22, 16, v4
	v_and_b32_e32 v23, 0xffff0000, v4
	v_lshlrev_b32_e32 v4, 16, v5
	v_and_b32_e32 v5, 0xffff0000, v5
	v_lshlrev_b32_e32 v24, 16, v6
	v_and_b32_e32 v25, 0xffff0000, v6
	v_lshlrev_b32_e32 v6, 16, v7
	v_and_b32_e32 v7, 0xffff0000, v7
	v_pk_add_f32 v[18:19], v[18:19], v[22:23]
	v_pk_add_f32 v[8:9], v[8:9], v[4:5]
	v_pk_add_f32 v[20:21], v[20:21], v[24:25]
	v_pk_add_f32 v[10:11], v[10:11], v[6:7]
	v_cvt_pk_bf16_f32 v4, v18, v19
	v_cvt_pk_bf16_f32 v5, v8, v9
	v_cvt_pk_bf16_f32 v6, v20, v21
	v_cvt_pk_bf16_f32 v7, v10, v11
	global_store_dwordx4 v[14:15], v[4:7], off
	global_load_dwordx4 v[4:7], v[16:17], off
	v_add_u32_e32 v8, 0xb00, v2
	v_ashrrev_i32_e32 v26, 4, v8
	v_mad_u64_u32 v[8:9], s[34:35], v3, s25, v[0:1]
	ds_read_b128 v[8:11], v8
	v_add_u32_e32 v14, s29, v26
	v_ashrrev_i32_e32 v15, 31, v14
	v_lshlrev_b64 v[14:15], 10, v[14:15]
	v_or3_b32 v14, v14, s30, v1
	s_waitcnt lgkmcnt(0)
	v_lshlrev_b32_e32 v18, 16, v8
	v_and_b32_e32 v19, 0xffff0000, v8
	v_lshlrev_b32_e32 v8, 16, v9
	v_and_b32_e32 v9, 0xffff0000, v9
	v_lshlrev_b32_e32 v20, 16, v10
	v_and_b32_e32 v21, 0xffff0000, v10
	v_lshlrev_b32_e32 v10, 16, v11
	v_and_b32_e32 v11, 0xffff0000, v11
	v_lshlrev_b64 v[14:15], 1, v[14:15]
	v_lshl_add_u64 v[16:17], s[12:13], 0, v[14:15]
	v_add_u32_e32 v3, 0xc00, v2
	v_ashrrev_i32_e32 v3, 4, v3
	v_lshl_add_u64 v[14:15], s[2:3], 0, v[14:15]
	s_waitcnt vmcnt(0)
	v_lshlrev_b32_e32 v22, 16, v4
	v_and_b32_e32 v23, 0xffff0000, v4
	v_lshlrev_b32_e32 v4, 16, v5
	v_and_b32_e32 v5, 0xffff0000, v5
	v_lshlrev_b32_e32 v24, 16, v6
	v_and_b32_e32 v25, 0xffff0000, v6
	v_lshlrev_b32_e32 v6, 16, v7
	v_and_b32_e32 v7, 0xffff0000, v7
	v_pk_add_f32 v[18:19], v[18:19], v[22:23]
	v_pk_add_f32 v[8:9], v[8:9], v[4:5]
	v_pk_add_f32 v[20:21], v[20:21], v[24:25]
	v_pk_add_f32 v[10:11], v[10:11], v[6:7]
	v_cvt_pk_bf16_f32 v4, v18, v19
	v_cvt_pk_bf16_f32 v5, v8, v9
	v_cvt_pk_bf16_f32 v6, v20, v21
	v_cvt_pk_bf16_f32 v7, v10, v11
	global_store_dwordx4 v[12:13], v[4:7], off
	global_load_dwordx4 v[4:7], v[16:17], off
	v_mad_u64_u32 v[8:9], s[34:35], v26, s25, v[0:1]
	ds_read_b128 v[8:11], v8
	v_add_u32_e32 v12, s29, v3
	v_ashrrev_i32_e32 v13, 31, v12
	v_lshlrev_b64 v[12:13], 10, v[12:13]
	v_or3_b32 v12, v12, s30, v1
	s_waitcnt lgkmcnt(0)
	v_lshlrev_b32_e32 v18, 16, v8
	v_and_b32_e32 v19, 0xffff0000, v8
	v_lshlrev_b32_e32 v8, 16, v9
	v_and_b32_e32 v9, 0xffff0000, v9
	v_lshlrev_b32_e32 v20, 16, v10
	v_and_b32_e32 v21, 0xffff0000, v10
	v_lshlrev_b32_e32 v10, 16, v11
	v_and_b32_e32 v11, 0xffff0000, v11
	v_lshlrev_b64 v[12:13], 1, v[12:13]
	v_lshl_add_u64 v[16:17], s[12:13], 0, v[12:13]
	v_lshl_add_u64 v[12:13], s[2:3], 0, v[12:13]
	s_waitcnt vmcnt(0)
	v_lshlrev_b32_e32 v22, 16, v4
	v_and_b32_e32 v23, 0xffff0000, v4
	v_lshlrev_b32_e32 v4, 16, v5
	v_and_b32_e32 v5, 0xffff0000, v5
	v_lshlrev_b32_e32 v24, 16, v6
	v_and_b32_e32 v25, 0xffff0000, v6
	v_lshlrev_b32_e32 v6, 16, v7
	v_and_b32_e32 v7, 0xffff0000, v7
	v_pk_add_f32 v[18:19], v[18:19], v[22:23]
	v_pk_add_f32 v[8:9], v[8:9], v[4:5]
	v_pk_add_f32 v[20:21], v[20:21], v[24:25]
	v_pk_add_f32 v[10:11], v[10:11], v[6:7]
	v_cvt_pk_bf16_f32 v4, v18, v19
	v_cvt_pk_bf16_f32 v5, v8, v9
	v_cvt_pk_bf16_f32 v6, v20, v21
	v_cvt_pk_bf16_f32 v7, v10, v11
	global_store_dwordx4 v[14:15], v[4:7], off
	global_load_dwordx4 v[4:7], v[16:17], off
	v_add_u32_e32 v8, 0xd00, v2
	v_ashrrev_i32_e32 v26, 4, v8
	v_mad_u64_u32 v[8:9], s[34:35], v3, s25, v[0:1]
	ds_read_b128 v[8:11], v8
	v_add_u32_e32 v14, s29, v26
	v_ashrrev_i32_e32 v15, 31, v14
	v_lshlrev_b64 v[14:15], 10, v[14:15]
	v_or3_b32 v14, v14, s30, v1
	s_waitcnt lgkmcnt(0)
; DI int tidx() { int t = __builtin_amdgcn_workitem_id_x(); asm volatile("" : "+v"(t)); return t; }
; DI unsigned cvtpk(float lo, float hi) { const f32x2_ v = {lo, hi}; return __builtin_bit_cast(unsigned, __builtin_convertvector(v, bf16x2_)); }
; DI float bflo(unsigned w) { return __uint_as_float(w << 16); }
; DI float bfhi(unsigned w) { return __uint_as_float(w & 0xffff0000u); }
; DI void phase9(const Params& p, const Sched& sched, unsigned char* smem) {
;     ...
;       const int tid = tidx();
; #pragma unroll
;       for (int i = 0; i < 16; ++i) {
;         const int c = tid + 256 * i, row = c >> 4, ch = (c & 15) * 8;
;         const size_t gi = (size_t)(tm * 256 + row) * 1024 + tn * 128 + ch;
;         const u32x4 sv = *(const u32x4*)(Ls + row * EST + ch), xv = *(const u32x4*)(x1b + gi);
;         u32x4 w;
;         w.x = cvtpk(bflo(xv.x) + bflo(sv.x), bfhi(xv.x) + bfhi(sv.x)); w.y = cvtpk(bflo(xv.y) + bflo(sv.y), bfhi(xv.y) + bfhi(sv.y));
;         w.z = cvtpk(bflo(xv.z) + bflo(sv.z), bfhi(xv.z) + bfhi(sv.z)); w.w = cvtpk(bflo(xv.w) + bflo(sv.w), bfhi(xv.w) + bfhi(sv.w));
;         *(u32x4*)(x2b + gi) = w;
;       }
	v_lshlrev_b32_e32 v18, 16, v8
	v_and_b32_e32 v19, 0xffff0000, v8
	v_lshlrev_b32_e32 v8, 16, v9
	v_and_b32_e32 v9, 0xffff0000, v9
	v_lshlrev_b32_e32 v20, 16, v10
	v_and_b32_e32 v21, 0xffff0000, v10
	v_lshlrev_b32_e32 v10, 16, v11
	v_and_b32_e32 v11, 0xffff0000, v11
	v_lshlrev_b64 v[14:15], 1, v[14:15]
	v_lshl_add_u64 v[16:17], s[12:13], 0, v[14:15]
	v_add_u32_e32 v3, 0xe00, v2
	v_ashrrev_i32_e32 v3, 4, v3
	v_lshl_add_u64 v[14:15], s[2:3], 0, v[14:15]
	v_add_u32_e32 v2, 0xf00, v2
	s_waitcnt vmcnt(0)
	v_lshlrev_b32_e32 v22, 16, v4
	v_and_b32_e32 v23, 0xffff0000, v4
	v_lshlrev_b32_e32 v4, 16, v5
	v_and_b32_e32 v5, 0xffff0000, v5
	v_lshlrev_b32_e32 v24, 16, v6
	v_and_b32_e32 v25, 0xffff0000, v6
	v_lshlrev_b32_e32 v6, 16, v7
	v_and_b32_e32 v7, 0xffff0000, v7
	v_pk_add_f32 v[18:19], v[18:19], v[22:23]
	v_pk_add_f32 v[8:9], v[8:9], v[4:5]
	v_pk_add_f32 v[20:21], v[20:21], v[24:25]
	v_pk_add_f32 v[10:11], v[10:11], v[6:7]
	v_cvt_pk_bf16_f32 v4, v18, v19
	v_cvt_pk_bf16_f32 v5, v8, v9
	v_cvt_pk_bf16_f32 v6, v20, v21
	v_cvt_pk_bf16_f32 v7, v10, v11
	global_store_dwordx4 v[12:13], v[4:7], off
	global_load_dwordx4 v[4:7], v[16:17], off
	v_mad_u64_u32 v[8:9], s[34:35], v26, s25, v[0:1]
	ds_read_b128 v[8:11], v8
	v_add_u32_e32 v12, s29, v3
	v_ashrrev_i32_e32 v13, 31, v12
	v_lshlrev_b64 v[12:13], 10, v[12:13]
	v_or3_b32 v12, v12, s30, v1
	s_waitcnt lgkmcnt(0)
	v_lshlrev_b32_e32 v18, 16, v8
	v_and_b32_e32 v19, 0xffff0000, v8
	v_lshlrev_b32_e32 v8, 16, v9
	v_and_b32_e32 v9, 0xffff0000, v9
	v_lshlrev_b32_e32 v20, 16, v10
	v_and_b32_e32 v21, 0xffff0000, v10
	v_lshlrev_b32_e32 v10, 16, v11
	v_and_b32_e32 v11, 0xffff0000, v11
	v_lshlrev_b64 v[12:13], 1, v[12:13]
	v_lshl_add_u64 v[16:17], s[12:13], 0, v[12:13]
	v_lshl_add_u64 v[12:13], s[2:3], 0, v[12:13]
	s_waitcnt vmcnt(0)
	v_lshlrev_b32_e32 v22, 16, v4
	v_and_b32_e32 v23, 0xffff0000, v4
	v_lshlrev_b32_e32 v4, 16, v5
	v_and_b32_e32 v5, 0xffff0000, v5
	v_lshlrev_b32_e32 v24, 16, v6
	v_and_b32_e32 v25, 0xffff0000, v6
	v_lshlrev_b32_e32 v6, 16, v7
	v_and_b32_e32 v7, 0xffff0000, v7
	v_pk_add_f32 v[18:19], v[18:19], v[22:23]
	v_pk_add_f32 v[8:9], v[8:9], v[4:5]
	v_pk_add_f32 v[20:21], v[20:21], v[24:25]
	v_pk_add_f32 v[10:11], v[10:11], v[6:7]
	v_cvt_pk_bf16_f32 v4, v18, v19
	v_cvt_pk_bf16_f32 v5, v8, v9
	v_cvt_pk_bf16_f32 v6, v20, v21
	v_cvt_pk_bf16_f32 v7, v10, v11
	global_store_dwordx4 v[14:15], v[4:7], off
	global_load_dwordx4 v[4:7], v[16:17], off
	v_mad_u64_u32 v[8:9], s[34:35], v3, s25, v[0:1]
	v_ashrrev_i32_e32 v24, 4, v2
	ds_read_b128 v[8:11], v8
	v_add_u32_e32 v2, s29, v24
	v_ashrrev_i32_e32 v3, 31, v2
	v_lshlrev_b64 v[2:3], 10, v[2:3]
	v_or3_b32 v2, v2, s30, v1
	v_lshlrev_b64 v[14:15], 1, v[2:3]
	s_waitcnt lgkmcnt(0)
	v_lshlrev_b32_e32 v2, 16, v8
	v_and_b32_e32 v3, 0xffff0000, v8
	v_lshlrev_b32_e32 v8, 16, v9
	v_and_b32_e32 v9, 0xffff0000, v9
	v_lshlrev_b32_e32 v18, 16, v10
	v_and_b32_e32 v19, 0xffff0000, v10
	v_lshlrev_b32_e32 v10, 16, v11
	v_and_b32_e32 v11, 0xffff0000, v11
	v_lshl_add_u64 v[16:17], s[12:13], 0, v[14:15]
	v_mad_u64_u32 v[0:1], s[30:31], v24, s25, v[0:1]
	s_waitcnt vmcnt(0)
	v_lshlrev_b32_e32 v20, 16, v4
	v_and_b32_e32 v21, 0xffff0000, v4
	v_lshlrev_b32_e32 v4, 16, v5
	v_and_b32_e32 v5, 0xffff0000, v5
	v_lshlrev_b32_e32 v22, 16, v6
	v_and_b32_e32 v23, 0xffff0000, v6
	v_lshlrev_b32_e32 v6, 16, v7
	v_and_b32_e32 v7, 0xffff0000, v7
	v_pk_add_f32 v[2:3], v[2:3], v[20:21]
	v_pk_add_f32 v[4:5], v[8:9], v[4:5]
	v_pk_add_f32 v[8:9], v[18:19], v[22:23]
	v_pk_add_f32 v[6:7], v[10:11], v[6:7]
	v_cvt_pk_bf16_f32 v2, v2, v3
	v_cvt_pk_bf16_f32 v3, v4, v5
	v_cvt_pk_bf16_f32 v4, v8, v9
	v_cvt_pk_bf16_f32 v5, v6, v7
	global_store_dwordx4 v[12:13], v[2:5], off
	global_load_dwordx4 v[2:5], v[16:17], off
	ds_read_b128 v[6:9], v0
	v_lshl_add_u64 v[10:11], s[2:3], 0, v[14:15]
	s_waitcnt lgkmcnt(0)
	v_lshlrev_b32_e32 v0, 16, v6
	v_and_b32_e32 v1, 0xffff0000, v6
	v_lshlrev_b32_e32 v6, 16, v7
	v_and_b32_e32 v7, 0xffff0000, v7
	v_lshlrev_b32_e32 v12, 16, v8
	v_and_b32_e32 v13, 0xffff0000, v8
	v_lshlrev_b32_e32 v8, 16, v9
	v_and_b32_e32 v9, 0xffff0000, v9
	s_waitcnt vmcnt(0)
	v_lshlrev_b32_e32 v14, 16, v2
	v_and_b32_e32 v15, 0xffff0000, v2
	v_lshlrev_b32_e32 v2, 16, v3
	v_and_b32_e32 v3, 0xffff0000, v3
	v_lshlrev_b32_e32 v16, 16, v4
	v_and_b32_e32 v17, 0xffff0000, v4
	v_lshlrev_b32_e32 v4, 16, v5
	v_and_b32_e32 v5, 0xffff0000, v5
	v_pk_add_f32 v[0:1], v[0:1], v[14:15]
	v_pk_add_f32 v[2:3], v[6:7], v[2:3]
	v_pk_add_f32 v[6:7], v[12:13], v[16:17]
	v_pk_add_f32 v[4:5], v[8:9], v[4:5]
	v_cvt_pk_bf16_f32 v0, v0, v1
	v_cvt_pk_bf16_f32 v1, v2, v3
	v_cvt_pk_bf16_f32 v2, v6, v7
	v_cvt_pk_bf16_f32 v3, v4, v5
	global_store_dwordx4 v[10:11], v[0:3], off
	s_cbranch_scc0 .LBB0_1094
	s_branch .LBB0_1091
